# GEMM K-loops: s_setprio moved off the barrier hand-off path (raise before the pre-MMA barrier, lower after the post-MMA barrier); on top of v42
# speedup vs baseline: 1.0046x; 1.0008x over previous
; #define PG8_STAGE(bufoff, gbase, V0, V1) do { \
;         __builtin_amdgcn_global_load_lds((const unsigned*)((const char*)(gbase) + (V0)), (LAS unsigned*)(lds + (bufoff) + ldsw), 16, 0, 0); \
;         __builtin_amdgcn_global_load_lds((const unsigned*)((const char*)(gbase) + (V1)), (LAS unsigned*)(lds + (bufoff) + ldsw + 8192), 16, 0, 0); } while (0)
; #define PG8_LDA(dst, b, h) do { _Pragma("unroll") for (int m = 0; m < 4; ++m) _Pragma("unroll") for (int k = 0; k < 2; ++k) dst[m][k] = *(const LAS bf16x8*)(lds + PG8_SA(b, h) + aoff + m * 2048 + k * 1024); } while (0)
; #define PG8_LDB(dst, b, h) do { _Pragma("unroll") for (int n = 0; n < 2; ++n) _Pragma("unroll") for (int k = 0; k < 2; ++k) dst[n][k] = *(const LAS bf16x8*)(lds + PG8_SB(b, h) + boff + n * 2048 + k * 1024); } while (0)
; #define PG8_MMA(ai, bj, At, Bt) do { __builtin_amdgcn_s_setprio(1); _Pragma("unroll") for (int m = 0; m < 4; ++m) _Pragma("unroll") for (int n = 0; n < 2; ++n) _Pragma("unroll") for (int k = 0; k < 2; ++k) \
;         acc[ai][bj][m][n] = __builtin_amdgcn_mfma_f32_16x16x32_bf16(Bt[n][k], At[m][k], acc[ai][bj][m][n], 0, 0, 0); __builtin_amdgcn_s_setprio(0); } while (0)
; template <class Epi, class Sched>
; DI void gemm_phase(LAS unsigned char* lds, const int lda2, const int ldb2, const int nt, const Sched& S, const Epi& E) {
;     ...
;     for (;;) {
;         const bool has_next = S.next(ui + 1, nxt);
;         const char* nA = has_next ? nxt.A : cA; const char* nB = has_next ? nxt.B : cB;
;         for (int t = 0; t < nt; t += 2) {
;             const bool last = (t == nt - 2);
;             const char* a1 = cA + (size_t)(t + 1) * kstep;
;             const char* a2 = last ? nA : cA + (size_t)(t + 2) * kstep; const char* b2 = last ? nB : cB + (size_t)(t + 2) * kstep;
;             const char* a3 = a2 + kstep; const char* b3 = b2 + kstep;
;             PG8_LDB(B0, 0, 0); PG8_LDB(B1, 0, 1); PG8_SCHED; PG8_LDA(At, 0, 0); PG8_STAGE(PG8_SA(1, 1), a1 + hstepA, vA0, vA1);
;             PG8_WAIT_V(8); PG8_WAIT_L(0); PG8_BAR; PG8_MMA(0, 0, At, B0); PG8_MMA(0, 1, At, B1); PG8_BAR; PG8_SCHED;
;             PG8_LDA(At, 0, 1); PG8_STAGE(PG8_SB(0, 0), b2, vB0, vB1); PG8_STAGE(PG8_SB(0, 1), b2 + hstepB, vB0, vB1); PG8_STAGE(PG8_SA(0, 0), a2, vA0, vA1);
;             PG8_WAIT_V(8); PG8_WAIT_L(0); PG8_BAR; PG8_MMA(1, 0, At, B0); PG8_MMA(1, 1, At, B1); PG8_BAR; PG8_SCHED;
.LBB0_198:
	s_add_u32 s4, s4, 0x40080
	s_addc_u32 s5, s5, 0
	s_add_u32 s7, s22, 0x100
	s_addc_u32 s15, s23, 0
	s_mov_b32 s17, -2
	s_add_u32 s22, s4, 0xfffc0080
	s_addc_u32 s23, s5, -1
	s_add_i32 s27, 0, 0x10000
	s_cmp_eq_u32 s17, 12
	s_cselect_b32 s25, s19, s23
	s_cselect_b32 s24, s18, s22
	s_cselect_b32 s23, s21, s15
	s_cselect_b32 s22, s20, s7
	s_add_i32 s48, 0, 0x14000
	v_add_u32_e32 v152, s27, v158
	v_add_u32_e32 v172, s48, v158
	ds_read_b128 v[140:143], v152
	ds_read_b128 v[144:147], v152 offset:1024
	ds_read_b128 v[148:151], v152 offset:2048
	ds_read_b128 v[152:155], v152 offset:3072
	ds_read_b128 v[160:163], v172
	ds_read_b128 v[164:167], v172 offset:1024
	ds_read_b128 v[168:171], v172 offset:2048
	ds_read_b128 v[172:175], v172 offset:3072
	v_lshl_add_u64 v[214:215], s[4:5], 0, v[136:137]
	s_add_i32 m0, s55, 0xc000
	ds_read_b128 v[176:179], v159
	ds_read_b128 v[180:183], v159 offset:1024
	ds_read_b128 v[184:187], v159 offset:2048
	ds_read_b128 v[188:191], v159 offset:3072
	ds_read_b128 v[192:195], v159 offset:4096
	ds_read_b128 v[202:205], v159 offset:5120
	ds_read_b128 v[206:209], v159 offset:6144
	ds_read_b128 v[210:213], v159 offset:7168
	global_load_lds_dwordx4 v[214:215], off
	v_lshl_add_u64 v[214:215], s[4:5], 0, v[138:139]
	s_add_i32 m0, s55, 0xe000
	s_nop 0
	global_load_lds_dwordx4 v[214:215], off
	s_waitcnt vmcnt(8)
	s_waitcnt lgkmcnt(0)
	s_setprio 1
	s_barrier
	s_waitcnt lgkmcnt(0)
	v_mfma_f32_16x16x32_bf16 v[126:129], v[140:143], v[176:179], 0
	v_mfma_f32_16x16x32_bf16 v[122:125], v[148:151], v[176:179], 0
	v_mfma_f32_16x16x32_bf16 v[106:109], v[148:151], v[184:187], 0
	v_mfma_f32_16x16x32_bf16 v[110:113], v[140:143], v[184:187], 0
	v_mfma_f32_16x16x32_bf16 v[92:95], v[140:143], v[192:195], 0
	v_mfma_f32_16x16x32_bf16 v[88:91], v[148:151], v[192:195], 0
	v_mfma_f32_16x16x32_bf16 v[72:75], v[148:151], v[206:209], 0
	v_mfma_f32_16x16x32_bf16 v[76:79], v[140:143], v[206:209], 0
	v_mfma_f32_16x16x32_bf16 v[126:129], v[144:147], v[180:183], v[126:129]
	v_mfma_f32_16x16x32_bf16 v[122:125], v[152:155], v[180:183], v[122:125]
	v_mfma_f32_16x16x32_bf16 v[106:109], v[152:155], v[188:191], v[106:109]
	v_mfma_f32_16x16x32_bf16 v[110:113], v[144:147], v[188:191], v[110:113]
	v_mfma_f32_16x16x32_bf16 v[92:95], v[144:147], v[202:205], v[92:95]
	v_mfma_f32_16x16x32_bf16 v[88:91], v[152:155], v[202:205], v[88:91]
	v_mfma_f32_16x16x32_bf16 v[72:75], v[152:155], v[210:213], v[72:75]
	v_mfma_f32_16x16x32_bf16 v[76:79], v[144:147], v[210:213], v[76:79]
	s_setprio 0
	s_setprio 1
	v_mfma_f32_16x16x32_bf16 v[118:121], v[160:163], v[176:179], 0
	v_mfma_f32_16x16x32_bf16 v[114:117], v[168:171], v[176:179], 0
	v_mfma_f32_16x16x32_bf16 v[98:101], v[168:171], v[184:187], 0
	v_mfma_f32_16x16x32_bf16 v[102:105], v[160:163], v[184:187], 0
	v_mfma_f32_16x16x32_bf16 v[84:87], v[160:163], v[192:195], 0
	v_mfma_f32_16x16x32_bf16 v[80:83], v[168:171], v[192:195], 0
	v_mfma_f32_16x16x32_bf16 v[64:67], v[168:171], v[206:209], 0
	v_mfma_f32_16x16x32_bf16 v[68:71], v[160:163], v[206:209], 0
	v_mfma_f32_16x16x32_bf16 v[118:121], v[164:167], v[180:183], v[118:121]
	v_mfma_f32_16x16x32_bf16 v[114:117], v[172:175], v[180:183], v[114:117]
	v_mfma_f32_16x16x32_bf16 v[98:101], v[172:175], v[188:191], v[98:101]
	v_mfma_f32_16x16x32_bf16 v[102:105], v[164:167], v[188:191], v[102:105]
	v_mfma_f32_16x16x32_bf16 v[84:87], v[164:167], v[202:205], v[84:87]
	v_mfma_f32_16x16x32_bf16 v[80:83], v[172:175], v[202:205], v[80:83]
	v_mfma_f32_16x16x32_bf16 v[64:67], v[172:175], v[210:213], v[64:67]
	v_mfma_f32_16x16x32_bf16 v[68:71], v[164:167], v[210:213], v[68:71]
	s_barrier
	s_setprio 0
	s_add_i32 s27, s27, s54
	v_lshl_add_u64 v[214:215], s[22:23], 0, v[96:97]
	s_mov_b32 m0, s27
	ds_read_b128 v[176:179], v159 offset:16384
	ds_read_b128 v[180:183], v159 offset:17408
	ds_read_b128 v[184:187], v159 offset:18432
	ds_read_b128 v[188:191], v159 offset:19456
	ds_read_b128 v[192:195], v159 offset:20480
	ds_read_b128 v[202:205], v159 offset:21504
	ds_read_b128 v[206:209], v159 offset:22528
	ds_read_b128 v[210:213], v159 offset:23552
	global_load_lds_dwordx4 v[214:215], off
	s_add_i32 m0, s27, 0x2000
	s_add_u32 s28, s22, 0x40000
	v_lshl_add_u64 v[216:217], s[22:23], 0, v[130:131]
	s_addc_u32 s29, s23, 0
	s_add_i32 s27, s48, s54
	global_load_lds_dwordx4 v[216:217], off
	v_lshl_add_u64 v[218:219], s[28:29], 0, v[96:97]
	s_mov_b32 m0, s27
	v_lshl_add_u64 v[220:221], s[24:25], 0, v[134:135]
	global_load_lds_dwordx4 v[218:219], off
	v_lshl_add_u64 v[218:219], s[28:29], 0, v[130:131]
	s_add_i32 m0, s27, 0x2000
	s_nop 0
	global_load_lds_dwordx4 v[218:219], off
	v_lshl_add_u64 v[218:219], s[24:25], 0, v[132:133]
	s_mov_b32 m0, s55
	s_nop 0
	global_load_lds_dwordx4 v[218:219], off
	s_mov_b32 m0, s72
	s_nop 0
	global_load_lds_dwordx4 v[220:221], off
	s_waitcnt vmcnt(8)
	s_waitcnt lgkmcnt(0)
	s_setprio 1
	s_barrier
; #define PG8_STAGE(bufoff, gbase, V0, V1) do { \
;         __builtin_amdgcn_global_load_lds((const unsigned*)((const char*)(gbase) + (V0)), (LAS unsigned*)(lds + (bufoff) + ldsw), 16, 0, 0); \
;         __builtin_amdgcn_global_load_lds((const unsigned*)((const char*)(gbase) + (V1)), (LAS unsigned*)(lds + (bufoff) + ldsw + 8192), 16, 0, 0); } while (0)
; #define PG8_LDA(dst, b, h) do { _Pragma("unroll") for (int m = 0; m < 4; ++m) _Pragma("unroll") for (int k = 0; k < 2; ++k) dst[m][k] = *(const LAS bf16x8*)(lds + PG8_SA(b, h) + aoff + m * 2048 + k * 1024); } while (0)
; #define PG8_LDB(dst, b, h) do { _Pragma("unroll") for (int n = 0; n < 2; ++n) _Pragma("unroll") for (int k = 0; k < 2; ++k) dst[n][k] = *(const LAS bf16x8*)(lds + PG8_SB(b, h) + boff + n * 2048 + k * 1024); } while (0)
; #define PG8_MMA(ai, bj, At, Bt) do { __builtin_amdgcn_s_setprio(1); _Pragma("unroll") for (int m = 0; m < 4; ++m) _Pragma("unroll") for (int n = 0; n < 2; ++n) _Pragma("unroll") for (int k = 0; k < 2; ++k) \
;         acc[ai][bj][m][n] = __builtin_amdgcn_mfma_f32_16x16x32_bf16(Bt[n][k], At[m][k], acc[ai][bj][m][n], 0, 0, 0); __builtin_amdgcn_s_setprio(0); } while (0)
; #define PG8_WAIT_V(n) asm volatile("s_waitcnt vmcnt(" #n ")" ::: "memory")
; #define PG8_WAIT_L(n) asm volatile("s_waitcnt lgkmcnt(" #n ")" ::: "memory")
; #define PG8_BAR __builtin_amdgcn_s_barrier()
; #define PG8_SCHED __builtin_amdgcn_sched_barrier(0)
; template <class Epi, class Sched>
; DI void gemm_phase(LAS unsigned char* lds, const int lda2, const int ldb2, const int nt, const Sched& S, const Epi& E) {
;     ...
;             PG8_WAIT_V(8); PG8_WAIT_L(0); PG8_BAR; PG8_MMA(0, 0, At, B0); PG8_MMA(0, 1, At, B1); PG8_BAR; PG8_SCHED;
;             PG8_LDA(At, 0, 1); PG8_STAGE(PG8_SB(0, 0), b2, vB0, vB1); PG8_STAGE(PG8_SB(0, 1), b2 + hstepB, vB0, vB1); PG8_STAGE(PG8_SA(0, 0), a2, vA0, vA1);
;             PG8_WAIT_V(8); PG8_WAIT_L(0); PG8_BAR; PG8_MMA(1, 0, At, B0); PG8_MMA(1, 1, At, B1); PG8_BAR; PG8_SCHED;
;             PG8_LDB(B0, 1, 0); PG8_LDB(B1, 1, 1); PG8_SCHED; PG8_LDA(At, 1, 0); PG8_STAGE(PG8_SA(0, 1), a2 + hstepA, vA0, vA1);
;             PG8_WAIT_V(8); PG8_WAIT_L(0); PG8_BAR; PG8_MMA(0, 0, At, B0); PG8_MMA(0, 1, At, B1); PG8_BAR; PG8_SCHED;
	s_waitcnt lgkmcnt(0)
	v_mfma_f32_16x16x32_bf16 v[60:63], v[140:143], v[176:179], 0
	v_mfma_f32_16x16x32_bf16 v[56:59], v[148:151], v[176:179], 0
	v_mfma_f32_16x16x32_bf16 v[40:43], v[148:151], v[184:187], 0
	v_mfma_f32_16x16x32_bf16 v[44:47], v[140:143], v[184:187], 0
	v_mfma_f32_16x16x32_bf16 v[28:31], v[140:143], v[192:195], 0
	v_mfma_f32_16x16x32_bf16 v[24:27], v[148:151], v[192:195], 0
	v_mfma_f32_16x16x32_bf16 v[8:11], v[148:151], v[206:209], 0
	v_mfma_f32_16x16x32_bf16 v[12:15], v[140:143], v[206:209], 0
	v_mfma_f32_16x16x32_bf16 v[60:63], v[144:147], v[180:183], v[60:63]
	v_mfma_f32_16x16x32_bf16 v[56:59], v[152:155], v[180:183], v[56:59]
	v_mfma_f32_16x16x32_bf16 v[40:43], v[152:155], v[188:191], v[40:43]
	v_mfma_f32_16x16x32_bf16 v[44:47], v[144:147], v[188:191], v[44:47]
	v_mfma_f32_16x16x32_bf16 v[28:31], v[144:147], v[202:205], v[28:31]
	v_mfma_f32_16x16x32_bf16 v[24:27], v[152:155], v[202:205], v[24:27]
	v_mfma_f32_16x16x32_bf16 v[8:11], v[152:155], v[210:213], v[8:11]
	v_mfma_f32_16x16x32_bf16 v[12:15], v[144:147], v[210:213], v[12:15]
	s_setprio 0
	s_setprio 1
	v_mfma_f32_16x16x32_bf16 v[52:55], v[160:163], v[176:179], 0
	v_mfma_f32_16x16x32_bf16 v[48:51], v[168:171], v[176:179], 0
	v_mfma_f32_16x16x32_bf16 v[32:35], v[168:171], v[184:187], 0
	v_mfma_f32_16x16x32_bf16 v[36:39], v[160:163], v[184:187], 0
	v_mfma_f32_16x16x32_bf16 v[20:23], v[160:163], v[192:195], 0
	v_mfma_f32_16x16x32_bf16 v[16:19], v[168:171], v[192:195], 0
	v_mfma_f32_16x16x32_bf16 v[0:3], v[168:171], v[206:209], 0
	v_mfma_f32_16x16x32_bf16 v[4:7], v[160:163], v[206:209], 0
	v_mfma_f32_16x16x32_bf16 v[52:55], v[164:167], v[180:183], v[52:55]
	v_mfma_f32_16x16x32_bf16 v[48:51], v[172:175], v[180:183], v[48:51]
	v_mfma_f32_16x16x32_bf16 v[32:35], v[172:175], v[188:191], v[32:35]
	v_mfma_f32_16x16x32_bf16 v[36:39], v[164:167], v[188:191], v[36:39]
	v_mfma_f32_16x16x32_bf16 v[20:23], v[164:167], v[202:205], v[20:23]
	v_mfma_f32_16x16x32_bf16 v[16:19], v[172:175], v[202:205], v[16:19]
	v_mfma_f32_16x16x32_bf16 v[0:3], v[172:175], v[210:213], v[0:3]
	v_mfma_f32_16x16x32_bf16 v[4:7], v[164:167], v[210:213], v[4:7]
	s_barrier
	s_setprio 0
	s_add_i32 s27, 0, 0x18000
	s_add_i32 s28, 0, 0x1c000
	v_add_u32_e32 v152, s27, v158
	v_add_u32_e32 v172, s28, v158
	ds_read_b128 v[140:143], v152
	ds_read_b128 v[144:147], v152 offset:1024
	ds_read_b128 v[148:151], v152 offset:2048
	ds_read_b128 v[152:155], v152 offset:3072
	ds_read_b128 v[160:163], v172
	ds_read_b128 v[164:167], v172 offset:1024
	ds_read_b128 v[168:171], v172 offset:2048
	ds_read_b128 v[172:175], v172 offset:3072
	s_add_u32 s24, s24, 0x40000
	s_addc_u32 s25, s25, 0
	s_mov_b32 m0, s73
	v_lshl_add_u64 v[222:223], s[24:25], 0, v[132:133]
	ds_read_b128 v[176:179], v159 offset:32768
	ds_read_b128 v[180:183], v159 offset:33792
	ds_read_b128 v[184:187], v159 offset:34816
	ds_read_b128 v[188:191], v159 offset:35840
	ds_read_b128 v[192:195], v159 offset:36864
	ds_read_b128 v[202:205], v159 offset:37888
	ds_read_b128 v[206:209], v159 offset:38912
	ds_read_b128 v[210:213], v159 offset:39936
	global_load_lds_dwordx4 v[222:223], off
	v_lshl_add_u64 v[222:223], s[24:25], 0, v[134:135]
	s_mov_b32 m0, s74
	s_nop 0
	global_load_lds_dwordx4 v[222:223], off
	s_waitcnt vmcnt(8)
	s_waitcnt lgkmcnt(0)
	s_setprio 1
	s_barrier
	s_waitcnt lgkmcnt(0)
	v_mfma_f32_16x16x32_bf16 v[126:129], v[140:143], v[176:179], v[126:129]
	v_mfma_f32_16x16x32_bf16 v[122:125], v[148:151], v[176:179], v[122:125]
	v_mfma_f32_16x16x32_bf16 v[106:109], v[148:151], v[184:187], v[106:109]
	v_mfma_f32_16x16x32_bf16 v[110:113], v[140:143], v[184:187], v[110:113]
	v_mfma_f32_16x16x32_bf16 v[92:95], v[140:143], v[192:195], v[92:95]
	v_mfma_f32_16x16x32_bf16 v[88:91], v[148:151], v[192:195], v[88:91]
	v_mfma_f32_16x16x32_bf16 v[72:75], v[148:151], v[206:209], v[72:75]
	v_mfma_f32_16x16x32_bf16 v[76:79], v[140:143], v[206:209], v[76:79]
	v_mfma_f32_16x16x32_bf16 v[126:129], v[144:147], v[180:183], v[126:129]
	v_mfma_f32_16x16x32_bf16 v[122:125], v[152:155], v[180:183], v[122:125]
	v_mfma_f32_16x16x32_bf16 v[106:109], v[152:155], v[188:191], v[106:109]
	v_mfma_f32_16x16x32_bf16 v[110:113], v[144:147], v[188:191], v[110:113]
	v_mfma_f32_16x16x32_bf16 v[92:95], v[144:147], v[202:205], v[92:95]
	v_mfma_f32_16x16x32_bf16 v[88:91], v[152:155], v[202:205], v[88:91]
	v_mfma_f32_16x16x32_bf16 v[72:75], v[152:155], v[210:213], v[72:75]
	v_mfma_f32_16x16x32_bf16 v[76:79], v[144:147], v[210:213], v[76:79]
	s_setprio 0
	s_setprio 1
	v_mfma_f32_16x16x32_bf16 v[118:121], v[160:163], v[176:179], v[118:121]
	v_mfma_f32_16x16x32_bf16 v[114:117], v[168:171], v[176:179], v[114:117]
	v_mfma_f32_16x16x32_bf16 v[98:101], v[168:171], v[184:187], v[98:101]
	v_mfma_f32_16x16x32_bf16 v[102:105], v[160:163], v[184:187], v[102:105]
	v_mfma_f32_16x16x32_bf16 v[84:87], v[160:163], v[192:195], v[84:87]
	v_mfma_f32_16x16x32_bf16 v[80:83], v[168:171], v[192:195], v[80:83]
	v_mfma_f32_16x16x32_bf16 v[64:67], v[168:171], v[206:209], v[64:67]
	v_mfma_f32_16x16x32_bf16 v[68:71], v[160:163], v[206:209], v[68:71]
	v_mfma_f32_16x16x32_bf16 v[118:121], v[164:167], v[180:183], v[118:121]
	v_mfma_f32_16x16x32_bf16 v[114:117], v[172:175], v[180:183], v[114:117]
	v_mfma_f32_16x16x32_bf16 v[98:101], v[172:175], v[188:191], v[98:101]
	v_mfma_f32_16x16x32_bf16 v[102:105], v[164:167], v[188:191], v[102:105]
	v_mfma_f32_16x16x32_bf16 v[84:87], v[164:167], v[202:205], v[84:87]
	v_mfma_f32_16x16x32_bf16 v[80:83], v[172:175], v[202:205], v[80:83]
	v_mfma_f32_16x16x32_bf16 v[64:67], v[172:175], v[210:213], v[64:67]
	v_mfma_f32_16x16x32_bf16 v[68:71], v[164:167], v[210:213], v[68:71]
	s_barrier
; #define PG8_STAGE(bufoff, gbase, V0, V1) do { \
;         __builtin_amdgcn_global_load_lds((const unsigned*)((const char*)(gbase) + (V0)), (LAS unsigned*)(lds + (bufoff) + ldsw), 16, 0, 0); \
;         __builtin_amdgcn_global_load_lds((const unsigned*)((const char*)(gbase) + (V1)), (LAS unsigned*)(lds + (bufoff) + ldsw + 8192), 16, 0, 0); } while (0)
; #define PG8_LDA(dst, b, h) do { _Pragma("unroll") for (int m = 0; m < 4; ++m) _Pragma("unroll") for (int k = 0; k < 2; ++k) dst[m][k] = *(const LAS bf16x8*)(lds + PG8_SA(b, h) + aoff + m * 2048 + k * 1024); } while (0)
; #define PG8_WAIT_V(n) asm volatile("s_waitcnt vmcnt(" #n ")" ::: "memory")
; template <class Epi, class Sched>
; DI void gemm_phase(LAS unsigned char* lds, const int lda2, const int ldb2, const int nt, const Sched& S, const Epi& E) {
;     ...
;         const bool has_next = S.next(ui + 1, nxt);
;         const char* nA = has_next ? nxt.A : cA; const char* nB = has_next ? nxt.B : cB;
;         for (int t = 0; t < nt; t += 2) {
;             const bool last = (t == nt - 2);
;             const char* a1 = cA + (size_t)(t + 1) * kstep;
;             const char* a2 = last ? nA : cA + (size_t)(t + 2) * kstep; const char* b2 = last ? nB : cB + (size_t)(t + 2) * kstep;
;             const char* a3 = a2 + kstep; const char* b3 = b2 + kstep;
;             PG8_LDB(B0, 0, 0); PG8_LDB(B1, 0, 1); PG8_SCHED; PG8_LDA(At, 0, 0); PG8_STAGE(PG8_SA(1, 1), a1 + hstepA, vA0, vA1);
;             PG8_WAIT_V(8); PG8_WAIT_L(0); PG8_BAR; PG8_MMA(0, 0, At, B0); PG8_MMA(0, 1, At, B1); PG8_BAR; PG8_SCHED;
;             PG8_LDA(At, 0, 1); PG8_STAGE(PG8_SB(0, 0), b2, vB0, vB1); PG8_STAGE(PG8_SB(0, 1), b2 + hstepB, vB0, vB1); PG8_STAGE(PG8_SA(0, 0), a2, vA0, vA1);
;             PG8_WAIT_V(8); PG8_WAIT_L(0); PG8_BAR; PG8_MMA(1, 0, At, B0); PG8_MMA(1, 1, At, B1); PG8_BAR; PG8_SCHED;
;             PG8_LDB(B0, 1, 0); PG8_LDB(B1, 1, 1); PG8_SCHED; PG8_LDA(At, 1, 0); PG8_STAGE(PG8_SA(0, 1), a2 + hstepA, vA0, vA1);
;             PG8_WAIT_V(8); PG8_WAIT_L(0); PG8_BAR; PG8_MMA(0, 0, At, B0); PG8_MMA(0, 1, At, B1); PG8_BAR; PG8_SCHED;
;             PG8_LDA(At, 1, 1); PG8_STAGE(PG8_SB(1, 0), b3, vB0, vB1); PG8_STAGE(PG8_SB(1, 1), b3 + hstepB, vB0, vB1); PG8_STAGE(PG8_SA(1, 0), a3, vA0, vA1);
;             PG8_WAIT_V(8); PG8_WAIT_L(0); PG8_BAR; PG8_MMA(1, 0, At, B0); PG8_MMA(1, 1, At, B1); PG8_BAR; PG8_SCHED;
	s_setprio 0
	s_add_i32 s24, s27, s54
	v_lshl_add_u64 v[214:215], v[214:215], 0, s[86:87]
	s_mov_b32 m0, s24
	ds_read_b128 v[176:179], v159 offset:49152
	ds_read_b128 v[180:183], v159 offset:50176
	ds_read_b128 v[184:187], v159 offset:51200
	ds_read_b128 v[188:191], v159 offset:52224
	ds_read_b128 v[192:195], v159 offset:53248
	ds_read_b128 v[202:205], v159 offset:54272
	ds_read_b128 v[206:209], v159 offset:55296
	ds_read_b128 v[210:213], v159 offset:56320
	global_load_lds_dwordx4 v[214:215], off
	s_add_i32 m0, s24, 0x2000
	s_add_u32 s22, s22, 0x40080
	v_lshl_add_u64 v[214:215], v[216:217], 0, s[86:87]
	s_addc_u32 s23, s23, 0
	s_add_i32 s24, s28, s54
	global_load_lds_dwordx4 v[214:215], off
	v_lshl_add_u64 v[214:215], s[22:23], 0, v[96:97]
	s_mov_b32 m0, s24
	s_nop 0
	global_load_lds_dwordx4 v[214:215], off
	v_lshl_add_u64 v[214:215], s[22:23], 0, v[130:131]
	s_add_i32 m0, s24, 0x2000
	s_nop 0
	global_load_lds_dwordx4 v[214:215], off
	v_lshl_add_u64 v[214:215], v[218:219], 0, s[86:87]
	s_mov_b32 m0, s77
	s_nop 0
	global_load_lds_dwordx4 v[214:215], off
	v_lshl_add_u64 v[214:215], v[220:221], 0, s[86:87]
	s_mov_b32 m0, s78
	s_nop 0
	global_load_lds_dwordx4 v[214:215], off
	s_waitcnt vmcnt(8)
	s_waitcnt lgkmcnt(0)
	s_setprio 1
	s_barrier
	s_waitcnt lgkmcnt(0)
	v_mfma_f32_16x16x32_bf16 v[60:63], v[140:143], v[176:179], v[60:63]
	v_mfma_f32_16x16x32_bf16 v[56:59], v[148:151], v[176:179], v[56:59]
	v_mfma_f32_16x16x32_bf16 v[40:43], v[148:151], v[184:187], v[40:43]
	v_mfma_f32_16x16x32_bf16 v[44:47], v[140:143], v[184:187], v[44:47]
	v_mfma_f32_16x16x32_bf16 v[28:31], v[140:143], v[192:195], v[28:31]
	v_mfma_f32_16x16x32_bf16 v[24:27], v[148:151], v[192:195], v[24:27]
	v_mfma_f32_16x16x32_bf16 v[8:11], v[148:151], v[206:209], v[8:11]
	v_mfma_f32_16x16x32_bf16 v[12:15], v[140:143], v[206:209], v[12:15]
	v_mfma_f32_16x16x32_bf16 v[60:63], v[144:147], v[180:183], v[60:63]
	v_mfma_f32_16x16x32_bf16 v[56:59], v[152:155], v[180:183], v[56:59]
	v_mfma_f32_16x16x32_bf16 v[40:43], v[152:155], v[188:191], v[40:43]
	v_mfma_f32_16x16x32_bf16 v[44:47], v[144:147], v[188:191], v[44:47]
	v_mfma_f32_16x16x32_bf16 v[28:31], v[144:147], v[202:205], v[28:31]
	v_mfma_f32_16x16x32_bf16 v[24:27], v[152:155], v[202:205], v[24:27]
	v_mfma_f32_16x16x32_bf16 v[8:11], v[152:155], v[210:213], v[8:11]
	v_mfma_f32_16x16x32_bf16 v[12:15], v[144:147], v[210:213], v[12:15]
	s_setprio 0
	s_setprio 1
	v_mfma_f32_16x16x32_bf16 v[52:55], v[160:163], v[176:179], v[52:55]
	v_mfma_f32_16x16x32_bf16 v[48:51], v[168:171], v[176:179], v[48:51]
	v_mfma_f32_16x16x32_bf16 v[32:35], v[168:171], v[184:187], v[32:35]
	v_mfma_f32_16x16x32_bf16 v[36:39], v[160:163], v[184:187], v[36:39]
	v_mfma_f32_16x16x32_bf16 v[20:23], v[160:163], v[192:195], v[20:23]
	v_mfma_f32_16x16x32_bf16 v[16:19], v[168:171], v[192:195], v[16:19]
	v_mfma_f32_16x16x32_bf16 v[0:3], v[168:171], v[206:209], v[0:3]
	v_mfma_f32_16x16x32_bf16 v[4:7], v[160:163], v[206:209], v[4:7]
	v_mfma_f32_16x16x32_bf16 v[52:55], v[164:167], v[180:183], v[52:55]
	v_mfma_f32_16x16x32_bf16 v[48:51], v[172:175], v[180:183], v[48:51]
	v_mfma_f32_16x16x32_bf16 v[32:35], v[172:175], v[188:191], v[32:35]
	v_mfma_f32_16x16x32_bf16 v[36:39], v[164:167], v[188:191], v[36:39]
	v_mfma_f32_16x16x32_bf16 v[20:23], v[164:167], v[202:205], v[20:23]
	v_mfma_f32_16x16x32_bf16 v[16:19], v[172:175], v[202:205], v[16:19]
	v_mfma_f32_16x16x32_bf16 v[0:3], v[172:175], v[210:213], v[0:3]
	v_mfma_f32_16x16x32_bf16 v[4:7], v[164:167], v[210:213], v[4:7]
	s_barrier
	s_setprio 0
	s_add_i32 s17, s17, 2
	s_add_u32 s4, s4, 0x100
	s_addc_u32 s5, s5, 0
	s_add_u32 s7, s7, 0x100
	s_addc_u32 s15, s15, 0
.LBB0_199:
	s_add_u32 s22, s4, 0xfffc0080
	s_addc_u32 s23, s5, -1
	s_add_i32 s27, 0, 0x10000
	s_cmp_eq_u32 s17, 12
	s_cselect_b32 s25, s19, s23
	s_cselect_b32 s24, s18, s22
	s_cselect_b32 s23, s21, s15
	s_cselect_b32 s22, s20, s7
	s_add_i32 s48, 0, 0x14000
	v_add_u32_e32 v152, s27, v158
	v_add_u32_e32 v172, s48, v158
	ds_read_b128 v[140:143], v152
	ds_read_b128 v[144:147], v152 offset:1024
	ds_read_b128 v[148:151], v152 offset:2048
	ds_read_b128 v[152:155], v152 offset:3072
	ds_read_b128 v[160:163], v172
	ds_read_b128 v[164:167], v172 offset:1024
	ds_read_b128 v[168:171], v172 offset:2048
	ds_read_b128 v[172:175], v172 offset:3072
	v_lshl_add_u64 v[214:215], s[4:5], 0, v[136:137]
	s_add_i32 m0, s55, 0xc000
	ds_read_b128 v[176:179], v159
	ds_read_b128 v[180:183], v159 offset:1024
	ds_read_b128 v[184:187], v159 offset:2048
	ds_read_b128 v[188:191], v159 offset:3072
	ds_read_b128 v[192:195], v159 offset:4096
	ds_read_b128 v[202:205], v159 offset:5120
	ds_read_b128 v[206:209], v159 offset:6144
	ds_read_b128 v[210:213], v159 offset:7168
	global_load_lds_dwordx4 v[214:215], off
	v_lshl_add_u64 v[214:215], s[4:5], 0, v[138:139]
	s_add_i32 m0, s55, 0xe000
	s_nop 0
	global_load_lds_dwordx4 v[214:215], off
	s_waitcnt vmcnt(8)
	s_waitcnt lgkmcnt(0)
	s_setprio 1
	s_barrier
; #define PG8_STAGE(bufoff, gbase, V0, V1) do { \
;         __builtin_amdgcn_global_load_lds((const unsigned*)((const char*)(gbase) + (V0)), (LAS unsigned*)(lds + (bufoff) + ldsw), 16, 0, 0); \
;         __builtin_amdgcn_global_load_lds((const unsigned*)((const char*)(gbase) + (V1)), (LAS unsigned*)(lds + (bufoff) + ldsw + 8192), 16, 0, 0); } while (0)
; #define PG8_LDA(dst, b, h) do { _Pragma("unroll") for (int m = 0; m < 4; ++m) _Pragma("unroll") for (int k = 0; k < 2; ++k) dst[m][k] = *(const LAS bf16x8*)(lds + PG8_SA(b, h) + aoff + m * 2048 + k * 1024); } while (0)
; #define PG8_LDB(dst, b, h) do { _Pragma("unroll") for (int n = 0; n < 2; ++n) _Pragma("unroll") for (int k = 0; k < 2; ++k) dst[n][k] = *(const LAS bf16x8*)(lds + PG8_SB(b, h) + boff + n * 2048 + k * 1024); } while (0)
; #define PG8_MMA(ai, bj, At, Bt) do { __builtin_amdgcn_s_setprio(1); _Pragma("unroll") for (int m = 0; m < 4; ++m) _Pragma("unroll") for (int n = 0; n < 2; ++n) _Pragma("unroll") for (int k = 0; k < 2; ++k) \
;         acc[ai][bj][m][n] = __builtin_amdgcn_mfma_f32_16x16x32_bf16(Bt[n][k], At[m][k], acc[ai][bj][m][n], 0, 0, 0); __builtin_amdgcn_s_setprio(0); } while (0)
; #define PG8_WAIT_V(n) asm volatile("s_waitcnt vmcnt(" #n ")" ::: "memory")
; #define PG8_WAIT_L(n) asm volatile("s_waitcnt lgkmcnt(" #n ")" ::: "memory")
; #define PG8_BAR __builtin_amdgcn_s_barrier()
; #define PG8_SCHED __builtin_amdgcn_sched_barrier(0)
; template <class Epi, class Sched>
; DI void gemm_phase(LAS unsigned char* lds, const int lda2, const int ldb2, const int nt, const Sched& S, const Epi& E) {
;     ...
;             PG8_LDB(B0, 0, 0); PG8_LDB(B1, 0, 1); PG8_SCHED; PG8_LDA(At, 0, 0); PG8_STAGE(PG8_SA(1, 1), a1 + hstepA, vA0, vA1);
;             PG8_WAIT_V(8); PG8_WAIT_L(0); PG8_BAR; PG8_MMA(0, 0, At, B0); PG8_MMA(0, 1, At, B1); PG8_BAR; PG8_SCHED;
;             PG8_LDA(At, 0, 1); PG8_STAGE(PG8_SB(0, 0), b2, vB0, vB1); PG8_STAGE(PG8_SB(0, 1), b2 + hstepB, vB0, vB1); PG8_STAGE(PG8_SA(0, 0), a2, vA0, vA1);
;             PG8_WAIT_V(8); PG8_WAIT_L(0); PG8_BAR; PG8_MMA(1, 0, At, B0); PG8_MMA(1, 1, At, B1); PG8_BAR; PG8_SCHED;
	s_waitcnt lgkmcnt(0)
	v_mfma_f32_16x16x32_bf16 v[126:129], v[140:143], v[176:179], v[126:129]
	v_mfma_f32_16x16x32_bf16 v[122:125], v[148:151], v[176:179], v[122:125]
	v_mfma_f32_16x16x32_bf16 v[106:109], v[148:151], v[184:187], v[106:109]
	v_mfma_f32_16x16x32_bf16 v[110:113], v[140:143], v[184:187], v[110:113]
	v_mfma_f32_16x16x32_bf16 v[92:95], v[140:143], v[192:195], v[92:95]
	v_mfma_f32_16x16x32_bf16 v[88:91], v[148:151], v[192:195], v[88:91]
	v_mfma_f32_16x16x32_bf16 v[72:75], v[148:151], v[206:209], v[72:75]
	v_mfma_f32_16x16x32_bf16 v[76:79], v[140:143], v[206:209], v[76:79]
	v_mfma_f32_16x16x32_bf16 v[126:129], v[144:147], v[180:183], v[126:129]
	v_mfma_f32_16x16x32_bf16 v[122:125], v[152:155], v[180:183], v[122:125]
	v_mfma_f32_16x16x32_bf16 v[106:109], v[152:155], v[188:191], v[106:109]
	v_mfma_f32_16x16x32_bf16 v[110:113], v[144:147], v[188:191], v[110:113]
	v_mfma_f32_16x16x32_bf16 v[92:95], v[144:147], v[202:205], v[92:95]
	v_mfma_f32_16x16x32_bf16 v[88:91], v[152:155], v[202:205], v[88:91]
	v_mfma_f32_16x16x32_bf16 v[72:75], v[152:155], v[210:213], v[72:75]
	v_mfma_f32_16x16x32_bf16 v[76:79], v[144:147], v[210:213], v[76:79]
	s_setprio 0
	s_setprio 1
	v_mfma_f32_16x16x32_bf16 v[118:121], v[160:163], v[176:179], v[118:121]
	v_mfma_f32_16x16x32_bf16 v[114:117], v[168:171], v[176:179], v[114:117]
	v_mfma_f32_16x16x32_bf16 v[98:101], v[168:171], v[184:187], v[98:101]
	v_mfma_f32_16x16x32_bf16 v[102:105], v[160:163], v[184:187], v[102:105]
	v_mfma_f32_16x16x32_bf16 v[84:87], v[160:163], v[192:195], v[84:87]
	v_mfma_f32_16x16x32_bf16 v[80:83], v[168:171], v[192:195], v[80:83]
	v_mfma_f32_16x16x32_bf16 v[64:67], v[168:171], v[206:209], v[64:67]
	v_mfma_f32_16x16x32_bf16 v[68:71], v[160:163], v[206:209], v[68:71]
	v_mfma_f32_16x16x32_bf16 v[118:121], v[164:167], v[180:183], v[118:121]
	v_mfma_f32_16x16x32_bf16 v[114:117], v[172:175], v[180:183], v[114:117]
	v_mfma_f32_16x16x32_bf16 v[98:101], v[172:175], v[188:191], v[98:101]
	v_mfma_f32_16x16x32_bf16 v[102:105], v[164:167], v[188:191], v[102:105]
	v_mfma_f32_16x16x32_bf16 v[84:87], v[164:167], v[202:205], v[84:87]
	v_mfma_f32_16x16x32_bf16 v[80:83], v[172:175], v[202:205], v[80:83]
	v_mfma_f32_16x16x32_bf16 v[64:67], v[172:175], v[210:213], v[64:67]
	v_mfma_f32_16x16x32_bf16 v[68:71], v[164:167], v[210:213], v[68:71]
	s_barrier
	s_setprio 0
	s_add_i32 s27, s27, s54
	v_lshl_add_u64 v[214:215], s[22:23], 0, v[96:97]
	s_mov_b32 m0, s27
	ds_read_b128 v[176:179], v159 offset:16384
	ds_read_b128 v[180:183], v159 offset:17408
	ds_read_b128 v[184:187], v159 offset:18432
	ds_read_b128 v[188:191], v159 offset:19456
	ds_read_b128 v[192:195], v159 offset:20480
	ds_read_b128 v[202:205], v159 offset:21504
	ds_read_b128 v[206:209], v159 offset:22528
	ds_read_b128 v[210:213], v159 offset:23552
	global_load_lds_dwordx4 v[214:215], off
	s_add_i32 m0, s27, 0x2000
	s_add_u32 s28, s22, 0x40000
	v_lshl_add_u64 v[216:217], s[22:23], 0, v[130:131]
	s_addc_u32 s29, s23, 0
	s_add_i32 s27, s48, s54
	global_load_lds_dwordx4 v[216:217], off
	v_lshl_add_u64 v[218:219], s[28:29], 0, v[96:97]
	s_mov_b32 m0, s27
	v_lshl_add_u64 v[220:221], s[24:25], 0, v[134:135]
	global_load_lds_dwordx4 v[218:219], off
	v_lshl_add_u64 v[218:219], s[28:29], 0, v[130:131]
	s_add_i32 m0, s27, 0x2000
	s_nop 0
	global_load_lds_dwordx4 v[218:219], off
	v_lshl_add_u64 v[218:219], s[24:25], 0, v[132:133]
	s_mov_b32 m0, s55
	s_nop 0
	global_load_lds_dwordx4 v[218:219], off
	s_mov_b32 m0, s72
	s_nop 0
	global_load_lds_dwordx4 v[220:221], off
	s_waitcnt vmcnt(8)
	s_waitcnt lgkmcnt(0)
	s_setprio 1
	s_barrier
	s_waitcnt lgkmcnt(0)
	v_mfma_f32_16x16x32_bf16 v[60:63], v[140:143], v[176:179], v[60:63]
	v_mfma_f32_16x16x32_bf16 v[56:59], v[148:151], v[176:179], v[56:59]
	v_mfma_f32_16x16x32_bf16 v[40:43], v[148:151], v[184:187], v[40:43]
	v_mfma_f32_16x16x32_bf16 v[44:47], v[140:143], v[184:187], v[44:47]
	v_mfma_f32_16x16x32_bf16 v[28:31], v[140:143], v[192:195], v[28:31]
	v_mfma_f32_16x16x32_bf16 v[24:27], v[148:151], v[192:195], v[24:27]
	v_mfma_f32_16x16x32_bf16 v[8:11], v[148:151], v[206:209], v[8:11]
	v_mfma_f32_16x16x32_bf16 v[12:15], v[140:143], v[206:209], v[12:15]
	v_mfma_f32_16x16x32_bf16 v[60:63], v[144:147], v[180:183], v[60:63]
	v_mfma_f32_16x16x32_bf16 v[56:59], v[152:155], v[180:183], v[56:59]
	v_mfma_f32_16x16x32_bf16 v[40:43], v[152:155], v[188:191], v[40:43]
	v_mfma_f32_16x16x32_bf16 v[44:47], v[144:147], v[188:191], v[44:47]
	v_mfma_f32_16x16x32_bf16 v[28:31], v[144:147], v[202:205], v[28:31]
	v_mfma_f32_16x16x32_bf16 v[24:27], v[152:155], v[202:205], v[24:27]
	v_mfma_f32_16x16x32_bf16 v[8:11], v[152:155], v[210:213], v[8:11]
	v_mfma_f32_16x16x32_bf16 v[12:15], v[144:147], v[210:213], v[12:15]
	s_setprio 0
	s_setprio 1
	v_mfma_f32_16x16x32_bf16 v[52:55], v[160:163], v[176:179], v[52:55]
	v_mfma_f32_16x16x32_bf16 v[48:51], v[168:171], v[176:179], v[48:51]
	v_mfma_f32_16x16x32_bf16 v[32:35], v[168:171], v[184:187], v[32:35]
	v_mfma_f32_16x16x32_bf16 v[36:39], v[160:163], v[184:187], v[36:39]
	v_mfma_f32_16x16x32_bf16 v[20:23], v[160:163], v[192:195], v[20:23]
	v_mfma_f32_16x16x32_bf16 v[16:19], v[168:171], v[192:195], v[16:19]
	v_mfma_f32_16x16x32_bf16 v[0:3], v[168:171], v[206:209], v[0:3]
	v_mfma_f32_16x16x32_bf16 v[4:7], v[160:163], v[206:209], v[4:7]
	v_mfma_f32_16x16x32_bf16 v[52:55], v[164:167], v[180:183], v[52:55]
	v_mfma_f32_16x16x32_bf16 v[48:51], v[172:175], v[180:183], v[48:51]
	v_mfma_f32_16x16x32_bf16 v[32:35], v[172:175], v[188:191], v[32:35]
	v_mfma_f32_16x16x32_bf16 v[36:39], v[164:167], v[188:191], v[36:39]
	v_mfma_f32_16x16x32_bf16 v[20:23], v[164:167], v[202:205], v[20:23]
	v_mfma_f32_16x16x32_bf16 v[16:19], v[172:175], v[202:205], v[16:19]
	v_mfma_f32_16x16x32_bf16 v[0:3], v[172:175], v[210:213], v[0:3]
	v_mfma_f32_16x16x32_bf16 v[4:7], v[164:167], v[210:213], v[4:7]
	s_barrier
; #define PG8_STAGE(bufoff, gbase, V0, V1) do { \
;         __builtin_amdgcn_global_load_lds((const unsigned*)((const char*)(gbase) + (V0)), (LAS unsigned*)(lds + (bufoff) + ldsw), 16, 0, 0); \
;         __builtin_amdgcn_global_load_lds((const unsigned*)((const char*)(gbase) + (V1)), (LAS unsigned*)(lds + (bufoff) + ldsw + 8192), 16, 0, 0); } while (0)
; #define PG8_LDA(dst, b, h) do { _Pragma("unroll") for (int m = 0; m < 4; ++m) _Pragma("unroll") for (int k = 0; k < 2; ++k) dst[m][k] = *(const LAS bf16x8*)(lds + PG8_SA(b, h) + aoff + m * 2048 + k * 1024); } while (0)
; #define PG8_LDB(dst, b, h) do { _Pragma("unroll") for (int n = 0; n < 2; ++n) _Pragma("unroll") for (int k = 0; k < 2; ++k) dst[n][k] = *(const LAS bf16x8*)(lds + PG8_SB(b, h) + boff + n * 2048 + k * 1024); } while (0)
; #define PG8_MMA(ai, bj, At, Bt) do { __builtin_amdgcn_s_setprio(1); _Pragma("unroll") for (int m = 0; m < 4; ++m) _Pragma("unroll") for (int n = 0; n < 2; ++n) _Pragma("unroll") for (int k = 0; k < 2; ++k) \
;         acc[ai][bj][m][n] = __builtin_amdgcn_mfma_f32_16x16x32_bf16(Bt[n][k], At[m][k], acc[ai][bj][m][n], 0, 0, 0); __builtin_amdgcn_s_setprio(0); } while (0)
; #define PG8_WAIT_V(n) asm volatile("s_waitcnt vmcnt(" #n ")" ::: "memory")
; #define PG8_WAIT_L(n) asm volatile("s_waitcnt lgkmcnt(" #n ")" ::: "memory")
; #define PG8_BAR __builtin_amdgcn_s_barrier()
; #define PG8_SCHED __builtin_amdgcn_sched_barrier(0)
; template <class Epi, class Sched>
; DI void gemm_phase(LAS unsigned char* lds, const int lda2, const int ldb2, const int nt, const Sched& S, const Epi& E) {
;     ...
;             PG8_LDB(B0, 1, 0); PG8_LDB(B1, 1, 1); PG8_SCHED; PG8_LDA(At, 1, 0); PG8_STAGE(PG8_SA(0, 1), a2 + hstepA, vA0, vA1);
;             PG8_WAIT_V(8); PG8_WAIT_L(0); PG8_BAR; PG8_MMA(0, 0, At, B0); PG8_MMA(0, 1, At, B1); PG8_BAR; PG8_SCHED;
	s_setprio 0
	s_add_i32 s27, 0, 0x18000
	s_add_i32 s28, 0, 0x1c000
	v_add_u32_e32 v152, s27, v158
	v_add_u32_e32 v172, s28, v158
	ds_read_b128 v[140:143], v152
	ds_read_b128 v[144:147], v152 offset:1024
	ds_read_b128 v[148:151], v152 offset:2048
	ds_read_b128 v[152:155], v152 offset:3072
	ds_read_b128 v[160:163], v172
	ds_read_b128 v[164:167], v172 offset:1024
	ds_read_b128 v[168:171], v172 offset:2048
	ds_read_b128 v[172:175], v172 offset:3072
	s_add_u32 s24, s24, 0x40000
	s_addc_u32 s25, s25, 0
	s_mov_b32 m0, s73
	v_lshl_add_u64 v[222:223], s[24:25], 0, v[132:133]
	ds_read_b128 v[176:179], v159 offset:32768
	ds_read_b128 v[180:183], v159 offset:33792
	ds_read_b128 v[184:187], v159 offset:34816
	ds_read_b128 v[188:191], v159 offset:35840
	ds_read_b128 v[192:195], v159 offset:36864
	ds_read_b128 v[202:205], v159 offset:37888
	ds_read_b128 v[206:209], v159 offset:38912
	ds_read_b128 v[210:213], v159 offset:39936
	global_load_lds_dwordx4 v[222:223], off
	v_lshl_add_u64 v[222:223], s[24:25], 0, v[134:135]
	s_mov_b32 m0, s74
	s_nop 0
	global_load_lds_dwordx4 v[222:223], off
	s_waitcnt vmcnt(8)
	s_waitcnt lgkmcnt(0)
	s_setprio 1
	s_barrier
	s_waitcnt lgkmcnt(0)
	v_mfma_f32_16x16x32_bf16 v[126:129], v[140:143], v[176:179], v[126:129]
	v_mfma_f32_16x16x32_bf16 v[122:125], v[148:151], v[176:179], v[122:125]
	v_mfma_f32_16x16x32_bf16 v[106:109], v[148:151], v[184:187], v[106:109]
	v_mfma_f32_16x16x32_bf16 v[110:113], v[140:143], v[184:187], v[110:113]
	v_mfma_f32_16x16x32_bf16 v[92:95], v[140:143], v[192:195], v[92:95]
	v_mfma_f32_16x16x32_bf16 v[88:91], v[148:151], v[192:195], v[88:91]
	v_mfma_f32_16x16x32_bf16 v[72:75], v[148:151], v[206:209], v[72:75]
	v_mfma_f32_16x16x32_bf16 v[76:79], v[140:143], v[206:209], v[76:79]
	v_mfma_f32_16x16x32_bf16 v[126:129], v[144:147], v[180:183], v[126:129]
	v_mfma_f32_16x16x32_bf16 v[122:125], v[152:155], v[180:183], v[122:125]
	v_mfma_f32_16x16x32_bf16 v[106:109], v[152:155], v[188:191], v[106:109]
	v_mfma_f32_16x16x32_bf16 v[110:113], v[144:147], v[188:191], v[110:113]
	v_mfma_f32_16x16x32_bf16 v[92:95], v[144:147], v[202:205], v[92:95]
	v_mfma_f32_16x16x32_bf16 v[88:91], v[152:155], v[202:205], v[88:91]
	v_mfma_f32_16x16x32_bf16 v[72:75], v[152:155], v[210:213], v[72:75]
	v_mfma_f32_16x16x32_bf16 v[76:79], v[144:147], v[210:213], v[76:79]
	s_setprio 0
	s_setprio 1
	v_mfma_f32_16x16x32_bf16 v[118:121], v[160:163], v[176:179], v[118:121]
	v_mfma_f32_16x16x32_bf16 v[114:117], v[168:171], v[176:179], v[114:117]
	v_mfma_f32_16x16x32_bf16 v[98:101], v[168:171], v[184:187], v[98:101]
	v_mfma_f32_16x16x32_bf16 v[102:105], v[160:163], v[184:187], v[102:105]
	v_mfma_f32_16x16x32_bf16 v[84:87], v[160:163], v[192:195], v[84:87]
	v_mfma_f32_16x16x32_bf16 v[80:83], v[168:171], v[192:195], v[80:83]
	v_mfma_f32_16x16x32_bf16 v[64:67], v[168:171], v[206:209], v[64:67]
	v_mfma_f32_16x16x32_bf16 v[68:71], v[160:163], v[206:209], v[68:71]
	v_mfma_f32_16x16x32_bf16 v[118:121], v[164:167], v[180:183], v[118:121]
	v_mfma_f32_16x16x32_bf16 v[114:117], v[172:175], v[180:183], v[114:117]
	v_mfma_f32_16x16x32_bf16 v[98:101], v[172:175], v[188:191], v[98:101]
	v_mfma_f32_16x16x32_bf16 v[102:105], v[164:167], v[188:191], v[102:105]
	v_mfma_f32_16x16x32_bf16 v[84:87], v[164:167], v[202:205], v[84:87]
	v_mfma_f32_16x16x32_bf16 v[80:83], v[172:175], v[202:205], v[80:83]
	v_mfma_f32_16x16x32_bf16 v[64:67], v[172:175], v[210:213], v[64:67]
	v_mfma_f32_16x16x32_bf16 v[68:71], v[164:167], v[210:213], v[68:71]
	s_barrier
; #define PG8_STAGE(bufoff, gbase, V0, V1) do { \
;         __builtin_amdgcn_global_load_lds((const unsigned*)((const char*)(gbase) + (V0)), (LAS unsigned*)(lds + (bufoff) + ldsw), 16, 0, 0); \
;         __builtin_amdgcn_global_load_lds((const unsigned*)((const char*)(gbase) + (V1)), (LAS unsigned*)(lds + (bufoff) + ldsw + 8192), 16, 0, 0); } while (0)
; #define PG8_LDA(dst, b, h) do { _Pragma("unroll") for (int m = 0; m < 4; ++m) _Pragma("unroll") for (int k = 0; k < 2; ++k) dst[m][k] = *(const LAS bf16x8*)(lds + PG8_SA(b, h) + aoff + m * 2048 + k * 1024); } while (0)
; #define PG8_MMA(ai, bj, At, Bt) do { __builtin_amdgcn_s_setprio(1); _Pragma("unroll") for (int m = 0; m < 4; ++m) _Pragma("unroll") for (int n = 0; n < 2; ++n) _Pragma("unroll") for (int k = 0; k < 2; ++k) \
;         acc[ai][bj][m][n] = __builtin_amdgcn_mfma_f32_16x16x32_bf16(Bt[n][k], At[m][k], acc[ai][bj][m][n], 0, 0, 0); __builtin_amdgcn_s_setprio(0); } while (0)
; #define PG8_WAIT_V(n) asm volatile("s_waitcnt vmcnt(" #n ")" ::: "memory")
; #define PG8_WAIT_L(n) asm volatile("s_waitcnt lgkmcnt(" #n ")" ::: "memory")
; #define PG8_BAR __builtin_amdgcn_s_barrier()
; #define PG8_SCHED __builtin_amdgcn_sched_barrier(0)
; template <class Epi, class Sched>
; DI void gemm_phase(LAS unsigned char* lds, const int lda2, const int ldb2, const int nt, const Sched& S, const Epi& E) {
;     ...
;             PG8_LDA(At, 1, 1); PG8_STAGE(PG8_SB(1, 0), b3, vB0, vB1); PG8_STAGE(PG8_SB(1, 1), b3 + hstepB, vB0, vB1); PG8_STAGE(PG8_SA(1, 0), a3, vA0, vA1);
;             PG8_WAIT_V(8); PG8_WAIT_L(0); PG8_BAR; PG8_MMA(1, 0, At, B0); PG8_MMA(1, 1, At, B1); PG8_BAR; PG8_SCHED;
;         }
;         if (wr == 0) PG8_BAR;
	s_setprio 0
	s_add_i32 s24, s27, s54
	v_lshl_add_u64 v[214:215], v[214:215], 0, s[86:87]
	s_mov_b32 m0, s24
	ds_read_b128 v[176:179], v159 offset:49152
	ds_read_b128 v[180:183], v159 offset:50176
	ds_read_b128 v[184:187], v159 offset:51200
	ds_read_b128 v[188:191], v159 offset:52224
	ds_read_b128 v[192:195], v159 offset:53248
	ds_read_b128 v[202:205], v159 offset:54272
	ds_read_b128 v[206:209], v159 offset:55296
	ds_read_b128 v[210:213], v159 offset:56320
	global_load_lds_dwordx4 v[214:215], off
	s_add_i32 m0, s24, 0x2000
	s_add_u32 s22, s22, 0x40080
	v_lshl_add_u64 v[214:215], v[216:217], 0, s[86:87]
	s_addc_u32 s23, s23, 0
	s_add_i32 s24, s28, s54
	global_load_lds_dwordx4 v[214:215], off
	v_lshl_add_u64 v[214:215], s[22:23], 0, v[96:97]
	s_mov_b32 m0, s24
	s_nop 0
	global_load_lds_dwordx4 v[214:215], off
	v_lshl_add_u64 v[214:215], s[22:23], 0, v[130:131]
	s_add_i32 m0, s24, 0x2000
	s_nop 0
	global_load_lds_dwordx4 v[214:215], off
	v_lshl_add_u64 v[214:215], v[218:219], 0, s[86:87]
	s_mov_b32 m0, s77
	s_nop 0
	global_load_lds_dwordx4 v[214:215], off
	v_lshl_add_u64 v[214:215], v[220:221], 0, s[86:87]
	s_mov_b32 m0, s78
	s_nop 0
	global_load_lds_dwordx4 v[214:215], off
	s_waitcnt vmcnt(8)
	s_waitcnt lgkmcnt(0)
	s_setprio 1
	s_barrier
	s_waitcnt lgkmcnt(0)
	v_mfma_f32_16x16x32_bf16 v[60:63], v[140:143], v[176:179], v[60:63]
	v_mfma_f32_16x16x32_bf16 v[56:59], v[148:151], v[176:179], v[56:59]
	v_mfma_f32_16x16x32_bf16 v[40:43], v[148:151], v[184:187], v[40:43]
	v_mfma_f32_16x16x32_bf16 v[44:47], v[140:143], v[184:187], v[44:47]
	v_mfma_f32_16x16x32_bf16 v[28:31], v[140:143], v[192:195], v[28:31]
	v_mfma_f32_16x16x32_bf16 v[24:27], v[148:151], v[192:195], v[24:27]
	v_mfma_f32_16x16x32_bf16 v[8:11], v[148:151], v[206:209], v[8:11]
	v_mfma_f32_16x16x32_bf16 v[12:15], v[140:143], v[206:209], v[12:15]
	v_mfma_f32_16x16x32_bf16 v[60:63], v[144:147], v[180:183], v[60:63]
	v_mfma_f32_16x16x32_bf16 v[56:59], v[152:155], v[180:183], v[56:59]
	v_mfma_f32_16x16x32_bf16 v[40:43], v[152:155], v[188:191], v[40:43]
	v_mfma_f32_16x16x32_bf16 v[44:47], v[144:147], v[188:191], v[44:47]
	v_mfma_f32_16x16x32_bf16 v[28:31], v[144:147], v[202:205], v[28:31]
	v_mfma_f32_16x16x32_bf16 v[24:27], v[152:155], v[202:205], v[24:27]
	v_mfma_f32_16x16x32_bf16 v[8:11], v[152:155], v[210:213], v[8:11]
	v_mfma_f32_16x16x32_bf16 v[12:15], v[144:147], v[210:213], v[12:15]
	s_setprio 0
	s_setprio 1
	v_mfma_f32_16x16x32_bf16 v[52:55], v[160:163], v[176:179], v[52:55]
	v_mfma_f32_16x16x32_bf16 v[48:51], v[168:171], v[176:179], v[48:51]
	v_mfma_f32_16x16x32_bf16 v[32:35], v[168:171], v[184:187], v[32:35]
	v_mfma_f32_16x16x32_bf16 v[36:39], v[160:163], v[184:187], v[36:39]
	v_mfma_f32_16x16x32_bf16 v[20:23], v[160:163], v[192:195], v[20:23]
	v_mfma_f32_16x16x32_bf16 v[16:19], v[168:171], v[192:195], v[16:19]
	v_mfma_f32_16x16x32_bf16 v[0:3], v[168:171], v[206:209], v[0:3]
	v_mfma_f32_16x16x32_bf16 v[4:7], v[160:163], v[206:209], v[4:7]
	v_mfma_f32_16x16x32_bf16 v[52:55], v[164:167], v[180:183], v[52:55]
	v_mfma_f32_16x16x32_bf16 v[48:51], v[172:175], v[180:183], v[48:51]
	v_mfma_f32_16x16x32_bf16 v[32:35], v[172:175], v[188:191], v[32:35]
	v_mfma_f32_16x16x32_bf16 v[36:39], v[164:167], v[188:191], v[36:39]
	v_mfma_f32_16x16x32_bf16 v[20:23], v[164:167], v[202:205], v[20:23]
	v_mfma_f32_16x16x32_bf16 v[16:19], v[172:175], v[202:205], v[16:19]
	v_mfma_f32_16x16x32_bf16 v[0:3], v[172:175], v[210:213], v[0:3]
	v_mfma_f32_16x16x32_bf16 v[4:7], v[164:167], v[210:213], v[4:7]
	s_barrier
	s_setprio 0
	s_add_i32 s17, s17, 2
	s_add_u32 s4, s4, 0x100
	s_addc_u32 s5, s5, 0
	s_add_u32 s7, s7, 0x100
	s_addc_u32 s15, s15, 0
	s_cmp_gt_u32 s17, 13
	s_cbranch_scc0 .LBB0_199
	s_and_b64 vcc, exec, s[12:13]
	s_cbranch_vccz .LBB0_202
	s_barrier

; #define PG8_STAGE(bufoff, gbase, V0, V1) do { \
;         __builtin_amdgcn_global_load_lds((const unsigned*)((const char*)(gbase) + (V0)), (LAS unsigned*)(lds + (bufoff) + ldsw), 16, 0, 0); \
;         __builtin_amdgcn_global_load_lds((const unsigned*)((const char*)(gbase) + (V1)), (LAS unsigned*)(lds + (bufoff) + ldsw + 8192), 16, 0, 0); } while (0)
; #define PG8_LDA(dst, b, h) do { _Pragma("unroll") for (int m = 0; m < 4; ++m) _Pragma("unroll") for (int k = 0; k < 2; ++k) dst[m][k] = *(const LAS bf16x8*)(lds + PG8_SA(b, h) + aoff + m * 2048 + k * 1024); } while (0)
; #define PG8_LDB(dst, b, h) do { _Pragma("unroll") for (int n = 0; n < 2; ++n) _Pragma("unroll") for (int k = 0; k < 2; ++k) dst[n][k] = *(const LAS bf16x8*)(lds + PG8_SB(b, h) + boff + n * 2048 + k * 1024); } while (0)
; #define PG8_MMA(ai, bj, At, Bt) do { __builtin_amdgcn_s_setprio(1); _Pragma("unroll") for (int m = 0; m < 4; ++m) _Pragma("unroll") for (int n = 0; n < 2; ++n) _Pragma("unroll") for (int k = 0; k < 2; ++k) \
;         acc[ai][bj][m][n] = __builtin_amdgcn_mfma_f32_16x16x32_bf16(Bt[n][k], At[m][k], acc[ai][bj][m][n], 0, 0, 0); __builtin_amdgcn_s_setprio(0); } while (0)
; #define PG8_WAIT_V(n) asm volatile("s_waitcnt vmcnt(" #n ")" ::: "memory")
; #define PG8_WAIT_L(n) asm volatile("s_waitcnt lgkmcnt(" #n ")" ::: "memory")
; #define PG8_BAR __builtin_amdgcn_s_barrier()
; #define PG8_SCHED __builtin_amdgcn_sched_barrier(0)
; template <class Epi, class Sched>
; DI void gemm_phase(LAS unsigned char* lds, const int lda2, const int ldb2, const int nt, const Sched& S, const Epi& E) {
;     ...
;             PG8_LDB(B0, 0, 0); PG8_LDB(B1, 0, 1); PG8_SCHED; PG8_LDA(At, 0, 0); PG8_STAGE(PG8_SA(1, 1), a1 + hstepA, vA0, vA1);
;             PG8_WAIT_V(8); PG8_WAIT_L(0); PG8_BAR; PG8_MMA(0, 0, At, B0); PG8_MMA(0, 1, At, B1); PG8_BAR; PG8_SCHED;
;             PG8_LDA(At, 0, 1); PG8_STAGE(PG8_SB(0, 0), b2, vB0, vB1); PG8_STAGE(PG8_SB(0, 1), b2 + hstepB, vB0, vB1); PG8_STAGE(PG8_SA(0, 0), a2, vA0, vA1);
;             PG8_WAIT_V(8); PG8_WAIT_L(0); PG8_BAR; PG8_MMA(1, 0, At, B0); PG8_MMA(1, 1, At, B1); PG8_BAR; PG8_SCHED;
.LBB0_680:
	s_add_u32 s24, s6, 0xffe90080
	s_addc_u32 s25, s7, -1
	s_add_i32 s51, 0, 0x10000
	s_cmp_eq_u32 s50, 4
	s_cselect_b32 s27, s21, s25
	s_cselect_b32 s26, s20, s24
	v_add_u32_e32 v96, s51, v238
	s_cselect_b32 s25, s23, s49
	s_cselect_b32 s24, s22, s5
	s_add_i32 s85, 0, 0x14000
	ds_read_b128 v[132:135], v96
	ds_read_b128 v[136:139], v96 offset:1024
	ds_read_b128 v[140:143], v96 offset:2048
	ds_read_b128 v[144:147], v96 offset:3072
	v_add_u32_e32 v96, s85, v238
	ds_read_b128 v[148:151], v96
	ds_read_b128 v[152:155], v96 offset:1024
	ds_read_b128 v[156:159], v96 offset:2048
	ds_read_b128 v[160:163], v96 offset:3072
	v_lshl_add_u64 v[98:99], s[6:7], 0, v[210:211]
	s_add_i32 m0, s52, 0xc000
	ds_read_b128 v[164:167], v239
	ds_read_b128 v[168:171], v239 offset:1024
	ds_read_b128 v[172:175], v239 offset:2048
	ds_read_b128 v[176:179], v239 offset:3072
	ds_read_b128 v[180:183], v239 offset:4096
	ds_read_b128 v[184:187], v239 offset:5120
	ds_read_b128 v[188:191], v239 offset:6144
	ds_read_b128 v[192:195], v239 offset:7168
	global_load_lds_dwordx4 v[98:99], off
	v_lshl_add_u64 v[98:99], s[6:7], 0, v[212:213]
	s_add_i32 m0, s52, 0xe000
	s_nop 0
	global_load_lds_dwordx4 v[98:99], off
	s_waitcnt vmcnt(8)
	s_waitcnt lgkmcnt(0)
	s_setprio 1
	s_barrier
	s_waitcnt lgkmcnt(0)
	v_mfma_f32_16x16x32_bf16 v[128:131], v[132:135], v[164:167], v[128:131]
	v_mfma_f32_16x16x32_bf16 v[124:127], v[140:143], v[164:167], v[124:127]
	v_mfma_f32_16x16x32_bf16 v[116:119], v[140:143], v[172:175], v[116:119]
	v_mfma_f32_16x16x32_bf16 v[120:123], v[132:135], v[172:175], v[120:123]
	v_mfma_f32_16x16x32_bf16 v[112:115], v[132:135], v[180:183], v[112:115]
	v_mfma_f32_16x16x32_bf16 v[108:111], v[140:143], v[180:183], v[108:111]
	v_mfma_f32_16x16x32_bf16 v[98:101], v[140:143], v[188:191], v[100:103]
	v_mfma_f32_16x16x32_bf16 v[104:107], v[132:135], v[188:191], v[104:107]
	v_mfma_f32_16x16x32_bf16 v[128:131], v[136:139], v[168:171], v[128:131]
	v_mfma_f32_16x16x32_bf16 v[124:127], v[144:147], v[168:171], v[124:127]
	v_mfma_f32_16x16x32_bf16 v[116:119], v[144:147], v[176:179], v[116:119]
	v_mfma_f32_16x16x32_bf16 v[120:123], v[136:139], v[176:179], v[120:123]
	v_mfma_f32_16x16x32_bf16 v[112:115], v[136:139], v[184:187], v[112:115]
	v_mfma_f32_16x16x32_bf16 v[108:111], v[144:147], v[184:187], v[108:111]
	v_mfma_f32_16x16x32_bf16 v[98:101], v[144:147], v[192:195], v[98:101]
	v_mfma_f32_16x16x32_bf16 v[104:107], v[136:139], v[192:195], v[104:107]
	s_setprio 0
	s_setprio 1
	v_mfma_f32_16x16x32_bf16 v[92:95], v[148:151], v[164:167], v[92:95]
	v_mfma_f32_16x16x32_bf16 v[88:91], v[156:159], v[164:167], v[88:91]
	v_mfma_f32_16x16x32_bf16 v[80:83], v[156:159], v[172:175], v[80:83]
	v_mfma_f32_16x16x32_bf16 v[84:87], v[148:151], v[172:175], v[84:87]
	v_mfma_f32_16x16x32_bf16 v[76:79], v[148:151], v[180:183], v[76:79]
	v_mfma_f32_16x16x32_bf16 v[72:75], v[156:159], v[180:183], v[72:75]
	v_mfma_f32_16x16x32_bf16 v[64:67], v[156:159], v[188:191], v[64:67]
	v_mfma_f32_16x16x32_bf16 v[68:71], v[148:151], v[188:191], v[68:71]
	v_mfma_f32_16x16x32_bf16 v[92:95], v[152:155], v[168:171], v[92:95]
	v_mfma_f32_16x16x32_bf16 v[88:91], v[160:163], v[168:171], v[88:91]
	v_mfma_f32_16x16x32_bf16 v[80:83], v[160:163], v[176:179], v[80:83]
	v_mfma_f32_16x16x32_bf16 v[84:87], v[152:155], v[176:179], v[84:87]
	v_mfma_f32_16x16x32_bf16 v[76:79], v[152:155], v[184:187], v[76:79]
	v_mfma_f32_16x16x32_bf16 v[72:75], v[160:163], v[184:187], v[72:75]
	v_mfma_f32_16x16x32_bf16 v[64:67], v[160:163], v[192:195], v[64:67]
	v_mfma_f32_16x16x32_bf16 v[68:71], v[152:155], v[192:195], v[68:71]
	s_barrier
	s_setprio 0
	s_add_i32 s51, s51, s47
	v_lshl_add_u64 v[214:215], s[24:25], 0, v[202:203]
	s_mov_b32 m0, s51
	ds_read_b128 v[164:167], v239 offset:16384
	ds_read_b128 v[168:171], v239 offset:17408
	ds_read_b128 v[172:175], v239 offset:18432
	ds_read_b128 v[176:179], v239 offset:19456
	ds_read_b128 v[180:183], v239 offset:20480
	ds_read_b128 v[184:187], v239 offset:21504
	ds_read_b128 v[188:191], v239 offset:22528
	ds_read_b128 v[192:195], v239 offset:23552
	global_load_lds_dwordx4 v[214:215], off
	s_add_i32 m0, s51, 0x2000
	s_add_u32 s56, s24, 0x60000
	v_lshl_add_u64 v[216:217], s[24:25], 0, v[204:205]
	s_addc_u32 s57, s25, 0
	s_add_i32 s51, s85, s47
	global_load_lds_dwordx4 v[216:217], off
	v_lshl_add_u64 v[102:103], s[56:57], 0, v[202:203]
	s_mov_b32 m0, s51
	v_lshl_add_u64 v[218:219], s[26:27], 0, v[206:207]
	global_load_lds_dwordx4 v[102:103], off
	v_lshl_add_u64 v[102:103], s[56:57], 0, v[204:205]
	s_add_i32 m0, s51, 0x2000
	v_lshl_add_u64 v[220:221], s[26:27], 0, v[208:209]
	global_load_lds_dwordx4 v[102:103], off
	s_mov_b32 m0, s52
	s_nop 0
	global_load_lds_dwordx4 v[218:219], off
	s_mov_b32 m0, s53
	s_nop 0
	global_load_lds_dwordx4 v[220:221], off
	s_waitcnt vmcnt(8)
	s_waitcnt lgkmcnt(0)
	s_setprio 1
	s_barrier
; #define PG8_STAGE(bufoff, gbase, V0, V1) do { \
;         __builtin_amdgcn_global_load_lds((const unsigned*)((const char*)(gbase) + (V0)), (LAS unsigned*)(lds + (bufoff) + ldsw), 16, 0, 0); \
;         __builtin_amdgcn_global_load_lds((const unsigned*)((const char*)(gbase) + (V1)), (LAS unsigned*)(lds + (bufoff) + ldsw + 8192), 16, 0, 0); } while (0)
; #define PG8_LDA(dst, b, h) do { _Pragma("unroll") for (int m = 0; m < 4; ++m) _Pragma("unroll") for (int k = 0; k < 2; ++k) dst[m][k] = *(const LAS bf16x8*)(lds + PG8_SA(b, h) + aoff + m * 2048 + k * 1024); } while (0)
; #define PG8_LDB(dst, b, h) do { _Pragma("unroll") for (int n = 0; n < 2; ++n) _Pragma("unroll") for (int k = 0; k < 2; ++k) dst[n][k] = *(const LAS bf16x8*)(lds + PG8_SB(b, h) + boff + n * 2048 + k * 1024); } while (0)
; #define PG8_MMA(ai, bj, At, Bt) do { __builtin_amdgcn_s_setprio(1); _Pragma("unroll") for (int m = 0; m < 4; ++m) _Pragma("unroll") for (int n = 0; n < 2; ++n) _Pragma("unroll") for (int k = 0; k < 2; ++k) \
;         acc[ai][bj][m][n] = __builtin_amdgcn_mfma_f32_16x16x32_bf16(Bt[n][k], At[m][k], acc[ai][bj][m][n], 0, 0, 0); __builtin_amdgcn_s_setprio(0); } while (0)
; #define PG8_WAIT_V(n) asm volatile("s_waitcnt vmcnt(" #n ")" ::: "memory")
; #define PG8_WAIT_L(n) asm volatile("s_waitcnt lgkmcnt(" #n ")" ::: "memory")
; #define PG8_BAR __builtin_amdgcn_s_barrier()
; #define PG8_SCHED __builtin_amdgcn_sched_barrier(0)
; template <class Epi, class Sched>
; DI void gemm_phase(LAS unsigned char* lds, const int lda2, const int ldb2, const int nt, const Sched& S, const Epi& E) {
;     ...
;             PG8_WAIT_V(8); PG8_WAIT_L(0); PG8_BAR; PG8_MMA(0, 0, At, B0); PG8_MMA(0, 1, At, B1); PG8_BAR; PG8_SCHED;
;             PG8_LDA(At, 0, 1); PG8_STAGE(PG8_SB(0, 0), b2, vB0, vB1); PG8_STAGE(PG8_SB(0, 1), b2 + hstepB, vB0, vB1); PG8_STAGE(PG8_SA(0, 0), a2, vA0, vA1);
;             PG8_WAIT_V(8); PG8_WAIT_L(0); PG8_BAR; PG8_MMA(1, 0, At, B0); PG8_MMA(1, 1, At, B1); PG8_BAR; PG8_SCHED;
;             PG8_LDB(B0, 1, 0); PG8_LDB(B1, 1, 1); PG8_SCHED; PG8_LDA(At, 1, 0); PG8_STAGE(PG8_SA(0, 1), a2 + hstepA, vA0, vA1);
;             PG8_WAIT_V(8); PG8_WAIT_L(0); PG8_BAR; PG8_MMA(0, 0, At, B0); PG8_MMA(0, 1, At, B1); PG8_BAR; PG8_SCHED;
	s_waitcnt lgkmcnt(0)
	v_mfma_f32_16x16x32_bf16 v[60:63], v[132:135], v[164:167], v[60:63]
	v_mfma_f32_16x16x32_bf16 v[56:59], v[140:143], v[164:167], v[56:59]
	v_mfma_f32_16x16x32_bf16 v[48:51], v[140:143], v[172:175], v[48:51]
	v_mfma_f32_16x16x32_bf16 v[52:55], v[132:135], v[172:175], v[52:55]
	v_mfma_f32_16x16x32_bf16 v[44:47], v[132:135], v[180:183], v[44:47]
	v_mfma_f32_16x16x32_bf16 v[40:43], v[140:143], v[180:183], v[40:43]
	v_mfma_f32_16x16x32_bf16 v[32:35], v[140:143], v[188:191], v[32:35]
	v_mfma_f32_16x16x32_bf16 v[36:39], v[132:135], v[188:191], v[36:39]
	v_mfma_f32_16x16x32_bf16 v[60:63], v[136:139], v[168:171], v[60:63]
	v_mfma_f32_16x16x32_bf16 v[56:59], v[144:147], v[168:171], v[56:59]
	v_mfma_f32_16x16x32_bf16 v[48:51], v[144:147], v[176:179], v[48:51]
	v_mfma_f32_16x16x32_bf16 v[52:55], v[136:139], v[176:179], v[52:55]
	v_mfma_f32_16x16x32_bf16 v[44:47], v[136:139], v[184:187], v[44:47]
	v_mfma_f32_16x16x32_bf16 v[40:43], v[144:147], v[184:187], v[40:43]
	v_mfma_f32_16x16x32_bf16 v[32:35], v[144:147], v[192:195], v[32:35]
	v_mfma_f32_16x16x32_bf16 v[36:39], v[136:139], v[192:195], v[36:39]
	s_setprio 0
	s_setprio 1
	v_mfma_f32_16x16x32_bf16 v[28:31], v[148:151], v[164:167], v[28:31]
	v_mfma_f32_16x16x32_bf16 v[24:27], v[156:159], v[164:167], v[24:27]
	v_mfma_f32_16x16x32_bf16 v[16:19], v[156:159], v[172:175], v[16:19]
	v_mfma_f32_16x16x32_bf16 v[20:23], v[148:151], v[172:175], v[20:23]
	v_mfma_f32_16x16x32_bf16 v[12:15], v[148:151], v[180:183], v[12:15]
	v_mfma_f32_16x16x32_bf16 v[8:11], v[156:159], v[180:183], v[8:11]
	v_mfma_f32_16x16x32_bf16 v[0:3], v[156:159], v[188:191], v[0:3]
	v_mfma_f32_16x16x32_bf16 v[4:7], v[148:151], v[188:191], v[4:7]
	v_mfma_f32_16x16x32_bf16 v[28:31], v[152:155], v[168:171], v[28:31]
	v_mfma_f32_16x16x32_bf16 v[24:27], v[160:163], v[168:171], v[24:27]
	v_mfma_f32_16x16x32_bf16 v[16:19], v[160:163], v[176:179], v[16:19]
	v_mfma_f32_16x16x32_bf16 v[20:23], v[152:155], v[176:179], v[20:23]
	v_mfma_f32_16x16x32_bf16 v[12:15], v[152:155], v[184:187], v[12:15]
	v_mfma_f32_16x16x32_bf16 v[8:11], v[160:163], v[184:187], v[8:11]
	v_mfma_f32_16x16x32_bf16 v[0:3], v[160:163], v[192:195], v[0:3]
	v_mfma_f32_16x16x32_bf16 v[4:7], v[152:155], v[192:195], v[4:7]
	s_barrier
	s_setprio 0
	s_add_i32 s51, 0, 0x18000
	v_add_u32_e32 v96, s51, v238
	s_add_i32 s56, 0, 0x1c000
	ds_read_b128 v[132:135], v96
	ds_read_b128 v[136:139], v96 offset:1024
	ds_read_b128 v[140:143], v96 offset:2048
	ds_read_b128 v[144:147], v96 offset:3072
	v_add_u32_e32 v96, s56, v238
	ds_read_b128 v[148:151], v96
	ds_read_b128 v[152:155], v96 offset:1024
	ds_read_b128 v[156:159], v96 offset:2048
	ds_read_b128 v[160:163], v96 offset:3072
	s_add_u32 s26, s26, 0x170000
	s_addc_u32 s27, s27, 0
	s_mov_b32 m0, s55
	v_lshl_add_u64 v[102:103], s[26:27], 0, v[206:207]
	ds_read_b128 v[164:167], v239 offset:32768
	ds_read_b128 v[168:171], v239 offset:33792
	ds_read_b128 v[172:175], v239 offset:34816
	ds_read_b128 v[176:179], v239 offset:35840
	ds_read_b128 v[180:183], v239 offset:36864
	ds_read_b128 v[184:187], v239 offset:37888
	ds_read_b128 v[188:191], v239 offset:38912
	ds_read_b128 v[192:195], v239 offset:39936
	global_load_lds_dwordx4 v[102:103], off
	v_lshl_add_u64 v[102:103], s[26:27], 0, v[208:209]
	s_mov_b32 m0, s72
	s_nop 0
	global_load_lds_dwordx4 v[102:103], off
	s_waitcnt vmcnt(8)
	s_waitcnt lgkmcnt(0)
	s_setprio 1
	s_barrier
	s_waitcnt lgkmcnt(0)
	v_mfma_f32_16x16x32_bf16 v[128:131], v[132:135], v[164:167], v[128:131]
	v_mfma_f32_16x16x32_bf16 v[124:127], v[140:143], v[164:167], v[124:127]
	v_mfma_f32_16x16x32_bf16 v[116:119], v[140:143], v[172:175], v[116:119]
	v_mfma_f32_16x16x32_bf16 v[120:123], v[132:135], v[172:175], v[120:123]
	v_mfma_f32_16x16x32_bf16 v[112:115], v[132:135], v[180:183], v[112:115]
	v_mfma_f32_16x16x32_bf16 v[108:111], v[140:143], v[180:183], v[108:111]
	v_mfma_f32_16x16x32_bf16 v[98:101], v[140:143], v[188:191], v[98:101]
	v_mfma_f32_16x16x32_bf16 v[102:105], v[132:135], v[188:191], v[104:107]
	v_mfma_f32_16x16x32_bf16 v[128:131], v[136:139], v[168:171], v[128:131]
	v_mfma_f32_16x16x32_bf16 v[124:127], v[144:147], v[168:171], v[124:127]
	v_mfma_f32_16x16x32_bf16 v[116:119], v[144:147], v[176:179], v[116:119]
	v_mfma_f32_16x16x32_bf16 v[120:123], v[136:139], v[176:179], v[120:123]
	v_mfma_f32_16x16x32_bf16 v[112:115], v[136:139], v[184:187], v[112:115]
	v_mfma_f32_16x16x32_bf16 v[108:111], v[144:147], v[184:187], v[108:111]
	v_mfma_f32_16x16x32_bf16 v[100:103], v[144:147], v[192:195], v[98:101]
	v_mfma_f32_16x16x32_bf16 v[104:107], v[136:139], v[192:195], v[102:105]
	s_setprio 0
	s_setprio 1
	v_mfma_f32_16x16x32_bf16 v[92:95], v[148:151], v[164:167], v[92:95]
	v_mfma_f32_16x16x32_bf16 v[88:91], v[156:159], v[164:167], v[88:91]
	v_mfma_f32_16x16x32_bf16 v[80:83], v[156:159], v[172:175], v[80:83]
	v_mfma_f32_16x16x32_bf16 v[84:87], v[148:151], v[172:175], v[84:87]
	v_mfma_f32_16x16x32_bf16 v[76:79], v[148:151], v[180:183], v[76:79]
	v_mfma_f32_16x16x32_bf16 v[72:75], v[156:159], v[180:183], v[72:75]
	v_mfma_f32_16x16x32_bf16 v[64:67], v[156:159], v[188:191], v[64:67]
	v_mfma_f32_16x16x32_bf16 v[68:71], v[148:151], v[188:191], v[68:71]
	v_mfma_f32_16x16x32_bf16 v[92:95], v[152:155], v[168:171], v[92:95]
	v_mfma_f32_16x16x32_bf16 v[88:91], v[160:163], v[168:171], v[88:91]
	v_mfma_f32_16x16x32_bf16 v[80:83], v[160:163], v[176:179], v[80:83]
	v_mfma_f32_16x16x32_bf16 v[84:87], v[152:155], v[176:179], v[84:87]
	v_mfma_f32_16x16x32_bf16 v[76:79], v[152:155], v[184:187], v[76:79]
	v_mfma_f32_16x16x32_bf16 v[72:75], v[160:163], v[184:187], v[72:75]
	v_mfma_f32_16x16x32_bf16 v[64:67], v[160:163], v[192:195], v[64:67]
	v_mfma_f32_16x16x32_bf16 v[68:71], v[152:155], v[192:195], v[68:71]
	s_barrier
; #define PG8_STAGE(bufoff, gbase, V0, V1) do { \
;         __builtin_amdgcn_global_load_lds((const unsigned*)((const char*)(gbase) + (V0)), (LAS unsigned*)(lds + (bufoff) + ldsw), 16, 0, 0); \
;         __builtin_amdgcn_global_load_lds((const unsigned*)((const char*)(gbase) + (V1)), (LAS unsigned*)(lds + (bufoff) + ldsw + 8192), 16, 0, 0); } while (0)
; #define PG8_LDA(dst, b, h) do { _Pragma("unroll") for (int m = 0; m < 4; ++m) _Pragma("unroll") for (int k = 0; k < 2; ++k) dst[m][k] = *(const LAS bf16x8*)(lds + PG8_SA(b, h) + aoff + m * 2048 + k * 1024); } while (0)
; #define PG8_MMA(ai, bj, At, Bt) do { __builtin_amdgcn_s_setprio(1); _Pragma("unroll") for (int m = 0; m < 4; ++m) _Pragma("unroll") for (int n = 0; n < 2; ++n) _Pragma("unroll") for (int k = 0; k < 2; ++k) \
;         acc[ai][bj][m][n] = __builtin_amdgcn_mfma_f32_16x16x32_bf16(Bt[n][k], At[m][k], acc[ai][bj][m][n], 0, 0, 0); __builtin_amdgcn_s_setprio(0); } while (0)
; #define PG8_WAIT_V(n) asm volatile("s_waitcnt vmcnt(" #n ")" ::: "memory")
; #define PG8_WAIT_L(n) asm volatile("s_waitcnt lgkmcnt(" #n ")" ::: "memory")
; #define PG8_BAR __builtin_amdgcn_s_barrier()
; #define PG8_SCHED __builtin_amdgcn_sched_barrier(0)
; template <class Epi, class Sched>
; DI void gemm_phase(LAS unsigned char* lds, const int lda2, const int ldb2, const int nt, const Sched& S, const Epi& E) {
;     ...
;             PG8_LDA(At, 1, 1); PG8_STAGE(PG8_SB(1, 0), b3, vB0, vB1); PG8_STAGE(PG8_SB(1, 1), b3 + hstepB, vB0, vB1); PG8_STAGE(PG8_SA(1, 0), a3, vA0, vA1);
;             PG8_WAIT_V(8); PG8_WAIT_L(0); PG8_BAR; PG8_MMA(1, 0, At, B0); PG8_MMA(1, 1, At, B1); PG8_BAR; PG8_SCHED;
;         }
;         if (wr == 0) PG8_BAR;
	s_setprio 0
	s_add_i32 s26, s51, s47
	v_lshl_add_u64 v[98:99], v[214:215], 0, s[86:87]
	s_mov_b32 m0, s26
	ds_read_b128 v[164:167], v239 offset:49152
	ds_read_b128 v[168:171], v239 offset:50176
	ds_read_b128 v[172:175], v239 offset:51200
	ds_read_b128 v[176:179], v239 offset:52224
	ds_read_b128 v[180:183], v239 offset:53248
	ds_read_b128 v[184:187], v239 offset:54272
	ds_read_b128 v[188:191], v239 offset:55296
	ds_read_b128 v[192:195], v239 offset:56320
	global_load_lds_dwordx4 v[98:99], off
	s_add_i32 m0, s26, 0x2000
	s_add_u32 s24, s24, 0x60080
	v_lshl_add_u64 v[98:99], v[216:217], 0, s[86:87]
	s_addc_u32 s25, s25, 0
	s_add_i32 s26, s56, s47
	global_load_lds_dwordx4 v[98:99], off
	v_lshl_add_u64 v[98:99], s[24:25], 0, v[202:203]
	s_mov_b32 m0, s26
	s_nop 0
	global_load_lds_dwordx4 v[98:99], off
	v_lshl_add_u64 v[98:99], s[24:25], 0, v[204:205]
	s_add_i32 m0, s26, 0x2000
	s_nop 0
	global_load_lds_dwordx4 v[98:99], off
	v_lshl_add_u64 v[98:99], v[218:219], 0, s[86:87]
	s_mov_b32 m0, s75
	s_nop 0
	global_load_lds_dwordx4 v[98:99], off
	v_lshl_add_u64 v[98:99], v[220:221], 0, s[86:87]
	s_mov_b32 m0, s76
	s_nop 0
	global_load_lds_dwordx4 v[98:99], off
	s_waitcnt vmcnt(8)
	s_waitcnt lgkmcnt(0)
	s_setprio 1
	s_barrier
	s_waitcnt lgkmcnt(0)
	v_mfma_f32_16x16x32_bf16 v[60:63], v[132:135], v[164:167], v[60:63]
	v_mfma_f32_16x16x32_bf16 v[56:59], v[140:143], v[164:167], v[56:59]
	v_mfma_f32_16x16x32_bf16 v[48:51], v[140:143], v[172:175], v[48:51]
	v_mfma_f32_16x16x32_bf16 v[52:55], v[132:135], v[172:175], v[52:55]
	v_mfma_f32_16x16x32_bf16 v[44:47], v[132:135], v[180:183], v[44:47]
	v_mfma_f32_16x16x32_bf16 v[40:43], v[140:143], v[180:183], v[40:43]
	v_mfma_f32_16x16x32_bf16 v[32:35], v[140:143], v[188:191], v[32:35]
	v_mfma_f32_16x16x32_bf16 v[36:39], v[132:135], v[188:191], v[36:39]
	v_mfma_f32_16x16x32_bf16 v[60:63], v[136:139], v[168:171], v[60:63]
	v_mfma_f32_16x16x32_bf16 v[56:59], v[144:147], v[168:171], v[56:59]
	v_mfma_f32_16x16x32_bf16 v[48:51], v[144:147], v[176:179], v[48:51]
	v_mfma_f32_16x16x32_bf16 v[52:55], v[136:139], v[176:179], v[52:55]
	v_mfma_f32_16x16x32_bf16 v[44:47], v[136:139], v[184:187], v[44:47]
	v_mfma_f32_16x16x32_bf16 v[40:43], v[144:147], v[184:187], v[40:43]
	v_mfma_f32_16x16x32_bf16 v[32:35], v[144:147], v[192:195], v[32:35]
	v_mfma_f32_16x16x32_bf16 v[36:39], v[136:139], v[192:195], v[36:39]
	s_setprio 0
	s_setprio 1
	v_mfma_f32_16x16x32_bf16 v[28:31], v[148:151], v[164:167], v[28:31]
	v_mfma_f32_16x16x32_bf16 v[24:27], v[156:159], v[164:167], v[24:27]
	v_mfma_f32_16x16x32_bf16 v[16:19], v[156:159], v[172:175], v[16:19]
	v_mfma_f32_16x16x32_bf16 v[20:23], v[148:151], v[172:175], v[20:23]
	v_mfma_f32_16x16x32_bf16 v[12:15], v[148:151], v[180:183], v[12:15]
	v_mfma_f32_16x16x32_bf16 v[8:11], v[156:159], v[180:183], v[8:11]
	v_mfma_f32_16x16x32_bf16 v[0:3], v[156:159], v[188:191], v[0:3]
	v_mfma_f32_16x16x32_bf16 v[4:7], v[148:151], v[188:191], v[4:7]
	v_mfma_f32_16x16x32_bf16 v[28:31], v[152:155], v[168:171], v[28:31]
	v_mfma_f32_16x16x32_bf16 v[24:27], v[160:163], v[168:171], v[24:27]
	v_mfma_f32_16x16x32_bf16 v[16:19], v[160:163], v[176:179], v[16:19]
	v_mfma_f32_16x16x32_bf16 v[20:23], v[152:155], v[176:179], v[20:23]
	v_mfma_f32_16x16x32_bf16 v[12:15], v[152:155], v[184:187], v[12:15]
	v_mfma_f32_16x16x32_bf16 v[8:11], v[160:163], v[184:187], v[8:11]
	v_mfma_f32_16x16x32_bf16 v[0:3], v[160:163], v[192:195], v[0:3]
	v_mfma_f32_16x16x32_bf16 v[4:7], v[152:155], v[192:195], v[4:7]
	s_barrier
	s_setprio 0
	s_add_i32 s50, s50, 2
	s_add_u32 s6, s6, 0x100
	s_addc_u32 s7, s7, 0
	s_add_u32 s5, s5, 0x100
	s_addc_u32 s49, s49, 0
	s_cmp_gt_u32 s50, 5
	s_cbranch_scc0 .LBB0_680
	s_and_b64 vcc, exec, s[18:19]
	s_cbranch_vccz .LBB0_683
	s_barrier

; #define PG8_STAGE(bufoff, gbase, V0, V1) do { \
;         __builtin_amdgcn_global_load_lds((const unsigned*)((const char*)(gbase) + (V0)), (LAS unsigned*)(lds + (bufoff) + ldsw), 16, 0, 0); \
;         __builtin_amdgcn_global_load_lds((const unsigned*)((const char*)(gbase) + (V1)), (LAS unsigned*)(lds + (bufoff) + ldsw + 8192), 16, 0, 0); } while (0)
; #define PG8_LDA(dst, b, h) do { _Pragma("unroll") for (int m = 0; m < 4; ++m) _Pragma("unroll") for (int k = 0; k < 2; ++k) dst[m][k] = *(const LAS bf16x8*)(lds + PG8_SA(b, h) + aoff + m * 2048 + k * 1024); } while (0)
; #define PG8_LDB(dst, b, h) do { _Pragma("unroll") for (int n = 0; n < 2; ++n) _Pragma("unroll") for (int k = 0; k < 2; ++k) dst[n][k] = *(const LAS bf16x8*)(lds + PG8_SB(b, h) + boff + n * 2048 + k * 1024); } while (0)
; #define PG8_MMA(ai, bj, At, Bt) do { __builtin_amdgcn_s_setprio(1); _Pragma("unroll") for (int m = 0; m < 4; ++m) _Pragma("unroll") for (int n = 0; n < 2; ++n) _Pragma("unroll") for (int k = 0; k < 2; ++k) \
;         acc[ai][bj][m][n] = __builtin_amdgcn_mfma_f32_16x16x32_bf16(Bt[n][k], At[m][k], acc[ai][bj][m][n], 0, 0, 0); __builtin_amdgcn_s_setprio(0); } while (0)
; template <class Epi, class Sched>
; DI void gemm_phase(LAS unsigned char* lds, const int lda2, const int ldb2, const int nt, const Sched& S, const Epi& E) {
;     ...
;     for (;;) {
;         const bool has_next = S.next(ui + 1, nxt);
;         const char* nA = has_next ? nxt.A : cA; const char* nB = has_next ? nxt.B : cB;
;         for (int t = 0; t < nt; t += 2) {
;             const bool last = (t == nt - 2);
;             const char* a1 = cA + (size_t)(t + 1) * kstep;
;             const char* a2 = last ? nA : cA + (size_t)(t + 2) * kstep; const char* b2 = last ? nB : cB + (size_t)(t + 2) * kstep;
;             const char* a3 = a2 + kstep; const char* b3 = b2 + kstep;
;             PG8_LDB(B0, 0, 0); PG8_LDB(B1, 0, 1); PG8_SCHED; PG8_LDA(At, 0, 0); PG8_STAGE(PG8_SA(1, 1), a1 + hstepA, vA0, vA1);
;             PG8_WAIT_V(8); PG8_WAIT_L(0); PG8_BAR; PG8_MMA(0, 0, At, B0); PG8_MMA(0, 1, At, B1); PG8_BAR; PG8_SCHED;
;             PG8_LDA(At, 0, 1); PG8_STAGE(PG8_SB(0, 0), b2, vB0, vB1); PG8_STAGE(PG8_SB(0, 1), b2 + hstepB, vB0, vB1); PG8_STAGE(PG8_SA(0, 0), a2, vA0, vA1);
;             PG8_WAIT_V(8); PG8_WAIT_L(0); PG8_BAR; PG8_MMA(1, 0, At, B0); PG8_MMA(1, 1, At, B1); PG8_BAR; PG8_SCHED;
.LBB0_905:
	s_add_u32 s26, s26, 0x170080
	s_addc_u32 s27, s27, 0
	s_add_u32 s1, s28, 0x100
	s_addc_u32 s10, s29, 0
	s_mov_b32 s21, -2
	s_waitcnt lgkmcnt(0)
	s_add_u32 s28, s26, 0xffe90080
	s_addc_u32 s29, s27, -1
	s_add_i32 s56, 0, 0x10000
	s_cmp_eq_u32 s21, 12
	s_cselect_b32 s31, s23, s29
	s_cselect_b32 s30, s22, s28
	v_add_u32_e32 v144, s56, v148
	s_cselect_b32 s29, s25, s10
	s_cselect_b32 s28, s24, s1
	s_add_i32 vcc_lo, 0, 0x14000
	ds_read_b128 v[140:143], v144
	ds_read_b128 v[150:153], v144 offset:1024
	ds_read_b128 v[154:157], v144 offset:2048
	ds_read_b128 v[158:161], v144 offset:3072
	v_add_u32_e32 v144, vcc_lo, v148
	ds_read_b128 v[162:165], v144
	ds_read_b128 v[166:169], v144 offset:1024
	ds_read_b128 v[170:173], v144 offset:2048
	ds_read_b128 v[174:177], v144 offset:3072
	v_lshl_add_u64 v[144:145], s[26:27], 0, v[136:137]
	s_add_i32 m0, s74, 0xc000
	ds_read_b128 v[178:181], v149
	ds_read_b128 v[182:185], v149 offset:1024
	ds_read_b128 v[186:189], v149 offset:2048
	ds_read_b128 v[190:193], v149 offset:3072
	ds_read_b128 v[202:205], v149 offset:4096
	ds_read_b128 v[206:209], v149 offset:5120
	ds_read_b128 v[210:213], v149 offset:6144
	ds_read_b128 v[214:217], v149 offset:7168
	global_load_lds_dwordx4 v[144:145], off
	v_lshl_add_u64 v[144:145], s[26:27], 0, v[138:139]
	s_add_i32 m0, s74, 0xe000
	s_nop 0
	global_load_lds_dwordx4 v[144:145], off
	s_waitcnt vmcnt(8)
	s_waitcnt lgkmcnt(0)
	s_setprio 1
	s_barrier
	s_waitcnt lgkmcnt(0)
	v_mfma_f32_16x16x32_bf16 v[126:129], v[140:143], v[178:181], 0
	v_mfma_f32_16x16x32_bf16 v[122:125], v[154:157], v[178:181], 0
	v_mfma_f32_16x16x32_bf16 v[106:109], v[154:157], v[186:189], 0
	v_mfma_f32_16x16x32_bf16 v[110:113], v[140:143], v[186:189], 0
	v_mfma_f32_16x16x32_bf16 v[92:95], v[140:143], v[202:205], 0
	v_mfma_f32_16x16x32_bf16 v[88:91], v[154:157], v[202:205], 0
	v_mfma_f32_16x16x32_bf16 v[72:75], v[154:157], v[210:213], 0
	v_mfma_f32_16x16x32_bf16 v[76:79], v[140:143], v[210:213], 0
	v_mfma_f32_16x16x32_bf16 v[126:129], v[150:153], v[182:185], v[126:129]
	v_mfma_f32_16x16x32_bf16 v[122:125], v[158:161], v[182:185], v[122:125]
	v_mfma_f32_16x16x32_bf16 v[106:109], v[158:161], v[190:193], v[106:109]
	v_mfma_f32_16x16x32_bf16 v[110:113], v[150:153], v[190:193], v[110:113]
	v_mfma_f32_16x16x32_bf16 v[92:95], v[150:153], v[206:209], v[92:95]
	v_mfma_f32_16x16x32_bf16 v[88:91], v[158:161], v[206:209], v[88:91]
	v_mfma_f32_16x16x32_bf16 v[72:75], v[158:161], v[214:217], v[72:75]
	v_mfma_f32_16x16x32_bf16 v[76:79], v[150:153], v[214:217], v[76:79]
	s_setprio 0
	s_setprio 1
	v_mfma_f32_16x16x32_bf16 v[118:121], v[162:165], v[178:181], 0
	v_mfma_f32_16x16x32_bf16 v[114:117], v[170:173], v[178:181], 0
	v_mfma_f32_16x16x32_bf16 v[98:101], v[170:173], v[186:189], 0
	v_mfma_f32_16x16x32_bf16 v[102:105], v[162:165], v[186:189], 0
	v_mfma_f32_16x16x32_bf16 v[84:87], v[162:165], v[202:205], 0
	v_mfma_f32_16x16x32_bf16 v[80:83], v[170:173], v[202:205], 0
	v_mfma_f32_16x16x32_bf16 v[64:67], v[170:173], v[210:213], 0
	v_mfma_f32_16x16x32_bf16 v[68:71], v[162:165], v[210:213], 0
	v_mfma_f32_16x16x32_bf16 v[118:121], v[166:169], v[182:185], v[118:121]
	v_mfma_f32_16x16x32_bf16 v[114:117], v[174:177], v[182:185], v[114:117]
	v_mfma_f32_16x16x32_bf16 v[98:101], v[174:177], v[190:193], v[98:101]
	v_mfma_f32_16x16x32_bf16 v[102:105], v[166:169], v[190:193], v[102:105]
	v_mfma_f32_16x16x32_bf16 v[84:87], v[166:169], v[206:209], v[84:87]
	v_mfma_f32_16x16x32_bf16 v[80:83], v[174:177], v[206:209], v[80:83]
	v_mfma_f32_16x16x32_bf16 v[64:67], v[174:177], v[214:217], v[64:67]
	v_mfma_f32_16x16x32_bf16 v[68:71], v[166:169], v[214:217], v[68:71]
	s_barrier
	s_setprio 0
	s_add_i32 s56, s56, s73
	v_lshl_add_u64 v[144:145], s[28:29], 0, v[96:97]
	s_mov_b32 m0, s56
	ds_read_b128 v[178:181], v149 offset:16384
	ds_read_b128 v[182:185], v149 offset:17408
	ds_read_b128 v[186:189], v149 offset:18432
	ds_read_b128 v[190:193], v149 offset:19456
	ds_read_b128 v[202:205], v149 offset:20480
	ds_read_b128 v[206:209], v149 offset:21504
	ds_read_b128 v[210:213], v149 offset:22528
	ds_read_b128 v[214:217], v149 offset:23552
	global_load_lds_dwordx4 v[144:145], off
	s_add_i32 m0, s56, 0x2000
	s_add_u32 s56, s28, 0x40000
	v_lshl_add_u64 v[194:195], s[28:29], 0, v[130:131]
	s_addc_u32 s57, s29, 0
	s_add_i32 vcc_lo, vcc_lo, s73
	global_load_lds_dwordx4 v[194:195], off
	v_lshl_add_u64 v[218:219], s[56:57], 0, v[96:97]
	s_mov_b32 m0, vcc_lo
	v_lshl_add_u64 v[220:221], s[30:31], 0, v[134:135]
	global_load_lds_dwordx4 v[218:219], off
	v_lshl_add_u64 v[218:219], s[56:57], 0, v[130:131]
	s_add_i32 m0, vcc_lo, 0x2000
	s_nop 0
	global_load_lds_dwordx4 v[218:219], off
	v_lshl_add_u64 v[218:219], s[30:31], 0, v[132:133]
	s_mov_b32 m0, s74
	s_nop 0
	global_load_lds_dwordx4 v[218:219], off
	s_mov_b32 m0, s75
	s_nop 0
	global_load_lds_dwordx4 v[220:221], off
	s_waitcnt vmcnt(8)
	s_waitcnt lgkmcnt(0)
	s_setprio 1
	s_barrier
; #define PG8_STAGE(bufoff, gbase, V0, V1) do { \
;         __builtin_amdgcn_global_load_lds((const unsigned*)((const char*)(gbase) + (V0)), (LAS unsigned*)(lds + (bufoff) + ldsw), 16, 0, 0); \
;         __builtin_amdgcn_global_load_lds((const unsigned*)((const char*)(gbase) + (V1)), (LAS unsigned*)(lds + (bufoff) + ldsw + 8192), 16, 0, 0); } while (0)
; #define PG8_LDA(dst, b, h) do { _Pragma("unroll") for (int m = 0; m < 4; ++m) _Pragma("unroll") for (int k = 0; k < 2; ++k) dst[m][k] = *(const LAS bf16x8*)(lds + PG8_SA(b, h) + aoff + m * 2048 + k * 1024); } while (0)
; #define PG8_LDB(dst, b, h) do { _Pragma("unroll") for (int n = 0; n < 2; ++n) _Pragma("unroll") for (int k = 0; k < 2; ++k) dst[n][k] = *(const LAS bf16x8*)(lds + PG8_SB(b, h) + boff + n * 2048 + k * 1024); } while (0)
; #define PG8_MMA(ai, bj, At, Bt) do { __builtin_amdgcn_s_setprio(1); _Pragma("unroll") for (int m = 0; m < 4; ++m) _Pragma("unroll") for (int n = 0; n < 2; ++n) _Pragma("unroll") for (int k = 0; k < 2; ++k) \
;         acc[ai][bj][m][n] = __builtin_amdgcn_mfma_f32_16x16x32_bf16(Bt[n][k], At[m][k], acc[ai][bj][m][n], 0, 0, 0); __builtin_amdgcn_s_setprio(0); } while (0)
; template <class Epi, class Sched>
; DI void gemm_phase(LAS unsigned char* lds, const int lda2, const int ldb2, const int nt, const Sched& S, const Epi& E) {
;     ...
;             PG8_LDB(B0, 0, 0); PG8_LDB(B1, 0, 1); PG8_SCHED; PG8_LDA(At, 0, 0); PG8_STAGE(PG8_SA(1, 1), a1 + hstepA, vA0, vA1);
;             PG8_WAIT_V(8); PG8_WAIT_L(0); PG8_BAR; PG8_MMA(0, 0, At, B0); PG8_MMA(0, 1, At, B1); PG8_BAR; PG8_SCHED;
;             PG8_LDA(At, 0, 1); PG8_STAGE(PG8_SB(0, 0), b2, vB0, vB1); PG8_STAGE(PG8_SB(0, 1), b2 + hstepB, vB0, vB1); PG8_STAGE(PG8_SA(0, 0), a2, vA0, vA1);
;             PG8_WAIT_V(8); PG8_WAIT_L(0); PG8_BAR; PG8_MMA(1, 0, At, B0); PG8_MMA(1, 1, At, B1); PG8_BAR; PG8_SCHED;
;             PG8_LDB(B0, 1, 0); PG8_LDB(B1, 1, 1); PG8_SCHED; PG8_LDA(At, 1, 0); PG8_STAGE(PG8_SA(0, 1), a2 + hstepA, vA0, vA1);
;             PG8_WAIT_V(8); PG8_WAIT_L(0); PG8_BAR; PG8_MMA(0, 0, At, B0); PG8_MMA(0, 1, At, B1); PG8_BAR; PG8_SCHED;
;             PG8_LDA(At, 1, 1); PG8_STAGE(PG8_SB(1, 0), b3, vB0, vB1); PG8_STAGE(PG8_SB(1, 1), b3 + hstepB, vB0, vB1); PG8_STAGE(PG8_SA(1, 0), a3, vA0, vA1);
;             PG8_WAIT_V(8); PG8_WAIT_L(0); PG8_BAR; PG8_MMA(1, 0, At, B0); PG8_MMA(1, 1, At, B1); PG8_BAR; PG8_SCHED;
	s_waitcnt lgkmcnt(0)
	v_mfma_f32_16x16x32_bf16 v[60:63], v[140:143], v[178:181], 0
	v_mfma_f32_16x16x32_bf16 v[56:59], v[154:157], v[178:181], 0
	v_mfma_f32_16x16x32_bf16 v[40:43], v[154:157], v[186:189], 0
	v_mfma_f32_16x16x32_bf16 v[44:47], v[140:143], v[186:189], 0
	v_mfma_f32_16x16x32_bf16 v[28:31], v[140:143], v[202:205], 0
	v_mfma_f32_16x16x32_bf16 v[24:27], v[154:157], v[202:205], 0
	v_mfma_f32_16x16x32_bf16 v[8:11], v[154:157], v[210:213], 0
	v_mfma_f32_16x16x32_bf16 v[12:15], v[140:143], v[210:213], 0
	v_mfma_f32_16x16x32_bf16 v[60:63], v[150:153], v[182:185], v[60:63]
	v_mfma_f32_16x16x32_bf16 v[56:59], v[158:161], v[182:185], v[56:59]
	v_mfma_f32_16x16x32_bf16 v[40:43], v[158:161], v[190:193], v[40:43]
	v_mfma_f32_16x16x32_bf16 v[44:47], v[150:153], v[190:193], v[44:47]
	v_mfma_f32_16x16x32_bf16 v[28:31], v[150:153], v[206:209], v[28:31]
	v_mfma_f32_16x16x32_bf16 v[24:27], v[158:161], v[206:209], v[24:27]
	v_mfma_f32_16x16x32_bf16 v[8:11], v[158:161], v[214:217], v[8:11]
	v_mfma_f32_16x16x32_bf16 v[12:15], v[150:153], v[214:217], v[12:15]
	s_setprio 0
	s_setprio 1
	v_mfma_f32_16x16x32_bf16 v[52:55], v[162:165], v[178:181], 0
	v_mfma_f32_16x16x32_bf16 v[48:51], v[170:173], v[178:181], 0
	v_mfma_f32_16x16x32_bf16 v[32:35], v[170:173], v[186:189], 0
	v_mfma_f32_16x16x32_bf16 v[36:39], v[162:165], v[186:189], 0
	v_mfma_f32_16x16x32_bf16 v[20:23], v[162:165], v[202:205], 0
	v_mfma_f32_16x16x32_bf16 v[16:19], v[170:173], v[202:205], 0
	v_mfma_f32_16x16x32_bf16 v[0:3], v[170:173], v[210:213], 0
	v_mfma_f32_16x16x32_bf16 v[4:7], v[162:165], v[210:213], 0
	v_mfma_f32_16x16x32_bf16 v[52:55], v[166:169], v[182:185], v[52:55]
	v_mfma_f32_16x16x32_bf16 v[48:51], v[174:177], v[182:185], v[48:51]
	v_mfma_f32_16x16x32_bf16 v[32:35], v[174:177], v[190:193], v[32:35]
	v_mfma_f32_16x16x32_bf16 v[36:39], v[166:169], v[190:193], v[36:39]
	v_mfma_f32_16x16x32_bf16 v[20:23], v[166:169], v[206:209], v[20:23]
	v_mfma_f32_16x16x32_bf16 v[16:19], v[174:177], v[206:209], v[16:19]
	v_mfma_f32_16x16x32_bf16 v[0:3], v[174:177], v[214:217], v[0:3]
	v_mfma_f32_16x16x32_bf16 v[4:7], v[166:169], v[214:217], v[4:7]
	s_barrier
	s_setprio 0
	s_add_i32 s56, 0, 0x18000
	s_add_i32 s57, 0, 0x1c000
	v_add_u32_e32 v158, s56, v148
	v_add_u32_e32 v174, s57, v148
	ds_read_b128 v[140:143], v158
	ds_read_b128 v[150:153], v158 offset:1024
	ds_read_b128 v[154:157], v158 offset:2048
	ds_read_b128 v[158:161], v158 offset:3072
	ds_read_b128 v[162:165], v174
	ds_read_b128 v[166:169], v174 offset:1024
	ds_read_b128 v[170:173], v174 offset:2048
	ds_read_b128 v[174:177], v174 offset:3072
	s_add_u32 s30, s30, 0x170000
	s_addc_u32 s31, s31, 0
	s_mov_b32 m0, s76
	v_lshl_add_u64 v[222:223], s[30:31], 0, v[132:133]
	ds_read_b128 v[178:181], v149 offset:32768
	ds_read_b128 v[182:185], v149 offset:33792
	ds_read_b128 v[186:189], v149 offset:34816
	ds_read_b128 v[190:193], v149 offset:35840
	ds_read_b128 v[202:205], v149 offset:36864
	ds_read_b128 v[206:209], v149 offset:37888
	ds_read_b128 v[210:213], v149 offset:38912
	ds_read_b128 v[214:217], v149 offset:39936
	global_load_lds_dwordx4 v[222:223], off
	v_lshl_add_u64 v[222:223], s[30:31], 0, v[134:135]
	s_mov_b32 m0, s77
	s_nop 0
	global_load_lds_dwordx4 v[222:223], off
	s_waitcnt vmcnt(8)
	s_waitcnt lgkmcnt(0)
	s_setprio 1
	s_barrier
	s_waitcnt lgkmcnt(0)
	v_mfma_f32_16x16x32_bf16 v[126:129], v[140:143], v[178:181], v[126:129]
	v_mfma_f32_16x16x32_bf16 v[122:125], v[154:157], v[178:181], v[122:125]
	v_mfma_f32_16x16x32_bf16 v[106:109], v[154:157], v[186:189], v[106:109]
	v_mfma_f32_16x16x32_bf16 v[110:113], v[140:143], v[186:189], v[110:113]
	v_mfma_f32_16x16x32_bf16 v[92:95], v[140:143], v[202:205], v[92:95]
	v_mfma_f32_16x16x32_bf16 v[88:91], v[154:157], v[202:205], v[88:91]
	v_mfma_f32_16x16x32_bf16 v[72:75], v[154:157], v[210:213], v[72:75]
	v_mfma_f32_16x16x32_bf16 v[76:79], v[140:143], v[210:213], v[76:79]
	v_mfma_f32_16x16x32_bf16 v[126:129], v[150:153], v[182:185], v[126:129]
	v_mfma_f32_16x16x32_bf16 v[122:125], v[158:161], v[182:185], v[122:125]
	v_mfma_f32_16x16x32_bf16 v[106:109], v[158:161], v[190:193], v[106:109]
	v_mfma_f32_16x16x32_bf16 v[110:113], v[150:153], v[190:193], v[110:113]
	v_mfma_f32_16x16x32_bf16 v[92:95], v[150:153], v[206:209], v[92:95]
	v_mfma_f32_16x16x32_bf16 v[88:91], v[158:161], v[206:209], v[88:91]
	v_mfma_f32_16x16x32_bf16 v[72:75], v[158:161], v[214:217], v[72:75]
	v_mfma_f32_16x16x32_bf16 v[76:79], v[150:153], v[214:217], v[76:79]
	s_setprio 0
	s_setprio 1
	v_mfma_f32_16x16x32_bf16 v[118:121], v[162:165], v[178:181], v[118:121]
	v_mfma_f32_16x16x32_bf16 v[114:117], v[170:173], v[178:181], v[114:117]
	v_mfma_f32_16x16x32_bf16 v[98:101], v[170:173], v[186:189], v[98:101]
	v_mfma_f32_16x16x32_bf16 v[102:105], v[162:165], v[186:189], v[102:105]
	v_mfma_f32_16x16x32_bf16 v[84:87], v[162:165], v[202:205], v[84:87]
	v_mfma_f32_16x16x32_bf16 v[80:83], v[170:173], v[202:205], v[80:83]
	v_mfma_f32_16x16x32_bf16 v[64:67], v[170:173], v[210:213], v[64:67]
	v_mfma_f32_16x16x32_bf16 v[68:71], v[162:165], v[210:213], v[68:71]
	v_mfma_f32_16x16x32_bf16 v[118:121], v[166:169], v[182:185], v[118:121]
	v_mfma_f32_16x16x32_bf16 v[114:117], v[174:177], v[182:185], v[114:117]
	v_mfma_f32_16x16x32_bf16 v[98:101], v[174:177], v[190:193], v[98:101]
	v_mfma_f32_16x16x32_bf16 v[102:105], v[166:169], v[190:193], v[102:105]
	v_mfma_f32_16x16x32_bf16 v[84:87], v[166:169], v[206:209], v[84:87]
	v_mfma_f32_16x16x32_bf16 v[80:83], v[174:177], v[206:209], v[80:83]
	v_mfma_f32_16x16x32_bf16 v[64:67], v[174:177], v[214:217], v[64:67]
	v_mfma_f32_16x16x32_bf16 v[68:71], v[166:169], v[214:217], v[68:71]
	s_barrier
; #define PG8_STAGE(bufoff, gbase, V0, V1) do { \
;         __builtin_amdgcn_global_load_lds((const unsigned*)((const char*)(gbase) + (V0)), (LAS unsigned*)(lds + (bufoff) + ldsw), 16, 0, 0); \
;         __builtin_amdgcn_global_load_lds((const unsigned*)((const char*)(gbase) + (V1)), (LAS unsigned*)(lds + (bufoff) + ldsw + 8192), 16, 0, 0); } while (0)
; #define PG8_LDA(dst, b, h) do { _Pragma("unroll") for (int m = 0; m < 4; ++m) _Pragma("unroll") for (int k = 0; k < 2; ++k) dst[m][k] = *(const LAS bf16x8*)(lds + PG8_SA(b, h) + aoff + m * 2048 + k * 1024); } while (0)
; #define PG8_LDB(dst, b, h) do { _Pragma("unroll") for (int n = 0; n < 2; ++n) _Pragma("unroll") for (int k = 0; k < 2; ++k) dst[n][k] = *(const LAS bf16x8*)(lds + PG8_SB(b, h) + boff + n * 2048 + k * 1024); } while (0)
; template <class Epi, class Sched>
; DI void gemm_phase(LAS unsigned char* lds, const int lda2, const int ldb2, const int nt, const Sched& S, const Epi& E) {
;     ...
;         for (int t = 0; t < nt; t += 2) {
;             const bool last = (t == nt - 2);
;             const char* a1 = cA + (size_t)(t + 1) * kstep;
;             const char* a2 = last ? nA : cA + (size_t)(t + 2) * kstep; const char* b2 = last ? nB : cB + (size_t)(t + 2) * kstep;
;             const char* a3 = a2 + kstep; const char* b3 = b2 + kstep;
;             PG8_LDB(B0, 0, 0); PG8_LDB(B1, 0, 1); PG8_SCHED; PG8_LDA(At, 0, 0); PG8_STAGE(PG8_SA(1, 1), a1 + hstepA, vA0, vA1);
;             PG8_WAIT_V(8); PG8_WAIT_L(0); PG8_BAR; PG8_MMA(0, 0, At, B0); PG8_MMA(0, 1, At, B1); PG8_BAR; PG8_SCHED;
;             PG8_LDA(At, 0, 1); PG8_STAGE(PG8_SB(0, 0), b2, vB0, vB1); PG8_STAGE(PG8_SB(0, 1), b2 + hstepB, vB0, vB1); PG8_STAGE(PG8_SA(0, 0), a2, vA0, vA1);
;             PG8_WAIT_V(8); PG8_WAIT_L(0); PG8_BAR; PG8_MMA(1, 0, At, B0); PG8_MMA(1, 1, At, B1); PG8_BAR; PG8_SCHED;
;             PG8_LDB(B0, 1, 0); PG8_LDB(B1, 1, 1); PG8_SCHED; PG8_LDA(At, 1, 0); PG8_STAGE(PG8_SA(0, 1), a2 + hstepA, vA0, vA1);
;             PG8_WAIT_V(8); PG8_WAIT_L(0); PG8_BAR; PG8_MMA(0, 0, At, B0); PG8_MMA(0, 1, At, B1); PG8_BAR; PG8_SCHED;
;             PG8_LDA(At, 1, 1); PG8_STAGE(PG8_SB(1, 0), b3, vB0, vB1); PG8_STAGE(PG8_SB(1, 1), b3 + hstepB, vB0, vB1); PG8_STAGE(PG8_SA(1, 0), a3, vA0, vA1);
;             PG8_WAIT_V(8); PG8_WAIT_L(0); PG8_BAR; PG8_MMA(1, 0, At, B0); PG8_MMA(1, 1, At, B1); PG8_BAR; PG8_SCHED;
	s_setprio 0
	s_add_i32 s30, s56, s73
	v_lshl_add_u64 v[144:145], v[144:145], 0, s[86:87]
	s_mov_b32 m0, s30
	ds_read_b128 v[178:181], v149 offset:49152
	ds_read_b128 v[182:185], v149 offset:50176
	ds_read_b128 v[186:189], v149 offset:51200
	ds_read_b128 v[190:193], v149 offset:52224
	ds_read_b128 v[202:205], v149 offset:53248
	ds_read_b128 v[206:209], v149 offset:54272
	ds_read_b128 v[210:213], v149 offset:55296
	ds_read_b128 v[214:217], v149 offset:56320
	global_load_lds_dwordx4 v[144:145], off
	s_add_i32 m0, s30, 0x2000
	s_add_u32 s28, s28, 0x40080
	v_lshl_add_u64 v[144:145], v[194:195], 0, s[86:87]
	s_addc_u32 s29, s29, 0
	s_add_i32 s30, s57, s73
	global_load_lds_dwordx4 v[144:145], off
	v_lshl_add_u64 v[144:145], s[28:29], 0, v[96:97]
	s_mov_b32 m0, s30
	s_nop 0
	global_load_lds_dwordx4 v[144:145], off
	v_lshl_add_u64 v[144:145], s[28:29], 0, v[130:131]
	s_add_i32 m0, s30, 0x2000
	s_nop 0
	global_load_lds_dwordx4 v[144:145], off
	v_lshl_add_u64 v[144:145], v[218:219], 0, s[86:87]
	s_mov_b32 m0, s81
	s_nop 0
	global_load_lds_dwordx4 v[144:145], off
	v_lshl_add_u64 v[144:145], v[220:221], 0, s[86:87]
	s_mov_b32 m0, s82
	s_nop 0
	global_load_lds_dwordx4 v[144:145], off
	s_waitcnt vmcnt(8)
	s_waitcnt lgkmcnt(0)
	s_setprio 1
	s_barrier
	s_waitcnt lgkmcnt(0)
	v_mfma_f32_16x16x32_bf16 v[60:63], v[140:143], v[178:181], v[60:63]
	v_mfma_f32_16x16x32_bf16 v[56:59], v[154:157], v[178:181], v[56:59]
	v_mfma_f32_16x16x32_bf16 v[40:43], v[154:157], v[186:189], v[40:43]
	v_mfma_f32_16x16x32_bf16 v[44:47], v[140:143], v[186:189], v[44:47]
	v_mfma_f32_16x16x32_bf16 v[28:31], v[140:143], v[202:205], v[28:31]
	v_mfma_f32_16x16x32_bf16 v[24:27], v[154:157], v[202:205], v[24:27]
	v_mfma_f32_16x16x32_bf16 v[8:11], v[154:157], v[210:213], v[8:11]
	v_mfma_f32_16x16x32_bf16 v[12:15], v[140:143], v[210:213], v[12:15]
	v_mfma_f32_16x16x32_bf16 v[60:63], v[150:153], v[182:185], v[60:63]
	v_mfma_f32_16x16x32_bf16 v[56:59], v[158:161], v[182:185], v[56:59]
	v_mfma_f32_16x16x32_bf16 v[40:43], v[158:161], v[190:193], v[40:43]
	v_mfma_f32_16x16x32_bf16 v[44:47], v[150:153], v[190:193], v[44:47]
	v_mfma_f32_16x16x32_bf16 v[28:31], v[150:153], v[206:209], v[28:31]
	v_mfma_f32_16x16x32_bf16 v[24:27], v[158:161], v[206:209], v[24:27]
	v_mfma_f32_16x16x32_bf16 v[8:11], v[158:161], v[214:217], v[8:11]
	v_mfma_f32_16x16x32_bf16 v[12:15], v[150:153], v[214:217], v[12:15]
	s_setprio 0
	s_setprio 1
	v_mfma_f32_16x16x32_bf16 v[52:55], v[162:165], v[178:181], v[52:55]
	v_mfma_f32_16x16x32_bf16 v[48:51], v[170:173], v[178:181], v[48:51]
	v_mfma_f32_16x16x32_bf16 v[32:35], v[170:173], v[186:189], v[32:35]
	v_mfma_f32_16x16x32_bf16 v[36:39], v[162:165], v[186:189], v[36:39]
	v_mfma_f32_16x16x32_bf16 v[20:23], v[162:165], v[202:205], v[20:23]
	v_mfma_f32_16x16x32_bf16 v[16:19], v[170:173], v[202:205], v[16:19]
	v_mfma_f32_16x16x32_bf16 v[0:3], v[170:173], v[210:213], v[0:3]
	v_mfma_f32_16x16x32_bf16 v[4:7], v[162:165], v[210:213], v[4:7]
	v_mfma_f32_16x16x32_bf16 v[52:55], v[166:169], v[182:185], v[52:55]
	v_mfma_f32_16x16x32_bf16 v[48:51], v[174:177], v[182:185], v[48:51]
	v_mfma_f32_16x16x32_bf16 v[32:35], v[174:177], v[190:193], v[32:35]
	v_mfma_f32_16x16x32_bf16 v[36:39], v[166:169], v[190:193], v[36:39]
	v_mfma_f32_16x16x32_bf16 v[20:23], v[166:169], v[206:209], v[20:23]
	v_mfma_f32_16x16x32_bf16 v[16:19], v[174:177], v[206:209], v[16:19]
	v_mfma_f32_16x16x32_bf16 v[0:3], v[174:177], v[214:217], v[0:3]
	v_mfma_f32_16x16x32_bf16 v[4:7], v[166:169], v[214:217], v[4:7]
	s_barrier
	s_setprio 0
	s_add_i32 s21, s21, 2
	s_add_u32 s26, s26, 0x100
	s_addc_u32 s27, s27, 0
	s_add_u32 s1, s1, 0x100
	s_addc_u32 s10, s10, 0
.LBB0_906:
	s_add_u32 s28, s26, 0xffe90080
	s_addc_u32 s29, s27, -1
	s_add_i32 s56, 0, 0x10000
	s_cmp_eq_u32 s21, 12
	s_cselect_b32 s31, s23, s29
	s_cselect_b32 s30, s22, s28
	v_add_u32_e32 v144, s56, v148
	s_cselect_b32 s29, s25, s10
	s_cselect_b32 s28, s24, s1
	s_add_i32 vcc_lo, 0, 0x14000
	ds_read_b128 v[140:143], v144
	ds_read_b128 v[150:153], v144 offset:1024
	ds_read_b128 v[154:157], v144 offset:2048
	ds_read_b128 v[158:161], v144 offset:3072
	v_add_u32_e32 v144, vcc_lo, v148
	ds_read_b128 v[162:165], v144
	ds_read_b128 v[166:169], v144 offset:1024
	ds_read_b128 v[170:173], v144 offset:2048
	ds_read_b128 v[174:177], v144 offset:3072
	v_lshl_add_u64 v[144:145], s[26:27], 0, v[136:137]
	s_add_i32 m0, s74, 0xc000
	ds_read_b128 v[178:181], v149
	ds_read_b128 v[182:185], v149 offset:1024
	ds_read_b128 v[186:189], v149 offset:2048
	ds_read_b128 v[190:193], v149 offset:3072
	ds_read_b128 v[202:205], v149 offset:4096
	ds_read_b128 v[206:209], v149 offset:5120
	ds_read_b128 v[210:213], v149 offset:6144
	ds_read_b128 v[214:217], v149 offset:7168
	global_load_lds_dwordx4 v[144:145], off
	v_lshl_add_u64 v[144:145], s[26:27], 0, v[138:139]
	s_add_i32 m0, s74, 0xe000
	s_nop 0
	global_load_lds_dwordx4 v[144:145], off
	s_waitcnt vmcnt(8)
	s_waitcnt lgkmcnt(0)
	s_setprio 1
	s_barrier
; #define PG8_STAGE(bufoff, gbase, V0, V1) do { \
;         __builtin_amdgcn_global_load_lds((const unsigned*)((const char*)(gbase) + (V0)), (LAS unsigned*)(lds + (bufoff) + ldsw), 16, 0, 0); \
;         __builtin_amdgcn_global_load_lds((const unsigned*)((const char*)(gbase) + (V1)), (LAS unsigned*)(lds + (bufoff) + ldsw + 8192), 16, 0, 0); } while (0)
; #define PG8_LDA(dst, b, h) do { _Pragma("unroll") for (int m = 0; m < 4; ++m) _Pragma("unroll") for (int k = 0; k < 2; ++k) dst[m][k] = *(const LAS bf16x8*)(lds + PG8_SA(b, h) + aoff + m * 2048 + k * 1024); } while (0)
; #define PG8_LDB(dst, b, h) do { _Pragma("unroll") for (int n = 0; n < 2; ++n) _Pragma("unroll") for (int k = 0; k < 2; ++k) dst[n][k] = *(const LAS bf16x8*)(lds + PG8_SB(b, h) + boff + n * 2048 + k * 1024); } while (0)
; #define PG8_MMA(ai, bj, At, Bt) do { __builtin_amdgcn_s_setprio(1); _Pragma("unroll") for (int m = 0; m < 4; ++m) _Pragma("unroll") for (int n = 0; n < 2; ++n) _Pragma("unroll") for (int k = 0; k < 2; ++k) \
;         acc[ai][bj][m][n] = __builtin_amdgcn_mfma_f32_16x16x32_bf16(Bt[n][k], At[m][k], acc[ai][bj][m][n], 0, 0, 0); __builtin_amdgcn_s_setprio(0); } while (0)
; template <class Epi, class Sched>
; DI void gemm_phase(LAS unsigned char* lds, const int lda2, const int ldb2, const int nt, const Sched& S, const Epi& E) {
;     ...
;             PG8_LDB(B0, 0, 0); PG8_LDB(B1, 0, 1); PG8_SCHED; PG8_LDA(At, 0, 0); PG8_STAGE(PG8_SA(1, 1), a1 + hstepA, vA0, vA1);
;             PG8_WAIT_V(8); PG8_WAIT_L(0); PG8_BAR; PG8_MMA(0, 0, At, B0); PG8_MMA(0, 1, At, B1); PG8_BAR; PG8_SCHED;
;             PG8_LDA(At, 0, 1); PG8_STAGE(PG8_SB(0, 0), b2, vB0, vB1); PG8_STAGE(PG8_SB(0, 1), b2 + hstepB, vB0, vB1); PG8_STAGE(PG8_SA(0, 0), a2, vA0, vA1);
;             PG8_WAIT_V(8); PG8_WAIT_L(0); PG8_BAR; PG8_MMA(1, 0, At, B0); PG8_MMA(1, 1, At, B1); PG8_BAR; PG8_SCHED;
;             PG8_LDB(B0, 1, 0); PG8_LDB(B1, 1, 1); PG8_SCHED; PG8_LDA(At, 1, 0); PG8_STAGE(PG8_SA(0, 1), a2 + hstepA, vA0, vA1);
;             PG8_WAIT_V(8); PG8_WAIT_L(0); PG8_BAR; PG8_MMA(0, 0, At, B0); PG8_MMA(0, 1, At, B1); PG8_BAR; PG8_SCHED;
;             PG8_LDA(At, 1, 1); PG8_STAGE(PG8_SB(1, 0), b3, vB0, vB1); PG8_STAGE(PG8_SB(1, 1), b3 + hstepB, vB0, vB1); PG8_STAGE(PG8_SA(1, 0), a3, vA0, vA1);
;             PG8_WAIT_V(8); PG8_WAIT_L(0); PG8_BAR; PG8_MMA(1, 0, At, B0); PG8_MMA(1, 1, At, B1); PG8_BAR; PG8_SCHED;
	s_waitcnt lgkmcnt(0)
	v_mfma_f32_16x16x32_bf16 v[126:129], v[140:143], v[178:181], v[126:129]
	v_mfma_f32_16x16x32_bf16 v[122:125], v[154:157], v[178:181], v[122:125]
	v_mfma_f32_16x16x32_bf16 v[106:109], v[154:157], v[186:189], v[106:109]
	v_mfma_f32_16x16x32_bf16 v[110:113], v[140:143], v[186:189], v[110:113]
	v_mfma_f32_16x16x32_bf16 v[92:95], v[140:143], v[202:205], v[92:95]
	v_mfma_f32_16x16x32_bf16 v[88:91], v[154:157], v[202:205], v[88:91]
	v_mfma_f32_16x16x32_bf16 v[72:75], v[154:157], v[210:213], v[72:75]
	v_mfma_f32_16x16x32_bf16 v[76:79], v[140:143], v[210:213], v[76:79]
	v_mfma_f32_16x16x32_bf16 v[126:129], v[150:153], v[182:185], v[126:129]
	v_mfma_f32_16x16x32_bf16 v[122:125], v[158:161], v[182:185], v[122:125]
	v_mfma_f32_16x16x32_bf16 v[106:109], v[158:161], v[190:193], v[106:109]
	v_mfma_f32_16x16x32_bf16 v[110:113], v[150:153], v[190:193], v[110:113]
	v_mfma_f32_16x16x32_bf16 v[92:95], v[150:153], v[206:209], v[92:95]
	v_mfma_f32_16x16x32_bf16 v[88:91], v[158:161], v[206:209], v[88:91]
	v_mfma_f32_16x16x32_bf16 v[72:75], v[158:161], v[214:217], v[72:75]
	v_mfma_f32_16x16x32_bf16 v[76:79], v[150:153], v[214:217], v[76:79]
	s_setprio 0
	s_setprio 1
	v_mfma_f32_16x16x32_bf16 v[118:121], v[162:165], v[178:181], v[118:121]
	v_mfma_f32_16x16x32_bf16 v[114:117], v[170:173], v[178:181], v[114:117]
	v_mfma_f32_16x16x32_bf16 v[98:101], v[170:173], v[186:189], v[98:101]
	v_mfma_f32_16x16x32_bf16 v[102:105], v[162:165], v[186:189], v[102:105]
	v_mfma_f32_16x16x32_bf16 v[84:87], v[162:165], v[202:205], v[84:87]
	v_mfma_f32_16x16x32_bf16 v[80:83], v[170:173], v[202:205], v[80:83]
	v_mfma_f32_16x16x32_bf16 v[64:67], v[170:173], v[210:213], v[64:67]
	v_mfma_f32_16x16x32_bf16 v[68:71], v[162:165], v[210:213], v[68:71]
	v_mfma_f32_16x16x32_bf16 v[118:121], v[166:169], v[182:185], v[118:121]
	v_mfma_f32_16x16x32_bf16 v[114:117], v[174:177], v[182:185], v[114:117]
	v_mfma_f32_16x16x32_bf16 v[98:101], v[174:177], v[190:193], v[98:101]
	v_mfma_f32_16x16x32_bf16 v[102:105], v[166:169], v[190:193], v[102:105]
	v_mfma_f32_16x16x32_bf16 v[84:87], v[166:169], v[206:209], v[84:87]
	v_mfma_f32_16x16x32_bf16 v[80:83], v[174:177], v[206:209], v[80:83]
	v_mfma_f32_16x16x32_bf16 v[64:67], v[174:177], v[214:217], v[64:67]
	v_mfma_f32_16x16x32_bf16 v[68:71], v[166:169], v[214:217], v[68:71]
	s_barrier
	s_setprio 0
	s_add_i32 s56, s56, s73
	v_lshl_add_u64 v[144:145], s[28:29], 0, v[96:97]
	s_mov_b32 m0, s56
	ds_read_b128 v[178:181], v149 offset:16384
	ds_read_b128 v[182:185], v149 offset:17408
	ds_read_b128 v[186:189], v149 offset:18432
	ds_read_b128 v[190:193], v149 offset:19456
	ds_read_b128 v[202:205], v149 offset:20480
	ds_read_b128 v[206:209], v149 offset:21504
	ds_read_b128 v[210:213], v149 offset:22528
	ds_read_b128 v[214:217], v149 offset:23552
	global_load_lds_dwordx4 v[144:145], off
	s_add_i32 m0, s56, 0x2000
	s_add_u32 s56, s28, 0x40000
	v_lshl_add_u64 v[194:195], s[28:29], 0, v[130:131]
	s_addc_u32 s57, s29, 0
	s_add_i32 vcc_lo, vcc_lo, s73
	global_load_lds_dwordx4 v[194:195], off
	v_lshl_add_u64 v[218:219], s[56:57], 0, v[96:97]
	s_mov_b32 m0, vcc_lo
	v_lshl_add_u64 v[220:221], s[30:31], 0, v[134:135]
	global_load_lds_dwordx4 v[218:219], off
	v_lshl_add_u64 v[218:219], s[56:57], 0, v[130:131]
	s_add_i32 m0, vcc_lo, 0x2000
	s_nop 0
	global_load_lds_dwordx4 v[218:219], off
	v_lshl_add_u64 v[218:219], s[30:31], 0, v[132:133]
	s_mov_b32 m0, s74
	s_nop 0
	global_load_lds_dwordx4 v[218:219], off
	s_mov_b32 m0, s75
	s_nop 0
	global_load_lds_dwordx4 v[220:221], off
	s_waitcnt vmcnt(8)
	s_waitcnt lgkmcnt(0)
	s_setprio 1
	s_barrier
	s_waitcnt lgkmcnt(0)
	v_mfma_f32_16x16x32_bf16 v[60:63], v[140:143], v[178:181], v[60:63]
	v_mfma_f32_16x16x32_bf16 v[56:59], v[154:157], v[178:181], v[56:59]
	v_mfma_f32_16x16x32_bf16 v[40:43], v[154:157], v[186:189], v[40:43]
	v_mfma_f32_16x16x32_bf16 v[44:47], v[140:143], v[186:189], v[44:47]
	v_mfma_f32_16x16x32_bf16 v[28:31], v[140:143], v[202:205], v[28:31]
	v_mfma_f32_16x16x32_bf16 v[24:27], v[154:157], v[202:205], v[24:27]
	v_mfma_f32_16x16x32_bf16 v[8:11], v[154:157], v[210:213], v[8:11]
	v_mfma_f32_16x16x32_bf16 v[12:15], v[140:143], v[210:213], v[12:15]
	v_mfma_f32_16x16x32_bf16 v[60:63], v[150:153], v[182:185], v[60:63]
	v_mfma_f32_16x16x32_bf16 v[56:59], v[158:161], v[182:185], v[56:59]
	v_mfma_f32_16x16x32_bf16 v[40:43], v[158:161], v[190:193], v[40:43]
	v_mfma_f32_16x16x32_bf16 v[44:47], v[150:153], v[190:193], v[44:47]
	v_mfma_f32_16x16x32_bf16 v[28:31], v[150:153], v[206:209], v[28:31]
	v_mfma_f32_16x16x32_bf16 v[24:27], v[158:161], v[206:209], v[24:27]
	v_mfma_f32_16x16x32_bf16 v[8:11], v[158:161], v[214:217], v[8:11]
	v_mfma_f32_16x16x32_bf16 v[12:15], v[150:153], v[214:217], v[12:15]
	s_setprio 0
	s_setprio 1
	v_mfma_f32_16x16x32_bf16 v[52:55], v[162:165], v[178:181], v[52:55]
	v_mfma_f32_16x16x32_bf16 v[48:51], v[170:173], v[178:181], v[48:51]
	v_mfma_f32_16x16x32_bf16 v[32:35], v[170:173], v[186:189], v[32:35]
	v_mfma_f32_16x16x32_bf16 v[36:39], v[162:165], v[186:189], v[36:39]
	v_mfma_f32_16x16x32_bf16 v[20:23], v[162:165], v[202:205], v[20:23]
	v_mfma_f32_16x16x32_bf16 v[16:19], v[170:173], v[202:205], v[16:19]
	v_mfma_f32_16x16x32_bf16 v[0:3], v[170:173], v[210:213], v[0:3]
	v_mfma_f32_16x16x32_bf16 v[4:7], v[162:165], v[210:213], v[4:7]
	v_mfma_f32_16x16x32_bf16 v[52:55], v[166:169], v[182:185], v[52:55]
	v_mfma_f32_16x16x32_bf16 v[48:51], v[174:177], v[182:185], v[48:51]
	v_mfma_f32_16x16x32_bf16 v[32:35], v[174:177], v[190:193], v[32:35]
	v_mfma_f32_16x16x32_bf16 v[36:39], v[166:169], v[190:193], v[36:39]
	v_mfma_f32_16x16x32_bf16 v[20:23], v[166:169], v[206:209], v[20:23]
	v_mfma_f32_16x16x32_bf16 v[16:19], v[174:177], v[206:209], v[16:19]
	v_mfma_f32_16x16x32_bf16 v[0:3], v[174:177], v[214:217], v[0:3]
	v_mfma_f32_16x16x32_bf16 v[4:7], v[166:169], v[214:217], v[4:7]
	s_barrier
; #define PG8_STAGE(bufoff, gbase, V0, V1) do { \
;         __builtin_amdgcn_global_load_lds((const unsigned*)((const char*)(gbase) + (V0)), (LAS unsigned*)(lds + (bufoff) + ldsw), 16, 0, 0); \
;         __builtin_amdgcn_global_load_lds((const unsigned*)((const char*)(gbase) + (V1)), (LAS unsigned*)(lds + (bufoff) + ldsw + 8192), 16, 0, 0); } while (0)
; #define PG8_LDA(dst, b, h) do { _Pragma("unroll") for (int m = 0; m < 4; ++m) _Pragma("unroll") for (int k = 0; k < 2; ++k) dst[m][k] = *(const LAS bf16x8*)(lds + PG8_SA(b, h) + aoff + m * 2048 + k * 1024); } while (0)
; #define PG8_MMA(ai, bj, At, Bt) do { __builtin_amdgcn_s_setprio(1); _Pragma("unroll") for (int m = 0; m < 4; ++m) _Pragma("unroll") for (int n = 0; n < 2; ++n) _Pragma("unroll") for (int k = 0; k < 2; ++k) \
;         acc[ai][bj][m][n] = __builtin_amdgcn_mfma_f32_16x16x32_bf16(Bt[n][k], At[m][k], acc[ai][bj][m][n], 0, 0, 0); __builtin_amdgcn_s_setprio(0); } while (0)
; #define PG8_WAIT_V(n) asm volatile("s_waitcnt vmcnt(" #n ")" ::: "memory")
; #define PG8_WAIT_L(n) asm volatile("s_waitcnt lgkmcnt(" #n ")" ::: "memory")
; #define PG8_BAR __builtin_amdgcn_s_barrier()
; #define PG8_SCHED __builtin_amdgcn_sched_barrier(0)
; template <class Epi, class Sched>
; DI void gemm_phase(LAS unsigned char* lds, const int lda2, const int ldb2, const int nt, const Sched& S, const Epi& E) {
;     ...
;             PG8_LDA(At, 1, 1); PG8_STAGE(PG8_SB(1, 0), b3, vB0, vB1); PG8_STAGE(PG8_SB(1, 1), b3 + hstepB, vB0, vB1); PG8_STAGE(PG8_SA(1, 0), a3, vA0, vA1);
;             PG8_WAIT_V(8); PG8_WAIT_L(0); PG8_BAR; PG8_MMA(1, 0, At, B0); PG8_MMA(1, 1, At, B1); PG8_BAR; PG8_SCHED;
	s_setprio 0
	s_add_i32 s56, 0, 0x18000
	s_add_i32 s57, 0, 0x1c000
	v_add_u32_e32 v158, s56, v148
	v_add_u32_e32 v174, s57, v148
	ds_read_b128 v[140:143], v158
	ds_read_b128 v[150:153], v158 offset:1024
	ds_read_b128 v[154:157], v158 offset:2048
	ds_read_b128 v[158:161], v158 offset:3072
	ds_read_b128 v[162:165], v174
	ds_read_b128 v[166:169], v174 offset:1024
	ds_read_b128 v[170:173], v174 offset:2048
	ds_read_b128 v[174:177], v174 offset:3072
	s_add_u32 s30, s30, 0x170000
	s_addc_u32 s31, s31, 0
	s_mov_b32 m0, s76
	v_lshl_add_u64 v[222:223], s[30:31], 0, v[132:133]
	ds_read_b128 v[178:181], v149 offset:32768
	ds_read_b128 v[182:185], v149 offset:33792
	ds_read_b128 v[186:189], v149 offset:34816
	ds_read_b128 v[190:193], v149 offset:35840
	ds_read_b128 v[202:205], v149 offset:36864
	ds_read_b128 v[206:209], v149 offset:37888
	ds_read_b128 v[210:213], v149 offset:38912
	ds_read_b128 v[214:217], v149 offset:39936
	global_load_lds_dwordx4 v[222:223], off
	v_lshl_add_u64 v[222:223], s[30:31], 0, v[134:135]
	s_mov_b32 m0, s77
	s_nop 0
	global_load_lds_dwordx4 v[222:223], off
	s_waitcnt vmcnt(8)
	s_waitcnt lgkmcnt(0)
	s_setprio 1
	s_barrier
	s_waitcnt lgkmcnt(0)
	v_mfma_f32_16x16x32_bf16 v[126:129], v[140:143], v[178:181], v[126:129]
	v_mfma_f32_16x16x32_bf16 v[122:125], v[154:157], v[178:181], v[122:125]
	v_mfma_f32_16x16x32_bf16 v[106:109], v[154:157], v[186:189], v[106:109]
	v_mfma_f32_16x16x32_bf16 v[110:113], v[140:143], v[186:189], v[110:113]
	v_mfma_f32_16x16x32_bf16 v[92:95], v[140:143], v[202:205], v[92:95]
	v_mfma_f32_16x16x32_bf16 v[88:91], v[154:157], v[202:205], v[88:91]
	v_mfma_f32_16x16x32_bf16 v[72:75], v[154:157], v[210:213], v[72:75]
	v_mfma_f32_16x16x32_bf16 v[76:79], v[140:143], v[210:213], v[76:79]
	v_mfma_f32_16x16x32_bf16 v[126:129], v[150:153], v[182:185], v[126:129]
	v_mfma_f32_16x16x32_bf16 v[122:125], v[158:161], v[182:185], v[122:125]
	v_mfma_f32_16x16x32_bf16 v[106:109], v[158:161], v[190:193], v[106:109]
	v_mfma_f32_16x16x32_bf16 v[110:113], v[150:153], v[190:193], v[110:113]
	v_mfma_f32_16x16x32_bf16 v[92:95], v[150:153], v[206:209], v[92:95]
	v_mfma_f32_16x16x32_bf16 v[88:91], v[158:161], v[206:209], v[88:91]
	v_mfma_f32_16x16x32_bf16 v[72:75], v[158:161], v[214:217], v[72:75]
	v_mfma_f32_16x16x32_bf16 v[76:79], v[150:153], v[214:217], v[76:79]
	s_setprio 0
	s_setprio 1
	v_mfma_f32_16x16x32_bf16 v[118:121], v[162:165], v[178:181], v[118:121]
	v_mfma_f32_16x16x32_bf16 v[114:117], v[170:173], v[178:181], v[114:117]
	v_mfma_f32_16x16x32_bf16 v[98:101], v[170:173], v[186:189], v[98:101]
	v_mfma_f32_16x16x32_bf16 v[102:105], v[162:165], v[186:189], v[102:105]
	v_mfma_f32_16x16x32_bf16 v[84:87], v[162:165], v[202:205], v[84:87]
	v_mfma_f32_16x16x32_bf16 v[80:83], v[170:173], v[202:205], v[80:83]
	v_mfma_f32_16x16x32_bf16 v[64:67], v[170:173], v[210:213], v[64:67]
	v_mfma_f32_16x16x32_bf16 v[68:71], v[162:165], v[210:213], v[68:71]
	v_mfma_f32_16x16x32_bf16 v[118:121], v[166:169], v[182:185], v[118:121]
	v_mfma_f32_16x16x32_bf16 v[114:117], v[174:177], v[182:185], v[114:117]
	v_mfma_f32_16x16x32_bf16 v[98:101], v[174:177], v[190:193], v[98:101]
	v_mfma_f32_16x16x32_bf16 v[102:105], v[166:169], v[190:193], v[102:105]
	v_mfma_f32_16x16x32_bf16 v[84:87], v[166:169], v[206:209], v[84:87]
	v_mfma_f32_16x16x32_bf16 v[80:83], v[174:177], v[206:209], v[80:83]
	v_mfma_f32_16x16x32_bf16 v[64:67], v[174:177], v[214:217], v[64:67]
	v_mfma_f32_16x16x32_bf16 v[68:71], v[166:169], v[214:217], v[68:71]
	s_barrier
; #define PG8_STAGE(bufoff, gbase, V0, V1) do { \
;         __builtin_amdgcn_global_load_lds((const unsigned*)((const char*)(gbase) + (V0)), (LAS unsigned*)(lds + (bufoff) + ldsw), 16, 0, 0); \
;         __builtin_amdgcn_global_load_lds((const unsigned*)((const char*)(gbase) + (V1)), (LAS unsigned*)(lds + (bufoff) + ldsw + 8192), 16, 0, 0); } while (0)
; #define PG8_LDA(dst, b, h) do { _Pragma("unroll") for (int m = 0; m < 4; ++m) _Pragma("unroll") for (int k = 0; k < 2; ++k) dst[m][k] = *(const LAS bf16x8*)(lds + PG8_SA(b, h) + aoff + m * 2048 + k * 1024); } while (0)
; #define PG8_MMA(ai, bj, At, Bt) do { __builtin_amdgcn_s_setprio(1); _Pragma("unroll") for (int m = 0; m < 4; ++m) _Pragma("unroll") for (int n = 0; n < 2; ++n) _Pragma("unroll") for (int k = 0; k < 2; ++k) \
;         acc[ai][bj][m][n] = __builtin_amdgcn_mfma_f32_16x16x32_bf16(Bt[n][k], At[m][k], acc[ai][bj][m][n], 0, 0, 0); __builtin_amdgcn_s_setprio(0); } while (0)
; #define PG8_WAIT_V(n) asm volatile("s_waitcnt vmcnt(" #n ")" ::: "memory")
; #define PG8_WAIT_L(n) asm volatile("s_waitcnt lgkmcnt(" #n ")" ::: "memory")
; #define PG8_BAR __builtin_amdgcn_s_barrier()
; #define PG8_SCHED __builtin_amdgcn_sched_barrier(0)
; template <class Epi, class Sched>
; DI void gemm_phase(LAS unsigned char* lds, const int lda2, const int ldb2, const int nt, const Sched& S, const Epi& E) {
;     ...
;             PG8_LDA(At, 1, 1); PG8_STAGE(PG8_SB(1, 0), b3, vB0, vB1); PG8_STAGE(PG8_SB(1, 1), b3 + hstepB, vB0, vB1); PG8_STAGE(PG8_SA(1, 0), a3, vA0, vA1);
;             PG8_WAIT_V(8); PG8_WAIT_L(0); PG8_BAR; PG8_MMA(1, 0, At, B0); PG8_MMA(1, 1, At, B1); PG8_BAR; PG8_SCHED;
;         }
;         if (wr == 0) PG8_BAR;
	s_setprio 0
	s_add_i32 s30, s56, s73
	v_lshl_add_u64 v[144:145], v[144:145], 0, s[86:87]
	s_mov_b32 m0, s30
	ds_read_b128 v[178:181], v149 offset:49152
	ds_read_b128 v[182:185], v149 offset:50176
	ds_read_b128 v[186:189], v149 offset:51200
	ds_read_b128 v[190:193], v149 offset:52224
	ds_read_b128 v[202:205], v149 offset:53248
	ds_read_b128 v[206:209], v149 offset:54272
	ds_read_b128 v[210:213], v149 offset:55296
	ds_read_b128 v[214:217], v149 offset:56320
	global_load_lds_dwordx4 v[144:145], off
	s_add_i32 m0, s30, 0x2000
	s_add_u32 s28, s28, 0x40080
	v_lshl_add_u64 v[144:145], v[194:195], 0, s[86:87]
	s_addc_u32 s29, s29, 0
	s_add_i32 s30, s57, s73
	global_load_lds_dwordx4 v[144:145], off
	v_lshl_add_u64 v[144:145], s[28:29], 0, v[96:97]
	s_mov_b32 m0, s30
	s_nop 0
	global_load_lds_dwordx4 v[144:145], off
	v_lshl_add_u64 v[144:145], s[28:29], 0, v[130:131]
	s_add_i32 m0, s30, 0x2000
	s_nop 0
	global_load_lds_dwordx4 v[144:145], off
	v_lshl_add_u64 v[144:145], v[218:219], 0, s[86:87]
	s_mov_b32 m0, s81
	s_nop 0
	global_load_lds_dwordx4 v[144:145], off
	v_lshl_add_u64 v[144:145], v[220:221], 0, s[86:87]
	s_mov_b32 m0, s82
	s_nop 0
	global_load_lds_dwordx4 v[144:145], off
	s_waitcnt vmcnt(8)
	s_waitcnt lgkmcnt(0)
	s_setprio 1
	s_barrier
	s_waitcnt lgkmcnt(0)
	v_mfma_f32_16x16x32_bf16 v[60:63], v[140:143], v[178:181], v[60:63]
	v_mfma_f32_16x16x32_bf16 v[56:59], v[154:157], v[178:181], v[56:59]
	v_mfma_f32_16x16x32_bf16 v[40:43], v[154:157], v[186:189], v[40:43]
	v_mfma_f32_16x16x32_bf16 v[44:47], v[140:143], v[186:189], v[44:47]
	v_mfma_f32_16x16x32_bf16 v[28:31], v[140:143], v[202:205], v[28:31]
	v_mfma_f32_16x16x32_bf16 v[24:27], v[154:157], v[202:205], v[24:27]
	v_mfma_f32_16x16x32_bf16 v[8:11], v[154:157], v[210:213], v[8:11]
	v_mfma_f32_16x16x32_bf16 v[12:15], v[140:143], v[210:213], v[12:15]
	v_mfma_f32_16x16x32_bf16 v[60:63], v[150:153], v[182:185], v[60:63]
	v_mfma_f32_16x16x32_bf16 v[56:59], v[158:161], v[182:185], v[56:59]
	v_mfma_f32_16x16x32_bf16 v[40:43], v[158:161], v[190:193], v[40:43]
	v_mfma_f32_16x16x32_bf16 v[44:47], v[150:153], v[190:193], v[44:47]
	v_mfma_f32_16x16x32_bf16 v[28:31], v[150:153], v[206:209], v[28:31]
	v_mfma_f32_16x16x32_bf16 v[24:27], v[158:161], v[206:209], v[24:27]
	v_mfma_f32_16x16x32_bf16 v[8:11], v[158:161], v[214:217], v[8:11]
	v_mfma_f32_16x16x32_bf16 v[12:15], v[150:153], v[214:217], v[12:15]
	s_setprio 0
	s_setprio 1
	v_mfma_f32_16x16x32_bf16 v[52:55], v[162:165], v[178:181], v[52:55]
	v_mfma_f32_16x16x32_bf16 v[48:51], v[170:173], v[178:181], v[48:51]
	v_mfma_f32_16x16x32_bf16 v[32:35], v[170:173], v[186:189], v[32:35]
	v_mfma_f32_16x16x32_bf16 v[36:39], v[162:165], v[186:189], v[36:39]
	v_mfma_f32_16x16x32_bf16 v[20:23], v[162:165], v[202:205], v[20:23]
	v_mfma_f32_16x16x32_bf16 v[16:19], v[170:173], v[202:205], v[16:19]
	v_mfma_f32_16x16x32_bf16 v[0:3], v[170:173], v[210:213], v[0:3]
	v_mfma_f32_16x16x32_bf16 v[4:7], v[162:165], v[210:213], v[4:7]
	v_mfma_f32_16x16x32_bf16 v[52:55], v[166:169], v[182:185], v[52:55]
	v_mfma_f32_16x16x32_bf16 v[48:51], v[174:177], v[182:185], v[48:51]
	v_mfma_f32_16x16x32_bf16 v[32:35], v[174:177], v[190:193], v[32:35]
	v_mfma_f32_16x16x32_bf16 v[36:39], v[166:169], v[190:193], v[36:39]
	v_mfma_f32_16x16x32_bf16 v[20:23], v[166:169], v[206:209], v[20:23]
	v_mfma_f32_16x16x32_bf16 v[16:19], v[174:177], v[206:209], v[16:19]
	v_mfma_f32_16x16x32_bf16 v[0:3], v[174:177], v[214:217], v[0:3]
	v_mfma_f32_16x16x32_bf16 v[4:7], v[166:169], v[214:217], v[4:7]
	s_barrier
	s_setprio 0
	s_add_i32 s21, s21, 2
	s_add_u32 s26, s26, 0x100
	s_addc_u32 s27, s27, 0
	s_add_u32 s1, s1, 0x100
	s_addc_u32 s10, s10, 0
	s_cmp_gt_u32 s21, 13
	s_cbranch_scc0 .LBB0_906
	s_and_b64 vcc, exec, s[18:19]
	s_cbranch_vccz .LBB0_909
	s_barrier

; #define PG8_STAGE(bufoff, gbase, V0, V1) do { \
;         __builtin_amdgcn_global_load_lds((const unsigned*)((const char*)(gbase) + (V0)), (LAS unsigned*)(lds + (bufoff) + ldsw), 16, 0, 0); \
;         __builtin_amdgcn_global_load_lds((const unsigned*)((const char*)(gbase) + (V1)), (LAS unsigned*)(lds + (bufoff) + ldsw + 8192), 16, 0, 0); } while (0)
; #define PG8_LDA(dst, b, h) do { _Pragma("unroll") for (int m = 0; m < 4; ++m) _Pragma("unroll") for (int k = 0; k < 2; ++k) dst[m][k] = *(const LAS bf16x8*)(lds + PG8_SA(b, h) + aoff + m * 2048 + k * 1024); } while (0)
; #define PG8_WAIT_V(n) asm volatile("s_waitcnt vmcnt(" #n ")" ::: "memory")
; template <class Epi, class Sched>
; DI void gemm_phase(LAS unsigned char* lds, const int lda2, const int ldb2, const int nt, const Sched& S, const Epi& E) {
;     ...
;     for (;;) {
;         const bool has_next = S.next(ui + 1, nxt);
;         const char* nA = has_next ? nxt.A : cA; const char* nB = has_next ? nxt.B : cB;
;         for (int t = 0; t < nt; t += 2) {
;             const bool last = (t == nt - 2);
;             const char* a1 = cA + (size_t)(t + 1) * kstep;
;             const char* a2 = last ? nA : cA + (size_t)(t + 2) * kstep; const char* b2 = last ? nB : cB + (size_t)(t + 2) * kstep;
;             const char* a3 = a2 + kstep; const char* b3 = b2 + kstep;
;             PG8_LDB(B0, 0, 0); PG8_LDB(B1, 0, 1); PG8_SCHED; PG8_LDA(At, 0, 0); PG8_STAGE(PG8_SA(1, 1), a1 + hstepA, vA0, vA1);
;             PG8_WAIT_V(8); PG8_WAIT_L(0); PG8_BAR; PG8_MMA(0, 0, At, B0); PG8_MMA(0, 1, At, B1); PG8_BAR; PG8_SCHED;
;             PG8_LDA(At, 0, 1); PG8_STAGE(PG8_SB(0, 0), b2, vB0, vB1); PG8_STAGE(PG8_SB(0, 1), b2 + hstepB, vB0, vB1); PG8_STAGE(PG8_SA(0, 0), a2, vA0, vA1);
;             PG8_WAIT_V(8); PG8_WAIT_L(0); PG8_BAR; PG8_MMA(1, 0, At, B0); PG8_MMA(1, 1, At, B1); PG8_BAR; PG8_SCHED;
;             PG8_LDB(B0, 1, 0); PG8_LDB(B1, 1, 1); PG8_SCHED; PG8_LDA(At, 1, 0); PG8_STAGE(PG8_SA(0, 1), a2 + hstepA, vA0, vA1);
;             PG8_WAIT_V(8); PG8_WAIT_L(0); PG8_BAR; PG8_MMA(0, 0, At, B0); PG8_MMA(0, 1, At, B1); PG8_BAR; PG8_SCHED;
;             PG8_LDA(At, 1, 1); PG8_STAGE(PG8_SB(1, 0), b3, vB0, vB1); PG8_STAGE(PG8_SB(1, 1), b3 + hstepB, vB0, vB1); PG8_STAGE(PG8_SA(1, 0), a3, vA0, vA1);
;             PG8_WAIT_V(8); PG8_WAIT_L(0); PG8_BAR; PG8_MMA(1, 0, At, B0); PG8_MMA(1, 1, At, B1); PG8_BAR; PG8_SCHED;
.LBB0_1052:
	s_add_u32 s28, s28, 0x40080
	s_addc_u32 s29, s29, 0
	s_add_u32 s19, s30, 0x100
	s_addc_u32 s21, s31, 0
	s_mov_b32 s27, -2
	s_add_u32 s30, s28, 0xfffc0080
	s_addc_u32 s31, s29, -1
	s_add_i32 s50, 0, 0x10000
	s_cmp_eq_u32 s27, 12
	s_cselect_b32 s53, s23, s31
	s_cselect_b32 s52, s22, s30
	v_add_u32_e32 v140, s50, v144
	s_cselect_b32 s31, s25, s21
	s_cselect_b32 s30, s24, s19
	s_add_i32 s56, 0, 0x14000
	ds_read_b128 v[146:149], v140
	ds_read_b128 v[150:153], v140 offset:1024
	ds_read_b128 v[154:157], v140 offset:2048
	ds_read_b128 v[158:161], v140 offset:3072
	v_add_u32_e32 v140, s56, v144
	ds_read_b128 v[162:165], v140
	ds_read_b128 v[166:169], v140 offset:1024
	ds_read_b128 v[170:173], v140 offset:2048
	ds_read_b128 v[174:177], v140 offset:3072
	v_lshl_add_u64 v[140:141], s[28:29], 0, v[136:137]
	s_add_i32 m0, s79, 0xc000
	ds_read_b128 v[178:181], v145
	ds_read_b128 v[182:185], v145 offset:1024
	ds_read_b128 v[186:189], v145 offset:2048
	ds_read_b128 v[190:193], v145 offset:3072
	ds_read_b128 v[202:205], v145 offset:4096
	ds_read_b128 v[206:209], v145 offset:5120
	ds_read_b128 v[210:213], v145 offset:6144
	ds_read_b128 v[214:217], v145 offset:7168
	global_load_lds_dwordx4 v[140:141], off
	v_lshl_add_u64 v[140:141], s[28:29], 0, v[138:139]
	s_add_i32 m0, s79, 0xe000
	s_nop 0
	global_load_lds_dwordx4 v[140:141], off
	s_waitcnt vmcnt(8)
	s_waitcnt lgkmcnt(0)
	s_setprio 1
	s_barrier
	s_waitcnt lgkmcnt(0)
	v_mfma_f32_16x16x32_bf16 v[126:129], v[146:149], v[178:181], 0
	v_mfma_f32_16x16x32_bf16 v[118:121], v[154:157], v[178:181], 0
	v_mfma_f32_16x16x32_bf16 v[102:105], v[154:157], v[186:189], 0
	v_mfma_f32_16x16x32_bf16 v[110:113], v[146:149], v[186:189], 0
	v_mfma_f32_16x16x32_bf16 v[92:95], v[146:149], v[202:205], 0
	v_mfma_f32_16x16x32_bf16 v[84:87], v[154:157], v[202:205], 0
	v_mfma_f32_16x16x32_bf16 v[68:71], v[154:157], v[210:213], 0
	v_mfma_f32_16x16x32_bf16 v[76:79], v[146:149], v[210:213], 0
	v_mfma_f32_16x16x32_bf16 v[126:129], v[150:153], v[182:185], v[126:129]
	v_mfma_f32_16x16x32_bf16 v[118:121], v[158:161], v[182:185], v[118:121]
	v_mfma_f32_16x16x32_bf16 v[102:105], v[158:161], v[190:193], v[102:105]
	v_mfma_f32_16x16x32_bf16 v[110:113], v[150:153], v[190:193], v[110:113]
	v_mfma_f32_16x16x32_bf16 v[92:95], v[150:153], v[206:209], v[92:95]
	v_mfma_f32_16x16x32_bf16 v[84:87], v[158:161], v[206:209], v[84:87]
	v_mfma_f32_16x16x32_bf16 v[68:71], v[158:161], v[214:217], v[68:71]
	v_mfma_f32_16x16x32_bf16 v[76:79], v[150:153], v[214:217], v[76:79]
	s_setprio 0
	s_setprio 1
	v_mfma_f32_16x16x32_bf16 v[122:125], v[162:165], v[178:181], 0
	v_mfma_f32_16x16x32_bf16 v[114:117], v[170:173], v[178:181], 0
	v_mfma_f32_16x16x32_bf16 v[98:101], v[170:173], v[186:189], 0
	v_mfma_f32_16x16x32_bf16 v[106:109], v[162:165], v[186:189], 0
	v_mfma_f32_16x16x32_bf16 v[88:91], v[162:165], v[202:205], 0
	v_mfma_f32_16x16x32_bf16 v[80:83], v[170:173], v[202:205], 0
	v_mfma_f32_16x16x32_bf16 v[64:67], v[170:173], v[210:213], 0
	v_mfma_f32_16x16x32_bf16 v[72:75], v[162:165], v[210:213], 0
	v_mfma_f32_16x16x32_bf16 v[122:125], v[166:169], v[182:185], v[122:125]
	v_mfma_f32_16x16x32_bf16 v[114:117], v[174:177], v[182:185], v[114:117]
	v_mfma_f32_16x16x32_bf16 v[98:101], v[174:177], v[190:193], v[98:101]
	v_mfma_f32_16x16x32_bf16 v[106:109], v[166:169], v[190:193], v[106:109]
	v_mfma_f32_16x16x32_bf16 v[88:91], v[166:169], v[206:209], v[88:91]
	v_mfma_f32_16x16x32_bf16 v[80:83], v[174:177], v[206:209], v[80:83]
	v_mfma_f32_16x16x32_bf16 v[64:67], v[174:177], v[214:217], v[64:67]
	v_mfma_f32_16x16x32_bf16 v[72:75], v[166:169], v[214:217], v[72:75]
	s_barrier
	s_setprio 0
	s_add_i32 s50, s50, s75
	v_lshl_add_u64 v[140:141], s[30:31], 0, v[96:97]
	s_mov_b32 m0, s50
	ds_read_b128 v[178:181], v145 offset:16384
	ds_read_b128 v[182:185], v145 offset:17408
	ds_read_b128 v[186:189], v145 offset:18432
	ds_read_b128 v[190:193], v145 offset:19456
	ds_read_b128 v[202:205], v145 offset:20480
	ds_read_b128 v[206:209], v145 offset:21504
	ds_read_b128 v[210:213], v145 offset:22528
	ds_read_b128 v[214:217], v145 offset:23552
	global_load_lds_dwordx4 v[140:141], off
	s_add_i32 m0, s50, 0x2000
	s_add_u32 s50, s30, 0x40000
	v_lshl_add_u64 v[194:195], s[30:31], 0, v[130:131]
	s_addc_u32 s51, s31, 0
	s_add_i32 s56, s56, s75
	global_load_lds_dwordx4 v[194:195], off
	v_lshl_add_u64 v[218:219], s[50:51], 0, v[96:97]
	s_mov_b32 m0, s56
	v_lshl_add_u64 v[220:221], s[52:53], 0, v[134:135]
	global_load_lds_dwordx4 v[218:219], off
	v_lshl_add_u64 v[218:219], s[50:51], 0, v[130:131]
	s_add_i32 m0, s56, 0x2000
	s_nop 0
	global_load_lds_dwordx4 v[218:219], off
	v_lshl_add_u64 v[218:219], s[52:53], 0, v[132:133]
	s_mov_b32 m0, s79
	s_nop 0
	global_load_lds_dwordx4 v[218:219], off
	s_mov_b32 m0, s80
	s_nop 0
	global_load_lds_dwordx4 v[220:221], off
	s_waitcnt vmcnt(8)
	s_waitcnt lgkmcnt(0)
	s_setprio 1
	s_barrier
; #define PG8_STAGE(bufoff, gbase, V0, V1) do { \
;         __builtin_amdgcn_global_load_lds((const unsigned*)((const char*)(gbase) + (V0)), (LAS unsigned*)(lds + (bufoff) + ldsw), 16, 0, 0); \
;         __builtin_amdgcn_global_load_lds((const unsigned*)((const char*)(gbase) + (V1)), (LAS unsigned*)(lds + (bufoff) + ldsw + 8192), 16, 0, 0); } while (0)
; #define PG8_LDA(dst, b, h) do { _Pragma("unroll") for (int m = 0; m < 4; ++m) _Pragma("unroll") for (int k = 0; k < 2; ++k) dst[m][k] = *(const LAS bf16x8*)(lds + PG8_SA(b, h) + aoff + m * 2048 + k * 1024); } while (0)
; #define PG8_LDB(dst, b, h) do { _Pragma("unroll") for (int n = 0; n < 2; ++n) _Pragma("unroll") for (int k = 0; k < 2; ++k) dst[n][k] = *(const LAS bf16x8*)(lds + PG8_SB(b, h) + boff + n * 2048 + k * 1024); } while (0)
; #define PG8_MMA(ai, bj, At, Bt) do { __builtin_amdgcn_s_setprio(1); _Pragma("unroll") for (int m = 0; m < 4; ++m) _Pragma("unroll") for (int n = 0; n < 2; ++n) _Pragma("unroll") for (int k = 0; k < 2; ++k) \
;         acc[ai][bj][m][n] = __builtin_amdgcn_mfma_f32_16x16x32_bf16(Bt[n][k], At[m][k], acc[ai][bj][m][n], 0, 0, 0); __builtin_amdgcn_s_setprio(0); } while (0)
; template <class Epi, class Sched>
; DI void gemm_phase(LAS unsigned char* lds, const int lda2, const int ldb2, const int nt, const Sched& S, const Epi& E) {
;     ...
;             PG8_LDB(B0, 0, 0); PG8_LDB(B1, 0, 1); PG8_SCHED; PG8_LDA(At, 0, 0); PG8_STAGE(PG8_SA(1, 1), a1 + hstepA, vA0, vA1);
;             PG8_WAIT_V(8); PG8_WAIT_L(0); PG8_BAR; PG8_MMA(0, 0, At, B0); PG8_MMA(0, 1, At, B1); PG8_BAR; PG8_SCHED;
;             PG8_LDA(At, 0, 1); PG8_STAGE(PG8_SB(0, 0), b2, vB0, vB1); PG8_STAGE(PG8_SB(0, 1), b2 + hstepB, vB0, vB1); PG8_STAGE(PG8_SA(0, 0), a2, vA0, vA1);
;             PG8_WAIT_V(8); PG8_WAIT_L(0); PG8_BAR; PG8_MMA(1, 0, At, B0); PG8_MMA(1, 1, At, B1); PG8_BAR; PG8_SCHED;
;             PG8_LDB(B0, 1, 0); PG8_LDB(B1, 1, 1); PG8_SCHED; PG8_LDA(At, 1, 0); PG8_STAGE(PG8_SA(0, 1), a2 + hstepA, vA0, vA1);
;             PG8_WAIT_V(8); PG8_WAIT_L(0); PG8_BAR; PG8_MMA(0, 0, At, B0); PG8_MMA(0, 1, At, B1); PG8_BAR; PG8_SCHED;
;             PG8_LDA(At, 1, 1); PG8_STAGE(PG8_SB(1, 0), b3, vB0, vB1); PG8_STAGE(PG8_SB(1, 1), b3 + hstepB, vB0, vB1); PG8_STAGE(PG8_SA(1, 0), a3, vA0, vA1);
;             PG8_WAIT_V(8); PG8_WAIT_L(0); PG8_BAR; PG8_MMA(1, 0, At, B0); PG8_MMA(1, 1, At, B1); PG8_BAR; PG8_SCHED;
	s_waitcnt lgkmcnt(0)
	v_mfma_f32_16x16x32_bf16 v[60:63], v[146:149], v[178:181], 0
	v_mfma_f32_16x16x32_bf16 v[52:55], v[154:157], v[178:181], 0
	v_mfma_f32_16x16x32_bf16 v[36:39], v[154:157], v[186:189], 0
	v_mfma_f32_16x16x32_bf16 v[44:47], v[146:149], v[186:189], 0
	v_mfma_f32_16x16x32_bf16 v[28:31], v[146:149], v[202:205], 0
	v_mfma_f32_16x16x32_bf16 v[20:23], v[154:157], v[202:205], 0
	v_mfma_f32_16x16x32_bf16 v[4:7], v[154:157], v[210:213], 0
	v_mfma_f32_16x16x32_bf16 v[12:15], v[146:149], v[210:213], 0
	v_mfma_f32_16x16x32_bf16 v[60:63], v[150:153], v[182:185], v[60:63]
	v_mfma_f32_16x16x32_bf16 v[52:55], v[158:161], v[182:185], v[52:55]
	v_mfma_f32_16x16x32_bf16 v[36:39], v[158:161], v[190:193], v[36:39]
	v_mfma_f32_16x16x32_bf16 v[44:47], v[150:153], v[190:193], v[44:47]
	v_mfma_f32_16x16x32_bf16 v[28:31], v[150:153], v[206:209], v[28:31]
	v_mfma_f32_16x16x32_bf16 v[20:23], v[158:161], v[206:209], v[20:23]
	v_mfma_f32_16x16x32_bf16 v[4:7], v[158:161], v[214:217], v[4:7]
	v_mfma_f32_16x16x32_bf16 v[12:15], v[150:153], v[214:217], v[12:15]
	s_setprio 0
	s_setprio 1
	v_mfma_f32_16x16x32_bf16 v[56:59], v[162:165], v[178:181], 0
	v_mfma_f32_16x16x32_bf16 v[48:51], v[170:173], v[178:181], 0
	v_mfma_f32_16x16x32_bf16 v[32:35], v[170:173], v[186:189], 0
	v_mfma_f32_16x16x32_bf16 v[40:43], v[162:165], v[186:189], 0
	v_mfma_f32_16x16x32_bf16 v[24:27], v[162:165], v[202:205], 0
	v_mfma_f32_16x16x32_bf16 v[16:19], v[170:173], v[202:205], 0
	v_mfma_f32_16x16x32_bf16 v[0:3], v[170:173], v[210:213], 0
	v_mfma_f32_16x16x32_bf16 v[8:11], v[162:165], v[210:213], 0
	v_mfma_f32_16x16x32_bf16 v[56:59], v[166:169], v[182:185], v[56:59]
	v_mfma_f32_16x16x32_bf16 v[48:51], v[174:177], v[182:185], v[48:51]
	v_mfma_f32_16x16x32_bf16 v[32:35], v[174:177], v[190:193], v[32:35]
	v_mfma_f32_16x16x32_bf16 v[40:43], v[166:169], v[190:193], v[40:43]
	v_mfma_f32_16x16x32_bf16 v[24:27], v[166:169], v[206:209], v[24:27]
	v_mfma_f32_16x16x32_bf16 v[16:19], v[174:177], v[206:209], v[16:19]
	v_mfma_f32_16x16x32_bf16 v[0:3], v[174:177], v[214:217], v[0:3]
	v_mfma_f32_16x16x32_bf16 v[8:11], v[166:169], v[214:217], v[8:11]
	s_barrier
	s_setprio 0
	s_add_i32 s56, 0, 0x18000
	s_add_i32 s57, 0, 0x1c000
	v_add_u32_e32 v158, s56, v144
	v_add_u32_e32 v174, s57, v144
	ds_read_b128 v[146:149], v158
	ds_read_b128 v[150:153], v158 offset:1024
	ds_read_b128 v[154:157], v158 offset:2048
	ds_read_b128 v[158:161], v158 offset:3072
	ds_read_b128 v[162:165], v174
	ds_read_b128 v[166:169], v174 offset:1024
	ds_read_b128 v[170:173], v174 offset:2048
	ds_read_b128 v[174:177], v174 offset:3072
	s_add_u32 s50, s52, 0x40000
	s_addc_u32 s51, s53, 0
	s_mov_b32 m0, s81
	v_lshl_add_u64 v[222:223], s[50:51], 0, v[132:133]
	ds_read_b128 v[178:181], v145 offset:32768
	ds_read_b128 v[182:185], v145 offset:33792
	ds_read_b128 v[186:189], v145 offset:34816
	ds_read_b128 v[190:193], v145 offset:35840
	ds_read_b128 v[202:205], v145 offset:36864
	ds_read_b128 v[206:209], v145 offset:37888
	ds_read_b128 v[210:213], v145 offset:38912
	ds_read_b128 v[214:217], v145 offset:39936
	global_load_lds_dwordx4 v[222:223], off
	v_lshl_add_u64 v[222:223], s[50:51], 0, v[134:135]
	s_mov_b32 m0, s82
	s_nop 0
	global_load_lds_dwordx4 v[222:223], off
	s_waitcnt vmcnt(8)
	s_waitcnt lgkmcnt(0)
	s_setprio 1
	s_barrier
	s_waitcnt lgkmcnt(0)
	v_mfma_f32_16x16x32_bf16 v[126:129], v[146:149], v[178:181], v[126:129]
	v_mfma_f32_16x16x32_bf16 v[118:121], v[154:157], v[178:181], v[118:121]
	v_mfma_f32_16x16x32_bf16 v[102:105], v[154:157], v[186:189], v[102:105]
	v_mfma_f32_16x16x32_bf16 v[110:113], v[146:149], v[186:189], v[110:113]
	v_mfma_f32_16x16x32_bf16 v[92:95], v[146:149], v[202:205], v[92:95]
	v_mfma_f32_16x16x32_bf16 v[84:87], v[154:157], v[202:205], v[84:87]
	v_mfma_f32_16x16x32_bf16 v[68:71], v[154:157], v[210:213], v[68:71]
	v_mfma_f32_16x16x32_bf16 v[76:79], v[146:149], v[210:213], v[76:79]
	v_mfma_f32_16x16x32_bf16 v[126:129], v[150:153], v[182:185], v[126:129]
	v_mfma_f32_16x16x32_bf16 v[118:121], v[158:161], v[182:185], v[118:121]
	v_mfma_f32_16x16x32_bf16 v[102:105], v[158:161], v[190:193], v[102:105]
	v_mfma_f32_16x16x32_bf16 v[110:113], v[150:153], v[190:193], v[110:113]
	v_mfma_f32_16x16x32_bf16 v[92:95], v[150:153], v[206:209], v[92:95]
	v_mfma_f32_16x16x32_bf16 v[84:87], v[158:161], v[206:209], v[84:87]
	v_mfma_f32_16x16x32_bf16 v[68:71], v[158:161], v[214:217], v[68:71]
	v_mfma_f32_16x16x32_bf16 v[76:79], v[150:153], v[214:217], v[76:79]
	s_setprio 0
	s_setprio 1
	v_mfma_f32_16x16x32_bf16 v[122:125], v[162:165], v[178:181], v[122:125]
	v_mfma_f32_16x16x32_bf16 v[114:117], v[170:173], v[178:181], v[114:117]
	v_mfma_f32_16x16x32_bf16 v[98:101], v[170:173], v[186:189], v[98:101]
	v_mfma_f32_16x16x32_bf16 v[106:109], v[162:165], v[186:189], v[106:109]
	v_mfma_f32_16x16x32_bf16 v[88:91], v[162:165], v[202:205], v[88:91]
	v_mfma_f32_16x16x32_bf16 v[80:83], v[170:173], v[202:205], v[80:83]
	v_mfma_f32_16x16x32_bf16 v[64:67], v[170:173], v[210:213], v[64:67]
	v_mfma_f32_16x16x32_bf16 v[72:75], v[162:165], v[210:213], v[72:75]
	v_mfma_f32_16x16x32_bf16 v[122:125], v[166:169], v[182:185], v[122:125]
	v_mfma_f32_16x16x32_bf16 v[114:117], v[174:177], v[182:185], v[114:117]
	v_mfma_f32_16x16x32_bf16 v[98:101], v[174:177], v[190:193], v[98:101]
	v_mfma_f32_16x16x32_bf16 v[106:109], v[166:169], v[190:193], v[106:109]
	v_mfma_f32_16x16x32_bf16 v[88:91], v[166:169], v[206:209], v[88:91]
	v_mfma_f32_16x16x32_bf16 v[80:83], v[174:177], v[206:209], v[80:83]
	v_mfma_f32_16x16x32_bf16 v[64:67], v[174:177], v[214:217], v[64:67]
	v_mfma_f32_16x16x32_bf16 v[72:75], v[166:169], v[214:217], v[72:75]
	s_barrier
; #define PG8_STAGE(bufoff, gbase, V0, V1) do { \
;         __builtin_amdgcn_global_load_lds((const unsigned*)((const char*)(gbase) + (V0)), (LAS unsigned*)(lds + (bufoff) + ldsw), 16, 0, 0); \
;         __builtin_amdgcn_global_load_lds((const unsigned*)((const char*)(gbase) + (V1)), (LAS unsigned*)(lds + (bufoff) + ldsw + 8192), 16, 0, 0); } while (0)
; #define PG8_LDA(dst, b, h) do { _Pragma("unroll") for (int m = 0; m < 4; ++m) _Pragma("unroll") for (int k = 0; k < 2; ++k) dst[m][k] = *(const LAS bf16x8*)(lds + PG8_SA(b, h) + aoff + m * 2048 + k * 1024); } while (0)
; #define PG8_LDB(dst, b, h) do { _Pragma("unroll") for (int n = 0; n < 2; ++n) _Pragma("unroll") for (int k = 0; k < 2; ++k) dst[n][k] = *(const LAS bf16x8*)(lds + PG8_SB(b, h) + boff + n * 2048 + k * 1024); } while (0)
; template <class Epi, class Sched>
; DI void gemm_phase(LAS unsigned char* lds, const int lda2, const int ldb2, const int nt, const Sched& S, const Epi& E) {
;     ...
;         for (int t = 0; t < nt; t += 2) {
;             const bool last = (t == nt - 2);
;             const char* a1 = cA + (size_t)(t + 1) * kstep;
;             const char* a2 = last ? nA : cA + (size_t)(t + 2) * kstep; const char* b2 = last ? nB : cB + (size_t)(t + 2) * kstep;
;             const char* a3 = a2 + kstep; const char* b3 = b2 + kstep;
;             PG8_LDB(B0, 0, 0); PG8_LDB(B1, 0, 1); PG8_SCHED; PG8_LDA(At, 0, 0); PG8_STAGE(PG8_SA(1, 1), a1 + hstepA, vA0, vA1);
;             PG8_WAIT_V(8); PG8_WAIT_L(0); PG8_BAR; PG8_MMA(0, 0, At, B0); PG8_MMA(0, 1, At, B1); PG8_BAR; PG8_SCHED;
;             PG8_LDA(At, 0, 1); PG8_STAGE(PG8_SB(0, 0), b2, vB0, vB1); PG8_STAGE(PG8_SB(0, 1), b2 + hstepB, vB0, vB1); PG8_STAGE(PG8_SA(0, 0), a2, vA0, vA1);
;             PG8_WAIT_V(8); PG8_WAIT_L(0); PG8_BAR; PG8_MMA(1, 0, At, B0); PG8_MMA(1, 1, At, B1); PG8_BAR; PG8_SCHED;
;             PG8_LDB(B0, 1, 0); PG8_LDB(B1, 1, 1); PG8_SCHED; PG8_LDA(At, 1, 0); PG8_STAGE(PG8_SA(0, 1), a2 + hstepA, vA0, vA1);
;             PG8_WAIT_V(8); PG8_WAIT_L(0); PG8_BAR; PG8_MMA(0, 0, At, B0); PG8_MMA(0, 1, At, B1); PG8_BAR; PG8_SCHED;
;             PG8_LDA(At, 1, 1); PG8_STAGE(PG8_SB(1, 0), b3, vB0, vB1); PG8_STAGE(PG8_SB(1, 1), b3 + hstepB, vB0, vB1); PG8_STAGE(PG8_SA(1, 0), a3, vA0, vA1);
;             PG8_WAIT_V(8); PG8_WAIT_L(0); PG8_BAR; PG8_MMA(1, 0, At, B0); PG8_MMA(1, 1, At, B1); PG8_BAR; PG8_SCHED;
	s_setprio 0
	s_add_i32 s50, s56, s75
	v_lshl_add_u64 v[140:141], v[140:141], 0, s[86:87]
	s_mov_b32 m0, s50
	ds_read_b128 v[178:181], v145 offset:49152
	ds_read_b128 v[182:185], v145 offset:50176
	ds_read_b128 v[186:189], v145 offset:51200
	ds_read_b128 v[190:193], v145 offset:52224
	ds_read_b128 v[202:205], v145 offset:53248
	ds_read_b128 v[206:209], v145 offset:54272
	ds_read_b128 v[210:213], v145 offset:55296
	ds_read_b128 v[214:217], v145 offset:56320
	global_load_lds_dwordx4 v[140:141], off
	s_add_i32 m0, s50, 0x2000
	s_add_u32 s30, s30, 0x40080
	v_lshl_add_u64 v[140:141], v[194:195], 0, s[86:87]
	s_addc_u32 s31, s31, 0
	s_add_i32 s50, s57, s75
	global_load_lds_dwordx4 v[140:141], off
	v_lshl_add_u64 v[140:141], s[30:31], 0, v[96:97]
	s_mov_b32 m0, s50
	s_nop 0
	global_load_lds_dwordx4 v[140:141], off
	v_lshl_add_u64 v[140:141], s[30:31], 0, v[130:131]
	s_add_i32 m0, s50, 0x2000
	s_nop 0
	global_load_lds_dwordx4 v[140:141], off
	v_lshl_add_u64 v[140:141], v[218:219], 0, s[86:87]
	s_mov_b32 m0, s85
	s_nop 0
	global_load_lds_dwordx4 v[140:141], off
	v_lshl_add_u64 v[140:141], v[220:221], 0, s[86:87]
	s_mov_b32 m0, s14
	s_nop 0
	global_load_lds_dwordx4 v[140:141], off
	s_waitcnt vmcnt(8)
	s_waitcnt lgkmcnt(0)
	s_setprio 1
	s_barrier
	s_waitcnt lgkmcnt(0)
	v_mfma_f32_16x16x32_bf16 v[60:63], v[146:149], v[178:181], v[60:63]
	v_mfma_f32_16x16x32_bf16 v[52:55], v[154:157], v[178:181], v[52:55]
	v_mfma_f32_16x16x32_bf16 v[36:39], v[154:157], v[186:189], v[36:39]
	v_mfma_f32_16x16x32_bf16 v[44:47], v[146:149], v[186:189], v[44:47]
	v_mfma_f32_16x16x32_bf16 v[28:31], v[146:149], v[202:205], v[28:31]
	v_mfma_f32_16x16x32_bf16 v[20:23], v[154:157], v[202:205], v[20:23]
	v_mfma_f32_16x16x32_bf16 v[4:7], v[154:157], v[210:213], v[4:7]
	v_mfma_f32_16x16x32_bf16 v[12:15], v[146:149], v[210:213], v[12:15]
	v_mfma_f32_16x16x32_bf16 v[60:63], v[150:153], v[182:185], v[60:63]
	v_mfma_f32_16x16x32_bf16 v[52:55], v[158:161], v[182:185], v[52:55]
	v_mfma_f32_16x16x32_bf16 v[36:39], v[158:161], v[190:193], v[36:39]
	v_mfma_f32_16x16x32_bf16 v[44:47], v[150:153], v[190:193], v[44:47]
	v_mfma_f32_16x16x32_bf16 v[28:31], v[150:153], v[206:209], v[28:31]
	v_mfma_f32_16x16x32_bf16 v[20:23], v[158:161], v[206:209], v[20:23]
	v_mfma_f32_16x16x32_bf16 v[4:7], v[158:161], v[214:217], v[4:7]
	v_mfma_f32_16x16x32_bf16 v[12:15], v[150:153], v[214:217], v[12:15]
	s_setprio 0
	s_setprio 1
	v_mfma_f32_16x16x32_bf16 v[56:59], v[162:165], v[178:181], v[56:59]
	v_mfma_f32_16x16x32_bf16 v[48:51], v[170:173], v[178:181], v[48:51]
	v_mfma_f32_16x16x32_bf16 v[32:35], v[170:173], v[186:189], v[32:35]
	v_mfma_f32_16x16x32_bf16 v[40:43], v[162:165], v[186:189], v[40:43]
	v_mfma_f32_16x16x32_bf16 v[24:27], v[162:165], v[202:205], v[24:27]
	v_mfma_f32_16x16x32_bf16 v[16:19], v[170:173], v[202:205], v[16:19]
	v_mfma_f32_16x16x32_bf16 v[0:3], v[170:173], v[210:213], v[0:3]
	v_mfma_f32_16x16x32_bf16 v[8:11], v[162:165], v[210:213], v[8:11]
	v_mfma_f32_16x16x32_bf16 v[56:59], v[166:169], v[182:185], v[56:59]
	v_mfma_f32_16x16x32_bf16 v[48:51], v[174:177], v[182:185], v[48:51]
	v_mfma_f32_16x16x32_bf16 v[32:35], v[174:177], v[190:193], v[32:35]
	v_mfma_f32_16x16x32_bf16 v[40:43], v[166:169], v[190:193], v[40:43]
	v_mfma_f32_16x16x32_bf16 v[24:27], v[166:169], v[206:209], v[24:27]
	v_mfma_f32_16x16x32_bf16 v[16:19], v[174:177], v[206:209], v[16:19]
	v_mfma_f32_16x16x32_bf16 v[0:3], v[174:177], v[214:217], v[0:3]
	v_mfma_f32_16x16x32_bf16 v[8:11], v[166:169], v[214:217], v[8:11]
	s_barrier
	s_setprio 0
	s_add_i32 s27, s27, 2
	s_add_u32 s28, s28, 0x100
	s_addc_u32 s29, s29, 0
	s_add_u32 s19, s19, 0x100
	s_addc_u32 s21, s21, 0
.LBB0_1053:
	s_add_u32 s30, s28, 0xfffc0080
	s_addc_u32 s31, s29, -1
	s_add_i32 s50, 0, 0x10000
	s_cmp_eq_u32 s27, 12
	s_cselect_b32 s53, s23, s31
	s_cselect_b32 s52, s22, s30
	v_add_u32_e32 v140, s50, v144
	s_cselect_b32 s31, s25, s21
	s_cselect_b32 s30, s24, s19
	s_add_i32 s56, 0, 0x14000
	ds_read_b128 v[146:149], v140
	ds_read_b128 v[150:153], v140 offset:1024
	ds_read_b128 v[154:157], v140 offset:2048
	ds_read_b128 v[158:161], v140 offset:3072
	v_add_u32_e32 v140, s56, v144
	ds_read_b128 v[162:165], v140
	ds_read_b128 v[166:169], v140 offset:1024
	ds_read_b128 v[170:173], v140 offset:2048
	ds_read_b128 v[174:177], v140 offset:3072
	v_lshl_add_u64 v[140:141], s[28:29], 0, v[136:137]
	s_add_i32 m0, s79, 0xc000
	ds_read_b128 v[178:181], v145
	ds_read_b128 v[182:185], v145 offset:1024
	ds_read_b128 v[186:189], v145 offset:2048
	ds_read_b128 v[190:193], v145 offset:3072
	ds_read_b128 v[202:205], v145 offset:4096
	ds_read_b128 v[206:209], v145 offset:5120
	ds_read_b128 v[210:213], v145 offset:6144
	ds_read_b128 v[214:217], v145 offset:7168
	global_load_lds_dwordx4 v[140:141], off
	v_lshl_add_u64 v[140:141], s[28:29], 0, v[138:139]
	s_add_i32 m0, s79, 0xe000
	s_nop 0
	global_load_lds_dwordx4 v[140:141], off
	s_waitcnt vmcnt(8)
	s_waitcnt lgkmcnt(0)
	s_setprio 1
	s_barrier
; #define PG8_STAGE(bufoff, gbase, V0, V1) do { \
;         __builtin_amdgcn_global_load_lds((const unsigned*)((const char*)(gbase) + (V0)), (LAS unsigned*)(lds + (bufoff) + ldsw), 16, 0, 0); \
;         __builtin_amdgcn_global_load_lds((const unsigned*)((const char*)(gbase) + (V1)), (LAS unsigned*)(lds + (bufoff) + ldsw + 8192), 16, 0, 0); } while (0)
; #define PG8_LDA(dst, b, h) do { _Pragma("unroll") for (int m = 0; m < 4; ++m) _Pragma("unroll") for (int k = 0; k < 2; ++k) dst[m][k] = *(const LAS bf16x8*)(lds + PG8_SA(b, h) + aoff + m * 2048 + k * 1024); } while (0)
; #define PG8_LDB(dst, b, h) do { _Pragma("unroll") for (int n = 0; n < 2; ++n) _Pragma("unroll") for (int k = 0; k < 2; ++k) dst[n][k] = *(const LAS bf16x8*)(lds + PG8_SB(b, h) + boff + n * 2048 + k * 1024); } while (0)
; #define PG8_MMA(ai, bj, At, Bt) do { __builtin_amdgcn_s_setprio(1); _Pragma("unroll") for (int m = 0; m < 4; ++m) _Pragma("unroll") for (int n = 0; n < 2; ++n) _Pragma("unroll") for (int k = 0; k < 2; ++k) \
;         acc[ai][bj][m][n] = __builtin_amdgcn_mfma_f32_16x16x32_bf16(Bt[n][k], At[m][k], acc[ai][bj][m][n], 0, 0, 0); __builtin_amdgcn_s_setprio(0); } while (0)
; template <class Epi, class Sched>
; DI void gemm_phase(LAS unsigned char* lds, const int lda2, const int ldb2, const int nt, const Sched& S, const Epi& E) {
;     ...
;             PG8_LDB(B0, 0, 0); PG8_LDB(B1, 0, 1); PG8_SCHED; PG8_LDA(At, 0, 0); PG8_STAGE(PG8_SA(1, 1), a1 + hstepA, vA0, vA1);
;             PG8_WAIT_V(8); PG8_WAIT_L(0); PG8_BAR; PG8_MMA(0, 0, At, B0); PG8_MMA(0, 1, At, B1); PG8_BAR; PG8_SCHED;
;             PG8_LDA(At, 0, 1); PG8_STAGE(PG8_SB(0, 0), b2, vB0, vB1); PG8_STAGE(PG8_SB(0, 1), b2 + hstepB, vB0, vB1); PG8_STAGE(PG8_SA(0, 0), a2, vA0, vA1);
;             PG8_WAIT_V(8); PG8_WAIT_L(0); PG8_BAR; PG8_MMA(1, 0, At, B0); PG8_MMA(1, 1, At, B1); PG8_BAR; PG8_SCHED;
;             PG8_LDB(B0, 1, 0); PG8_LDB(B1, 1, 1); PG8_SCHED; PG8_LDA(At, 1, 0); PG8_STAGE(PG8_SA(0, 1), a2 + hstepA, vA0, vA1);
;             PG8_WAIT_V(8); PG8_WAIT_L(0); PG8_BAR; PG8_MMA(0, 0, At, B0); PG8_MMA(0, 1, At, B1); PG8_BAR; PG8_SCHED;
;             PG8_LDA(At, 1, 1); PG8_STAGE(PG8_SB(1, 0), b3, vB0, vB1); PG8_STAGE(PG8_SB(1, 1), b3 + hstepB, vB0, vB1); PG8_STAGE(PG8_SA(1, 0), a3, vA0, vA1);
;             PG8_WAIT_V(8); PG8_WAIT_L(0); PG8_BAR; PG8_MMA(1, 0, At, B0); PG8_MMA(1, 1, At, B1); PG8_BAR; PG8_SCHED;
	s_waitcnt lgkmcnt(0)
	v_mfma_f32_16x16x32_bf16 v[126:129], v[146:149], v[178:181], v[126:129]
	v_mfma_f32_16x16x32_bf16 v[118:121], v[154:157], v[178:181], v[118:121]
	v_mfma_f32_16x16x32_bf16 v[102:105], v[154:157], v[186:189], v[102:105]
	v_mfma_f32_16x16x32_bf16 v[110:113], v[146:149], v[186:189], v[110:113]
	v_mfma_f32_16x16x32_bf16 v[92:95], v[146:149], v[202:205], v[92:95]
	v_mfma_f32_16x16x32_bf16 v[84:87], v[154:157], v[202:205], v[84:87]
	v_mfma_f32_16x16x32_bf16 v[68:71], v[154:157], v[210:213], v[68:71]
	v_mfma_f32_16x16x32_bf16 v[76:79], v[146:149], v[210:213], v[76:79]
	v_mfma_f32_16x16x32_bf16 v[126:129], v[150:153], v[182:185], v[126:129]
	v_mfma_f32_16x16x32_bf16 v[118:121], v[158:161], v[182:185], v[118:121]
	v_mfma_f32_16x16x32_bf16 v[102:105], v[158:161], v[190:193], v[102:105]
	v_mfma_f32_16x16x32_bf16 v[110:113], v[150:153], v[190:193], v[110:113]
	v_mfma_f32_16x16x32_bf16 v[92:95], v[150:153], v[206:209], v[92:95]
	v_mfma_f32_16x16x32_bf16 v[84:87], v[158:161], v[206:209], v[84:87]
	v_mfma_f32_16x16x32_bf16 v[68:71], v[158:161], v[214:217], v[68:71]
	v_mfma_f32_16x16x32_bf16 v[76:79], v[150:153], v[214:217], v[76:79]
	s_setprio 0
	s_setprio 1
	v_mfma_f32_16x16x32_bf16 v[122:125], v[162:165], v[178:181], v[122:125]
	v_mfma_f32_16x16x32_bf16 v[114:117], v[170:173], v[178:181], v[114:117]
	v_mfma_f32_16x16x32_bf16 v[98:101], v[170:173], v[186:189], v[98:101]
	v_mfma_f32_16x16x32_bf16 v[106:109], v[162:165], v[186:189], v[106:109]
	v_mfma_f32_16x16x32_bf16 v[88:91], v[162:165], v[202:205], v[88:91]
	v_mfma_f32_16x16x32_bf16 v[80:83], v[170:173], v[202:205], v[80:83]
	v_mfma_f32_16x16x32_bf16 v[64:67], v[170:173], v[210:213], v[64:67]
	v_mfma_f32_16x16x32_bf16 v[72:75], v[162:165], v[210:213], v[72:75]
	v_mfma_f32_16x16x32_bf16 v[122:125], v[166:169], v[182:185], v[122:125]
	v_mfma_f32_16x16x32_bf16 v[114:117], v[174:177], v[182:185], v[114:117]
	v_mfma_f32_16x16x32_bf16 v[98:101], v[174:177], v[190:193], v[98:101]
	v_mfma_f32_16x16x32_bf16 v[106:109], v[166:169], v[190:193], v[106:109]
	v_mfma_f32_16x16x32_bf16 v[88:91], v[166:169], v[206:209], v[88:91]
	v_mfma_f32_16x16x32_bf16 v[80:83], v[174:177], v[206:209], v[80:83]
	v_mfma_f32_16x16x32_bf16 v[64:67], v[174:177], v[214:217], v[64:67]
	v_mfma_f32_16x16x32_bf16 v[72:75], v[166:169], v[214:217], v[72:75]
	s_barrier
	s_setprio 0
	s_add_i32 s50, s50, s75
	v_lshl_add_u64 v[140:141], s[30:31], 0, v[96:97]
	s_mov_b32 m0, s50
	ds_read_b128 v[178:181], v145 offset:16384
	ds_read_b128 v[182:185], v145 offset:17408
	ds_read_b128 v[186:189], v145 offset:18432
	ds_read_b128 v[190:193], v145 offset:19456
	ds_read_b128 v[202:205], v145 offset:20480
	ds_read_b128 v[206:209], v145 offset:21504
	ds_read_b128 v[210:213], v145 offset:22528
	ds_read_b128 v[214:217], v145 offset:23552
	global_load_lds_dwordx4 v[140:141], off
	s_add_i32 m0, s50, 0x2000
	s_add_u32 s50, s30, 0x40000
	v_lshl_add_u64 v[194:195], s[30:31], 0, v[130:131]
	s_addc_u32 s51, s31, 0
	s_add_i32 s56, s56, s75
	global_load_lds_dwordx4 v[194:195], off
	v_lshl_add_u64 v[218:219], s[50:51], 0, v[96:97]
	s_mov_b32 m0, s56
	v_lshl_add_u64 v[220:221], s[52:53], 0, v[134:135]
	global_load_lds_dwordx4 v[218:219], off
	v_lshl_add_u64 v[218:219], s[50:51], 0, v[130:131]
	s_add_i32 m0, s56, 0x2000
	s_nop 0
	global_load_lds_dwordx4 v[218:219], off
	v_lshl_add_u64 v[218:219], s[52:53], 0, v[132:133]
	s_mov_b32 m0, s79
	s_nop 0
	global_load_lds_dwordx4 v[218:219], off
	s_mov_b32 m0, s80
	s_nop 0
	global_load_lds_dwordx4 v[220:221], off
	s_waitcnt vmcnt(8)
	s_waitcnt lgkmcnt(0)
	s_setprio 1
	s_barrier
	s_waitcnt lgkmcnt(0)
	v_mfma_f32_16x16x32_bf16 v[60:63], v[146:149], v[178:181], v[60:63]
	v_mfma_f32_16x16x32_bf16 v[52:55], v[154:157], v[178:181], v[52:55]
	v_mfma_f32_16x16x32_bf16 v[36:39], v[154:157], v[186:189], v[36:39]
	v_mfma_f32_16x16x32_bf16 v[44:47], v[146:149], v[186:189], v[44:47]
	v_mfma_f32_16x16x32_bf16 v[28:31], v[146:149], v[202:205], v[28:31]
	v_mfma_f32_16x16x32_bf16 v[20:23], v[154:157], v[202:205], v[20:23]
	v_mfma_f32_16x16x32_bf16 v[4:7], v[154:157], v[210:213], v[4:7]
	v_mfma_f32_16x16x32_bf16 v[12:15], v[146:149], v[210:213], v[12:15]
	v_mfma_f32_16x16x32_bf16 v[60:63], v[150:153], v[182:185], v[60:63]
	v_mfma_f32_16x16x32_bf16 v[52:55], v[158:161], v[182:185], v[52:55]
	v_mfma_f32_16x16x32_bf16 v[36:39], v[158:161], v[190:193], v[36:39]
	v_mfma_f32_16x16x32_bf16 v[44:47], v[150:153], v[190:193], v[44:47]
	v_mfma_f32_16x16x32_bf16 v[28:31], v[150:153], v[206:209], v[28:31]
	v_mfma_f32_16x16x32_bf16 v[20:23], v[158:161], v[206:209], v[20:23]
	v_mfma_f32_16x16x32_bf16 v[4:7], v[158:161], v[214:217], v[4:7]
	v_mfma_f32_16x16x32_bf16 v[12:15], v[150:153], v[214:217], v[12:15]
	s_setprio 0
	s_setprio 1
	v_mfma_f32_16x16x32_bf16 v[56:59], v[162:165], v[178:181], v[56:59]
	v_mfma_f32_16x16x32_bf16 v[48:51], v[170:173], v[178:181], v[48:51]
	v_mfma_f32_16x16x32_bf16 v[32:35], v[170:173], v[186:189], v[32:35]
	v_mfma_f32_16x16x32_bf16 v[40:43], v[162:165], v[186:189], v[40:43]
	v_mfma_f32_16x16x32_bf16 v[24:27], v[162:165], v[202:205], v[24:27]
	v_mfma_f32_16x16x32_bf16 v[16:19], v[170:173], v[202:205], v[16:19]
	v_mfma_f32_16x16x32_bf16 v[0:3], v[170:173], v[210:213], v[0:3]
	v_mfma_f32_16x16x32_bf16 v[8:11], v[162:165], v[210:213], v[8:11]
	v_mfma_f32_16x16x32_bf16 v[56:59], v[166:169], v[182:185], v[56:59]
	v_mfma_f32_16x16x32_bf16 v[48:51], v[174:177], v[182:185], v[48:51]
	v_mfma_f32_16x16x32_bf16 v[32:35], v[174:177], v[190:193], v[32:35]
	v_mfma_f32_16x16x32_bf16 v[40:43], v[166:169], v[190:193], v[40:43]
	v_mfma_f32_16x16x32_bf16 v[24:27], v[166:169], v[206:209], v[24:27]
	v_mfma_f32_16x16x32_bf16 v[16:19], v[174:177], v[206:209], v[16:19]
	v_mfma_f32_16x16x32_bf16 v[0:3], v[174:177], v[214:217], v[0:3]
	v_mfma_f32_16x16x32_bf16 v[8:11], v[166:169], v[214:217], v[8:11]
	s_barrier
; #define PG8_STAGE(bufoff, gbase, V0, V1) do { \
;         __builtin_amdgcn_global_load_lds((const unsigned*)((const char*)(gbase) + (V0)), (LAS unsigned*)(lds + (bufoff) + ldsw), 16, 0, 0); \
;         __builtin_amdgcn_global_load_lds((const unsigned*)((const char*)(gbase) + (V1)), (LAS unsigned*)(lds + (bufoff) + ldsw + 8192), 16, 0, 0); } while (0)
; #define PG8_LDA(dst, b, h) do { _Pragma("unroll") for (int m = 0; m < 4; ++m) _Pragma("unroll") for (int k = 0; k < 2; ++k) dst[m][k] = *(const LAS bf16x8*)(lds + PG8_SA(b, h) + aoff + m * 2048 + k * 1024); } while (0)
; #define PG8_MMA(ai, bj, At, Bt) do { __builtin_amdgcn_s_setprio(1); _Pragma("unroll") for (int m = 0; m < 4; ++m) _Pragma("unroll") for (int n = 0; n < 2; ++n) _Pragma("unroll") for (int k = 0; k < 2; ++k) \
;         acc[ai][bj][m][n] = __builtin_amdgcn_mfma_f32_16x16x32_bf16(Bt[n][k], At[m][k], acc[ai][bj][m][n], 0, 0, 0); __builtin_amdgcn_s_setprio(0); } while (0)
; #define PG8_WAIT_V(n) asm volatile("s_waitcnt vmcnt(" #n ")" ::: "memory")
; #define PG8_WAIT_L(n) asm volatile("s_waitcnt lgkmcnt(" #n ")" ::: "memory")
; #define PG8_BAR __builtin_amdgcn_s_barrier()
; #define PG8_SCHED __builtin_amdgcn_sched_barrier(0)
; template <class Epi, class Sched>
; DI void gemm_phase(LAS unsigned char* lds, const int lda2, const int ldb2, const int nt, const Sched& S, const Epi& E) {
;     ...
;             PG8_LDA(At, 1, 1); PG8_STAGE(PG8_SB(1, 0), b3, vB0, vB1); PG8_STAGE(PG8_SB(1, 1), b3 + hstepB, vB0, vB1); PG8_STAGE(PG8_SA(1, 0), a3, vA0, vA1);
;             PG8_WAIT_V(8); PG8_WAIT_L(0); PG8_BAR; PG8_MMA(1, 0, At, B0); PG8_MMA(1, 1, At, B1); PG8_BAR; PG8_SCHED;
	s_setprio 0
	s_add_i32 s56, 0, 0x18000
	s_add_i32 s57, 0, 0x1c000
	v_add_u32_e32 v158, s56, v144
	v_add_u32_e32 v174, s57, v144
	ds_read_b128 v[146:149], v158
	ds_read_b128 v[150:153], v158 offset:1024
	ds_read_b128 v[154:157], v158 offset:2048
	ds_read_b128 v[158:161], v158 offset:3072
	ds_read_b128 v[162:165], v174
	ds_read_b128 v[166:169], v174 offset:1024
	ds_read_b128 v[170:173], v174 offset:2048
	ds_read_b128 v[174:177], v174 offset:3072
	s_add_u32 s50, s52, 0x40000
	s_addc_u32 s51, s53, 0
	s_mov_b32 m0, s81
	v_lshl_add_u64 v[222:223], s[50:51], 0, v[132:133]
	ds_read_b128 v[178:181], v145 offset:32768
	ds_read_b128 v[182:185], v145 offset:33792
	ds_read_b128 v[186:189], v145 offset:34816
	ds_read_b128 v[190:193], v145 offset:35840
	ds_read_b128 v[202:205], v145 offset:36864
	ds_read_b128 v[206:209], v145 offset:37888
	ds_read_b128 v[210:213], v145 offset:38912
	ds_read_b128 v[214:217], v145 offset:39936
	global_load_lds_dwordx4 v[222:223], off
	v_lshl_add_u64 v[222:223], s[50:51], 0, v[134:135]
	s_mov_b32 m0, s82
	s_nop 0
	global_load_lds_dwordx4 v[222:223], off
	s_waitcnt vmcnt(8)
	s_waitcnt lgkmcnt(0)
	s_setprio 1
	s_barrier
	s_waitcnt lgkmcnt(0)
	v_mfma_f32_16x16x32_bf16 v[126:129], v[146:149], v[178:181], v[126:129]
	v_mfma_f32_16x16x32_bf16 v[118:121], v[154:157], v[178:181], v[118:121]
	v_mfma_f32_16x16x32_bf16 v[102:105], v[154:157], v[186:189], v[102:105]
	v_mfma_f32_16x16x32_bf16 v[110:113], v[146:149], v[186:189], v[110:113]
	v_mfma_f32_16x16x32_bf16 v[92:95], v[146:149], v[202:205], v[92:95]
	v_mfma_f32_16x16x32_bf16 v[84:87], v[154:157], v[202:205], v[84:87]
	v_mfma_f32_16x16x32_bf16 v[68:71], v[154:157], v[210:213], v[68:71]
	v_mfma_f32_16x16x32_bf16 v[76:79], v[146:149], v[210:213], v[76:79]
	v_mfma_f32_16x16x32_bf16 v[126:129], v[150:153], v[182:185], v[126:129]
	v_mfma_f32_16x16x32_bf16 v[118:121], v[158:161], v[182:185], v[118:121]
	v_mfma_f32_16x16x32_bf16 v[102:105], v[158:161], v[190:193], v[102:105]
	v_mfma_f32_16x16x32_bf16 v[110:113], v[150:153], v[190:193], v[110:113]
	v_mfma_f32_16x16x32_bf16 v[92:95], v[150:153], v[206:209], v[92:95]
	v_mfma_f32_16x16x32_bf16 v[84:87], v[158:161], v[206:209], v[84:87]
	v_mfma_f32_16x16x32_bf16 v[68:71], v[158:161], v[214:217], v[68:71]
	v_mfma_f32_16x16x32_bf16 v[76:79], v[150:153], v[214:217], v[76:79]
	s_setprio 0
	s_setprio 1
	v_mfma_f32_16x16x32_bf16 v[122:125], v[162:165], v[178:181], v[122:125]
	v_mfma_f32_16x16x32_bf16 v[114:117], v[170:173], v[178:181], v[114:117]
	v_mfma_f32_16x16x32_bf16 v[98:101], v[170:173], v[186:189], v[98:101]
	v_mfma_f32_16x16x32_bf16 v[106:109], v[162:165], v[186:189], v[106:109]
	v_mfma_f32_16x16x32_bf16 v[88:91], v[162:165], v[202:205], v[88:91]
	v_mfma_f32_16x16x32_bf16 v[80:83], v[170:173], v[202:205], v[80:83]
	v_mfma_f32_16x16x32_bf16 v[64:67], v[170:173], v[210:213], v[64:67]
	v_mfma_f32_16x16x32_bf16 v[72:75], v[162:165], v[210:213], v[72:75]
	v_mfma_f32_16x16x32_bf16 v[122:125], v[166:169], v[182:185], v[122:125]
	v_mfma_f32_16x16x32_bf16 v[114:117], v[174:177], v[182:185], v[114:117]
	v_mfma_f32_16x16x32_bf16 v[98:101], v[174:177], v[190:193], v[98:101]
	v_mfma_f32_16x16x32_bf16 v[106:109], v[166:169], v[190:193], v[106:109]
	v_mfma_f32_16x16x32_bf16 v[88:91], v[166:169], v[206:209], v[88:91]
	v_mfma_f32_16x16x32_bf16 v[80:83], v[174:177], v[206:209], v[80:83]
	v_mfma_f32_16x16x32_bf16 v[64:67], v[174:177], v[214:217], v[64:67]
	v_mfma_f32_16x16x32_bf16 v[72:75], v[166:169], v[214:217], v[72:75]
	s_barrier
; #define PG8_STAGE(bufoff, gbase, V0, V1) do { \
;         __builtin_amdgcn_global_load_lds((const unsigned*)((const char*)(gbase) + (V0)), (LAS unsigned*)(lds + (bufoff) + ldsw), 16, 0, 0); \
;         __builtin_amdgcn_global_load_lds((const unsigned*)((const char*)(gbase) + (V1)), (LAS unsigned*)(lds + (bufoff) + ldsw + 8192), 16, 0, 0); } while (0)
; #define PG8_LDA(dst, b, h) do { _Pragma("unroll") for (int m = 0; m < 4; ++m) _Pragma("unroll") for (int k = 0; k < 2; ++k) dst[m][k] = *(const LAS bf16x8*)(lds + PG8_SA(b, h) + aoff + m * 2048 + k * 1024); } while (0)
; #define PG8_MMA(ai, bj, At, Bt) do { __builtin_amdgcn_s_setprio(1); _Pragma("unroll") for (int m = 0; m < 4; ++m) _Pragma("unroll") for (int n = 0; n < 2; ++n) _Pragma("unroll") for (int k = 0; k < 2; ++k) \
;         acc[ai][bj][m][n] = __builtin_amdgcn_mfma_f32_16x16x32_bf16(Bt[n][k], At[m][k], acc[ai][bj][m][n], 0, 0, 0); __builtin_amdgcn_s_setprio(0); } while (0)
; #define PG8_WAIT_V(n) asm volatile("s_waitcnt vmcnt(" #n ")" ::: "memory")
; #define PG8_WAIT_L(n) asm volatile("s_waitcnt lgkmcnt(" #n ")" ::: "memory")
; #define PG8_BAR __builtin_amdgcn_s_barrier()
; #define PG8_SCHED __builtin_amdgcn_sched_barrier(0)
; template <class Epi, class Sched>
; DI void gemm_phase(LAS unsigned char* lds, const int lda2, const int ldb2, const int nt, const Sched& S, const Epi& E) {
;     ...
;             PG8_LDA(At, 1, 1); PG8_STAGE(PG8_SB(1, 0), b3, vB0, vB1); PG8_STAGE(PG8_SB(1, 1), b3 + hstepB, vB0, vB1); PG8_STAGE(PG8_SA(1, 0), a3, vA0, vA1);
;             PG8_WAIT_V(8); PG8_WAIT_L(0); PG8_BAR; PG8_MMA(1, 0, At, B0); PG8_MMA(1, 1, At, B1); PG8_BAR; PG8_SCHED;
;         }
;         if (wr == 0) PG8_BAR;
	s_setprio 0
	s_add_i32 s50, s56, s75
	v_lshl_add_u64 v[140:141], v[140:141], 0, s[86:87]
	s_mov_b32 m0, s50
	ds_read_b128 v[178:181], v145 offset:49152
	ds_read_b128 v[182:185], v145 offset:50176
	ds_read_b128 v[186:189], v145 offset:51200
	ds_read_b128 v[190:193], v145 offset:52224
	ds_read_b128 v[202:205], v145 offset:53248
	ds_read_b128 v[206:209], v145 offset:54272
	ds_read_b128 v[210:213], v145 offset:55296
	ds_read_b128 v[214:217], v145 offset:56320
	global_load_lds_dwordx4 v[140:141], off
	s_add_i32 m0, s50, 0x2000
	s_add_u32 s30, s30, 0x40080
	v_lshl_add_u64 v[140:141], v[194:195], 0, s[86:87]
	s_addc_u32 s31, s31, 0
	s_add_i32 s50, s57, s75
	global_load_lds_dwordx4 v[140:141], off
	v_lshl_add_u64 v[140:141], s[30:31], 0, v[96:97]
	s_mov_b32 m0, s50
	s_nop 0
	global_load_lds_dwordx4 v[140:141], off
	v_lshl_add_u64 v[140:141], s[30:31], 0, v[130:131]
	s_add_i32 m0, s50, 0x2000
	s_nop 0
	global_load_lds_dwordx4 v[140:141], off
	v_lshl_add_u64 v[140:141], v[218:219], 0, s[86:87]
	s_mov_b32 m0, s85
	s_nop 0
	global_load_lds_dwordx4 v[140:141], off
	v_lshl_add_u64 v[140:141], v[220:221], 0, s[86:87]
	s_mov_b32 m0, s14
	s_nop 0
	global_load_lds_dwordx4 v[140:141], off
	s_waitcnt vmcnt(8)
	s_waitcnt lgkmcnt(0)
	s_setprio 1
	s_barrier
	s_waitcnt lgkmcnt(0)
	v_mfma_f32_16x16x32_bf16 v[60:63], v[146:149], v[178:181], v[60:63]
	v_mfma_f32_16x16x32_bf16 v[52:55], v[154:157], v[178:181], v[52:55]
	v_mfma_f32_16x16x32_bf16 v[36:39], v[154:157], v[186:189], v[36:39]
	v_mfma_f32_16x16x32_bf16 v[44:47], v[146:149], v[186:189], v[44:47]
	v_mfma_f32_16x16x32_bf16 v[28:31], v[146:149], v[202:205], v[28:31]
	v_mfma_f32_16x16x32_bf16 v[20:23], v[154:157], v[202:205], v[20:23]
	v_mfma_f32_16x16x32_bf16 v[4:7], v[154:157], v[210:213], v[4:7]
	v_mfma_f32_16x16x32_bf16 v[12:15], v[146:149], v[210:213], v[12:15]
	v_mfma_f32_16x16x32_bf16 v[60:63], v[150:153], v[182:185], v[60:63]
	v_mfma_f32_16x16x32_bf16 v[52:55], v[158:161], v[182:185], v[52:55]
	v_mfma_f32_16x16x32_bf16 v[36:39], v[158:161], v[190:193], v[36:39]
	v_mfma_f32_16x16x32_bf16 v[44:47], v[150:153], v[190:193], v[44:47]
	v_mfma_f32_16x16x32_bf16 v[28:31], v[150:153], v[206:209], v[28:31]
	v_mfma_f32_16x16x32_bf16 v[20:23], v[158:161], v[206:209], v[20:23]
	v_mfma_f32_16x16x32_bf16 v[4:7], v[158:161], v[214:217], v[4:7]
	v_mfma_f32_16x16x32_bf16 v[12:15], v[150:153], v[214:217], v[12:15]
	s_setprio 0
	s_setprio 1
	v_mfma_f32_16x16x32_bf16 v[56:59], v[162:165], v[178:181], v[56:59]
	v_mfma_f32_16x16x32_bf16 v[48:51], v[170:173], v[178:181], v[48:51]
	v_mfma_f32_16x16x32_bf16 v[32:35], v[170:173], v[186:189], v[32:35]
	v_mfma_f32_16x16x32_bf16 v[40:43], v[162:165], v[186:189], v[40:43]
	v_mfma_f32_16x16x32_bf16 v[24:27], v[162:165], v[202:205], v[24:27]
	v_mfma_f32_16x16x32_bf16 v[16:19], v[170:173], v[202:205], v[16:19]
	v_mfma_f32_16x16x32_bf16 v[0:3], v[170:173], v[210:213], v[0:3]
	v_mfma_f32_16x16x32_bf16 v[8:11], v[162:165], v[210:213], v[8:11]
	v_mfma_f32_16x16x32_bf16 v[56:59], v[166:169], v[182:185], v[56:59]
	v_mfma_f32_16x16x32_bf16 v[48:51], v[174:177], v[182:185], v[48:51]
	v_mfma_f32_16x16x32_bf16 v[32:35], v[174:177], v[190:193], v[32:35]
	v_mfma_f32_16x16x32_bf16 v[40:43], v[166:169], v[190:193], v[40:43]
	v_mfma_f32_16x16x32_bf16 v[24:27], v[166:169], v[206:209], v[24:27]
	v_mfma_f32_16x16x32_bf16 v[16:19], v[174:177], v[206:209], v[16:19]
	v_mfma_f32_16x16x32_bf16 v[0:3], v[174:177], v[214:217], v[0:3]
	v_mfma_f32_16x16x32_bf16 v[8:11], v[166:169], v[214:217], v[8:11]
	s_barrier
	s_setprio 0
	s_add_i32 s27, s27, 2
	s_add_u32 s28, s28, 0x100
	s_addc_u32 s29, s29, 0
	s_add_u32 s19, s19, 0x100
	s_addc_u32 s21, s21, 0
	s_cmp_gt_u32 s27, 13
	s_cbranch_scc0 .LBB0_1053
	s_and_b64 vcc, exec, s[16:17]
	s_cbranch_vccz .LBB0_1056
	s_barrier

; #define PG8_STAGE(bufoff, gbase, V0, V1) do { \
;         __builtin_amdgcn_global_load_lds((const unsigned*)((const char*)(gbase) + (V0)), (LAS unsigned*)(lds + (bufoff) + ldsw), 16, 0, 0); \
;         __builtin_amdgcn_global_load_lds((const unsigned*)((const char*)(gbase) + (V1)), (LAS unsigned*)(lds + (bufoff) + ldsw + 8192), 16, 0, 0); } while (0)
; #define PG8_LDA(dst, b, h) do { _Pragma("unroll") for (int m = 0; m < 4; ++m) _Pragma("unroll") for (int k = 0; k < 2; ++k) dst[m][k] = *(const LAS bf16x8*)(lds + PG8_SA(b, h) + aoff + m * 2048 + k * 1024); } while (0)
; #define PG8_WAIT_V(n) asm volatile("s_waitcnt vmcnt(" #n ")" ::: "memory")
; template <class Epi, class Sched>
; DI void gemm_phase(LAS unsigned char* lds, const int lda2, const int ldb2, const int nt, const Sched& S, const Epi& E) {
;     ...
;     for (;;) {
;         const bool has_next = S.next(ui + 1, nxt);
;         const char* nA = has_next ? nxt.A : cA; const char* nB = has_next ? nxt.B : cB;
;         for (int t = 0; t < nt; t += 2) {
;             const bool last = (t == nt - 2);
;             const char* a1 = cA + (size_t)(t + 1) * kstep;
;             const char* a2 = last ? nA : cA + (size_t)(t + 2) * kstep; const char* b2 = last ? nB : cB + (size_t)(t + 2) * kstep;
;             const char* a3 = a2 + kstep; const char* b3 = b2 + kstep;
;             PG8_LDB(B0, 0, 0); PG8_LDB(B1, 0, 1); PG8_SCHED; PG8_LDA(At, 0, 0); PG8_STAGE(PG8_SA(1, 1), a1 + hstepA, vA0, vA1);
;             PG8_WAIT_V(8); PG8_WAIT_L(0); PG8_BAR; PG8_MMA(0, 0, At, B0); PG8_MMA(0, 1, At, B1); PG8_BAR; PG8_SCHED;
;             PG8_LDA(At, 0, 1); PG8_STAGE(PG8_SB(0, 0), b2, vB0, vB1); PG8_STAGE(PG8_SB(0, 1), b2 + hstepB, vB0, vB1); PG8_STAGE(PG8_SA(0, 0), a2, vA0, vA1);
;             PG8_WAIT_V(8); PG8_WAIT_L(0); PG8_BAR; PG8_MMA(1, 0, At, B0); PG8_MMA(1, 1, At, B1); PG8_BAR; PG8_SCHED;
;             PG8_LDB(B0, 1, 0); PG8_LDB(B1, 1, 1); PG8_SCHED; PG8_LDA(At, 1, 0); PG8_STAGE(PG8_SA(0, 1), a2 + hstepA, vA0, vA1);
;             PG8_WAIT_V(8); PG8_WAIT_L(0); PG8_BAR; PG8_MMA(0, 0, At, B0); PG8_MMA(0, 1, At, B1); PG8_BAR; PG8_SCHED;
;             PG8_LDA(At, 1, 1); PG8_STAGE(PG8_SB(1, 0), b3, vB0, vB1); PG8_STAGE(PG8_SB(1, 1), b3 + hstepB, vB0, vB1); PG8_STAGE(PG8_SA(1, 0), a3, vA0, vA1);
;             PG8_WAIT_V(8); PG8_WAIT_L(0); PG8_BAR; PG8_MMA(1, 0, At, B0); PG8_MMA(1, 1, At, B1); PG8_BAR; PG8_SCHED;
.LBB0_1123:
	s_add_u32 s28, s28, 0xb0080
	s_addc_u32 s29, s29, 0
	s_add_u32 s1, s30, 0x100
	s_addc_u32 s10, s31, 0
	s_mov_b32 s57, -2
	s_waitcnt lgkmcnt(0)
	s_add_u32 s30, s28, 0xfff50080
	s_addc_u32 s31, s29, -1
	s_add_i32 vcc_lo, 0, 0x10000
	s_cmp_eq_u32 s57, 40
	s_cselect_b32 s53, s25, s31
	s_cselect_b32 s52, s24, s30
	v_add_u32_e32 v144, vcc_lo, v148
	s_cselect_b32 s31, s27, s10
	s_cselect_b32 s30, s26, s1
	s_add_i32 s58, 0, 0x14000
	ds_read_b128 v[140:143], v144
	ds_read_b128 v[150:153], v144 offset:1024
	ds_read_b128 v[154:157], v144 offset:2048
	ds_read_b128 v[158:161], v144 offset:3072
	v_add_u32_e32 v144, s58, v148
	ds_read_b128 v[162:165], v144
	ds_read_b128 v[166:169], v144 offset:1024
	ds_read_b128 v[170:173], v144 offset:2048
	ds_read_b128 v[174:177], v144 offset:3072
	v_lshl_add_u64 v[144:145], s[28:29], 0, v[136:137]
	s_add_i32 m0, s74, 0xc000
	ds_read_b128 v[178:181], v149
	ds_read_b128 v[182:185], v149 offset:1024
	ds_read_b128 v[186:189], v149 offset:2048
	ds_read_b128 v[190:193], v149 offset:3072
	ds_read_b128 v[202:205], v149 offset:4096
	ds_read_b128 v[206:209], v149 offset:5120
	ds_read_b128 v[210:213], v149 offset:6144
	ds_read_b128 v[214:217], v149 offset:7168
	global_load_lds_dwordx4 v[144:145], off
	v_lshl_add_u64 v[144:145], s[28:29], 0, v[138:139]
	s_add_i32 m0, s74, 0xe000
	s_nop 0
	global_load_lds_dwordx4 v[144:145], off
	s_waitcnt vmcnt(8)
	s_waitcnt lgkmcnt(0)
	s_setprio 1
	s_barrier
	s_waitcnt lgkmcnt(0)
	v_mfma_f32_16x16x32_bf16 v[126:129], v[140:143], v[178:181], 0
	v_mfma_f32_16x16x32_bf16 v[122:125], v[154:157], v[178:181], 0
	v_mfma_f32_16x16x32_bf16 v[106:109], v[154:157], v[186:189], 0
	v_mfma_f32_16x16x32_bf16 v[110:113], v[140:143], v[186:189], 0
	v_mfma_f32_16x16x32_bf16 v[92:95], v[140:143], v[202:205], 0
	v_mfma_f32_16x16x32_bf16 v[88:91], v[154:157], v[202:205], 0
	v_mfma_f32_16x16x32_bf16 v[72:75], v[154:157], v[210:213], 0
	v_mfma_f32_16x16x32_bf16 v[76:79], v[140:143], v[210:213], 0
	v_mfma_f32_16x16x32_bf16 v[126:129], v[150:153], v[182:185], v[126:129]
	v_mfma_f32_16x16x32_bf16 v[122:125], v[158:161], v[182:185], v[122:125]
	v_mfma_f32_16x16x32_bf16 v[106:109], v[158:161], v[190:193], v[106:109]
	v_mfma_f32_16x16x32_bf16 v[110:113], v[150:153], v[190:193], v[110:113]
	v_mfma_f32_16x16x32_bf16 v[92:95], v[150:153], v[206:209], v[92:95]
	v_mfma_f32_16x16x32_bf16 v[88:91], v[158:161], v[206:209], v[88:91]
	v_mfma_f32_16x16x32_bf16 v[72:75], v[158:161], v[214:217], v[72:75]
	v_mfma_f32_16x16x32_bf16 v[76:79], v[150:153], v[214:217], v[76:79]
	s_setprio 0
	s_setprio 1
	v_mfma_f32_16x16x32_bf16 v[118:121], v[162:165], v[178:181], 0
	v_mfma_f32_16x16x32_bf16 v[114:117], v[170:173], v[178:181], 0
	v_mfma_f32_16x16x32_bf16 v[98:101], v[170:173], v[186:189], 0
	v_mfma_f32_16x16x32_bf16 v[102:105], v[162:165], v[186:189], 0
	v_mfma_f32_16x16x32_bf16 v[84:87], v[162:165], v[202:205], 0
	v_mfma_f32_16x16x32_bf16 v[80:83], v[170:173], v[202:205], 0
	v_mfma_f32_16x16x32_bf16 v[64:67], v[170:173], v[210:213], 0
	v_mfma_f32_16x16x32_bf16 v[68:71], v[162:165], v[210:213], 0
	v_mfma_f32_16x16x32_bf16 v[118:121], v[166:169], v[182:185], v[118:121]
	v_mfma_f32_16x16x32_bf16 v[114:117], v[174:177], v[182:185], v[114:117]
	v_mfma_f32_16x16x32_bf16 v[98:101], v[174:177], v[190:193], v[98:101]
	v_mfma_f32_16x16x32_bf16 v[102:105], v[166:169], v[190:193], v[102:105]
	v_mfma_f32_16x16x32_bf16 v[84:87], v[166:169], v[206:209], v[84:87]
	v_mfma_f32_16x16x32_bf16 v[80:83], v[174:177], v[206:209], v[80:83]
	v_mfma_f32_16x16x32_bf16 v[64:67], v[174:177], v[214:217], v[64:67]
	v_mfma_f32_16x16x32_bf16 v[68:71], v[166:169], v[214:217], v[68:71]
	s_barrier
	s_setprio 0
	s_add_i32 s59, vcc_lo, s73
	v_lshl_add_u64 v[144:145], s[30:31], 0, v[96:97]
	s_mov_b32 m0, s59
	ds_read_b128 v[178:181], v149 offset:16384
	ds_read_b128 v[182:185], v149 offset:17408
	ds_read_b128 v[186:189], v149 offset:18432
	ds_read_b128 v[190:193], v149 offset:19456
	ds_read_b128 v[202:205], v149 offset:20480
	ds_read_b128 v[206:209], v149 offset:21504
	ds_read_b128 v[210:213], v149 offset:22528
	ds_read_b128 v[214:217], v149 offset:23552
	global_load_lds_dwordx4 v[144:145], off
	s_add_i32 m0, s59, 0x2000
	s_add_u32 vcc_lo, s30, 0xb0000
	v_lshl_add_u64 v[194:195], s[30:31], 0, v[130:131]
	s_addc_u32 vcc_hi, s31, 0
	s_add_i32 s58, s58, s73
	global_load_lds_dwordx4 v[194:195], off
	v_lshl_add_u64 v[218:219], vcc, 0, v[96:97]
	s_mov_b32 m0, s58
	v_lshl_add_u64 v[220:221], s[52:53], 0, v[134:135]
	global_load_lds_dwordx4 v[218:219], off
	v_lshl_add_u64 v[218:219], vcc, 0, v[130:131]
	s_add_i32 m0, s58, 0x2000
	s_nop 0
	global_load_lds_dwordx4 v[218:219], off
	v_lshl_add_u64 v[218:219], s[52:53], 0, v[132:133]
	s_mov_b32 m0, s74
	s_nop 0
	global_load_lds_dwordx4 v[218:219], off
	s_mov_b32 m0, s75
	s_nop 0
	global_load_lds_dwordx4 v[220:221], off
	s_waitcnt vmcnt(8)
	s_waitcnt lgkmcnt(0)
	s_setprio 1
	s_barrier
; #define PG8_STAGE(bufoff, gbase, V0, V1) do { \
;         __builtin_amdgcn_global_load_lds((const unsigned*)((const char*)(gbase) + (V0)), (LAS unsigned*)(lds + (bufoff) + ldsw), 16, 0, 0); \
;         __builtin_amdgcn_global_load_lds((const unsigned*)((const char*)(gbase) + (V1)), (LAS unsigned*)(lds + (bufoff) + ldsw + 8192), 16, 0, 0); } while (0)
; #define PG8_LDA(dst, b, h) do { _Pragma("unroll") for (int m = 0; m < 4; ++m) _Pragma("unroll") for (int k = 0; k < 2; ++k) dst[m][k] = *(const LAS bf16x8*)(lds + PG8_SA(b, h) + aoff + m * 2048 + k * 1024); } while (0)
; #define PG8_LDB(dst, b, h) do { _Pragma("unroll") for (int n = 0; n < 2; ++n) _Pragma("unroll") for (int k = 0; k < 2; ++k) dst[n][k] = *(const LAS bf16x8*)(lds + PG8_SB(b, h) + boff + n * 2048 + k * 1024); } while (0)
; #define PG8_MMA(ai, bj, At, Bt) do { __builtin_amdgcn_s_setprio(1); _Pragma("unroll") for (int m = 0; m < 4; ++m) _Pragma("unroll") for (int n = 0; n < 2; ++n) _Pragma("unroll") for (int k = 0; k < 2; ++k) \
;         acc[ai][bj][m][n] = __builtin_amdgcn_mfma_f32_16x16x32_bf16(Bt[n][k], At[m][k], acc[ai][bj][m][n], 0, 0, 0); __builtin_amdgcn_s_setprio(0); } while (0)
; template <class Epi, class Sched>
; DI void gemm_phase(LAS unsigned char* lds, const int lda2, const int ldb2, const int nt, const Sched& S, const Epi& E) {
;     ...
;             PG8_LDB(B0, 0, 0); PG8_LDB(B1, 0, 1); PG8_SCHED; PG8_LDA(At, 0, 0); PG8_STAGE(PG8_SA(1, 1), a1 + hstepA, vA0, vA1);
;             PG8_WAIT_V(8); PG8_WAIT_L(0); PG8_BAR; PG8_MMA(0, 0, At, B0); PG8_MMA(0, 1, At, B1); PG8_BAR; PG8_SCHED;
;             PG8_LDA(At, 0, 1); PG8_STAGE(PG8_SB(0, 0), b2, vB0, vB1); PG8_STAGE(PG8_SB(0, 1), b2 + hstepB, vB0, vB1); PG8_STAGE(PG8_SA(0, 0), a2, vA0, vA1);
;             PG8_WAIT_V(8); PG8_WAIT_L(0); PG8_BAR; PG8_MMA(1, 0, At, B0); PG8_MMA(1, 1, At, B1); PG8_BAR; PG8_SCHED;
;             PG8_LDB(B0, 1, 0); PG8_LDB(B1, 1, 1); PG8_SCHED; PG8_LDA(At, 1, 0); PG8_STAGE(PG8_SA(0, 1), a2 + hstepA, vA0, vA1);
;             PG8_WAIT_V(8); PG8_WAIT_L(0); PG8_BAR; PG8_MMA(0, 0, At, B0); PG8_MMA(0, 1, At, B1); PG8_BAR; PG8_SCHED;
;             PG8_LDA(At, 1, 1); PG8_STAGE(PG8_SB(1, 0), b3, vB0, vB1); PG8_STAGE(PG8_SB(1, 1), b3 + hstepB, vB0, vB1); PG8_STAGE(PG8_SA(1, 0), a3, vA0, vA1);
;             PG8_WAIT_V(8); PG8_WAIT_L(0); PG8_BAR; PG8_MMA(1, 0, At, B0); PG8_MMA(1, 1, At, B1); PG8_BAR; PG8_SCHED;
	s_waitcnt lgkmcnt(0)
	v_mfma_f32_16x16x32_bf16 v[60:63], v[140:143], v[178:181], 0
	v_mfma_f32_16x16x32_bf16 v[56:59], v[154:157], v[178:181], 0
	v_mfma_f32_16x16x32_bf16 v[40:43], v[154:157], v[186:189], 0
	v_mfma_f32_16x16x32_bf16 v[44:47], v[140:143], v[186:189], 0
	v_mfma_f32_16x16x32_bf16 v[28:31], v[140:143], v[202:205], 0
	v_mfma_f32_16x16x32_bf16 v[24:27], v[154:157], v[202:205], 0
	v_mfma_f32_16x16x32_bf16 v[8:11], v[154:157], v[210:213], 0
	v_mfma_f32_16x16x32_bf16 v[12:15], v[140:143], v[210:213], 0
	v_mfma_f32_16x16x32_bf16 v[60:63], v[150:153], v[182:185], v[60:63]
	v_mfma_f32_16x16x32_bf16 v[56:59], v[158:161], v[182:185], v[56:59]
	v_mfma_f32_16x16x32_bf16 v[40:43], v[158:161], v[190:193], v[40:43]
	v_mfma_f32_16x16x32_bf16 v[44:47], v[150:153], v[190:193], v[44:47]
	v_mfma_f32_16x16x32_bf16 v[28:31], v[150:153], v[206:209], v[28:31]
	v_mfma_f32_16x16x32_bf16 v[24:27], v[158:161], v[206:209], v[24:27]
	v_mfma_f32_16x16x32_bf16 v[8:11], v[158:161], v[214:217], v[8:11]
	v_mfma_f32_16x16x32_bf16 v[12:15], v[150:153], v[214:217], v[12:15]
	s_setprio 0
	s_setprio 1
	v_mfma_f32_16x16x32_bf16 v[52:55], v[162:165], v[178:181], 0
	v_mfma_f32_16x16x32_bf16 v[48:51], v[170:173], v[178:181], 0
	v_mfma_f32_16x16x32_bf16 v[32:35], v[170:173], v[186:189], 0
	v_mfma_f32_16x16x32_bf16 v[36:39], v[162:165], v[186:189], 0
	v_mfma_f32_16x16x32_bf16 v[20:23], v[162:165], v[202:205], 0
	v_mfma_f32_16x16x32_bf16 v[16:19], v[170:173], v[202:205], 0
	v_mfma_f32_16x16x32_bf16 v[0:3], v[170:173], v[210:213], 0
	v_mfma_f32_16x16x32_bf16 v[4:7], v[162:165], v[210:213], 0
	v_mfma_f32_16x16x32_bf16 v[52:55], v[166:169], v[182:185], v[52:55]
	v_mfma_f32_16x16x32_bf16 v[48:51], v[174:177], v[182:185], v[48:51]
	v_mfma_f32_16x16x32_bf16 v[32:35], v[174:177], v[190:193], v[32:35]
	v_mfma_f32_16x16x32_bf16 v[36:39], v[166:169], v[190:193], v[36:39]
	v_mfma_f32_16x16x32_bf16 v[20:23], v[166:169], v[206:209], v[20:23]
	v_mfma_f32_16x16x32_bf16 v[16:19], v[174:177], v[206:209], v[16:19]
	v_mfma_f32_16x16x32_bf16 v[0:3], v[174:177], v[214:217], v[0:3]
	v_mfma_f32_16x16x32_bf16 v[4:7], v[166:169], v[214:217], v[4:7]
	s_barrier
	s_setprio 0
	s_add_i32 s58, 0, 0x18000
	s_add_i32 s59, 0, 0x1c000
	v_add_u32_e32 v158, s58, v148
	v_add_u32_e32 v174, s59, v148
	ds_read_b128 v[140:143], v158
	ds_read_b128 v[150:153], v158 offset:1024
	ds_read_b128 v[154:157], v158 offset:2048
	ds_read_b128 v[158:161], v158 offset:3072
	ds_read_b128 v[162:165], v174
	ds_read_b128 v[166:169], v174 offset:1024
	ds_read_b128 v[170:173], v174 offset:2048
	ds_read_b128 v[174:177], v174 offset:3072
	s_add_u32 s52, s52, 0xb0000
	s_addc_u32 s53, s53, 0
	s_mov_b32 m0, s76
	v_lshl_add_u64 v[222:223], s[52:53], 0, v[132:133]
	ds_read_b128 v[178:181], v149 offset:32768
	ds_read_b128 v[182:185], v149 offset:33792
	ds_read_b128 v[186:189], v149 offset:34816
	ds_read_b128 v[190:193], v149 offset:35840
	ds_read_b128 v[202:205], v149 offset:36864
	ds_read_b128 v[206:209], v149 offset:37888
	ds_read_b128 v[210:213], v149 offset:38912
	ds_read_b128 v[214:217], v149 offset:39936
	global_load_lds_dwordx4 v[222:223], off
	v_lshl_add_u64 v[222:223], s[52:53], 0, v[134:135]
	s_mov_b32 m0, s77
	s_nop 0
	global_load_lds_dwordx4 v[222:223], off
	s_waitcnt vmcnt(8)
	s_waitcnt lgkmcnt(0)
	s_setprio 1
	s_barrier
	s_waitcnt lgkmcnt(0)
	v_mfma_f32_16x16x32_bf16 v[126:129], v[140:143], v[178:181], v[126:129]
	v_mfma_f32_16x16x32_bf16 v[122:125], v[154:157], v[178:181], v[122:125]
	v_mfma_f32_16x16x32_bf16 v[106:109], v[154:157], v[186:189], v[106:109]
	v_mfma_f32_16x16x32_bf16 v[110:113], v[140:143], v[186:189], v[110:113]
	v_mfma_f32_16x16x32_bf16 v[92:95], v[140:143], v[202:205], v[92:95]
	v_mfma_f32_16x16x32_bf16 v[88:91], v[154:157], v[202:205], v[88:91]
	v_mfma_f32_16x16x32_bf16 v[72:75], v[154:157], v[210:213], v[72:75]
	v_mfma_f32_16x16x32_bf16 v[76:79], v[140:143], v[210:213], v[76:79]
	v_mfma_f32_16x16x32_bf16 v[126:129], v[150:153], v[182:185], v[126:129]
	v_mfma_f32_16x16x32_bf16 v[122:125], v[158:161], v[182:185], v[122:125]
	v_mfma_f32_16x16x32_bf16 v[106:109], v[158:161], v[190:193], v[106:109]
	v_mfma_f32_16x16x32_bf16 v[110:113], v[150:153], v[190:193], v[110:113]
	v_mfma_f32_16x16x32_bf16 v[92:95], v[150:153], v[206:209], v[92:95]
	v_mfma_f32_16x16x32_bf16 v[88:91], v[158:161], v[206:209], v[88:91]
	v_mfma_f32_16x16x32_bf16 v[72:75], v[158:161], v[214:217], v[72:75]
	v_mfma_f32_16x16x32_bf16 v[76:79], v[150:153], v[214:217], v[76:79]
	s_setprio 0
	s_setprio 1
	v_mfma_f32_16x16x32_bf16 v[118:121], v[162:165], v[178:181], v[118:121]
	v_mfma_f32_16x16x32_bf16 v[114:117], v[170:173], v[178:181], v[114:117]
	v_mfma_f32_16x16x32_bf16 v[98:101], v[170:173], v[186:189], v[98:101]
	v_mfma_f32_16x16x32_bf16 v[102:105], v[162:165], v[186:189], v[102:105]
	v_mfma_f32_16x16x32_bf16 v[84:87], v[162:165], v[202:205], v[84:87]
	v_mfma_f32_16x16x32_bf16 v[80:83], v[170:173], v[202:205], v[80:83]
	v_mfma_f32_16x16x32_bf16 v[64:67], v[170:173], v[210:213], v[64:67]
	v_mfma_f32_16x16x32_bf16 v[68:71], v[162:165], v[210:213], v[68:71]
	v_mfma_f32_16x16x32_bf16 v[118:121], v[166:169], v[182:185], v[118:121]
	v_mfma_f32_16x16x32_bf16 v[114:117], v[174:177], v[182:185], v[114:117]
	v_mfma_f32_16x16x32_bf16 v[98:101], v[174:177], v[190:193], v[98:101]
	v_mfma_f32_16x16x32_bf16 v[102:105], v[166:169], v[190:193], v[102:105]
	v_mfma_f32_16x16x32_bf16 v[84:87], v[166:169], v[206:209], v[84:87]
	v_mfma_f32_16x16x32_bf16 v[80:83], v[174:177], v[206:209], v[80:83]
	v_mfma_f32_16x16x32_bf16 v[64:67], v[174:177], v[214:217], v[64:67]
	v_mfma_f32_16x16x32_bf16 v[68:71], v[166:169], v[214:217], v[68:71]
	s_barrier
; #define PG8_STAGE(bufoff, gbase, V0, V1) do { \
;         __builtin_amdgcn_global_load_lds((const unsigned*)((const char*)(gbase) + (V0)), (LAS unsigned*)(lds + (bufoff) + ldsw), 16, 0, 0); \
;         __builtin_amdgcn_global_load_lds((const unsigned*)((const char*)(gbase) + (V1)), (LAS unsigned*)(lds + (bufoff) + ldsw + 8192), 16, 0, 0); } while (0)
; #define PG8_LDA(dst, b, h) do { _Pragma("unroll") for (int m = 0; m < 4; ++m) _Pragma("unroll") for (int k = 0; k < 2; ++k) dst[m][k] = *(const LAS bf16x8*)(lds + PG8_SA(b, h) + aoff + m * 2048 + k * 1024); } while (0)
; #define PG8_LDB(dst, b, h) do { _Pragma("unroll") for (int n = 0; n < 2; ++n) _Pragma("unroll") for (int k = 0; k < 2; ++k) dst[n][k] = *(const LAS bf16x8*)(lds + PG8_SB(b, h) + boff + n * 2048 + k * 1024); } while (0)
; template <class Epi, class Sched>
; DI void gemm_phase(LAS unsigned char* lds, const int lda2, const int ldb2, const int nt, const Sched& S, const Epi& E) {
;     ...
;         for (int t = 0; t < nt; t += 2) {
;             const bool last = (t == nt - 2);
;             const char* a1 = cA + (size_t)(t + 1) * kstep;
;             const char* a2 = last ? nA : cA + (size_t)(t + 2) * kstep; const char* b2 = last ? nB : cB + (size_t)(t + 2) * kstep;
;             const char* a3 = a2 + kstep; const char* b3 = b2 + kstep;
;             PG8_LDB(B0, 0, 0); PG8_LDB(B1, 0, 1); PG8_SCHED; PG8_LDA(At, 0, 0); PG8_STAGE(PG8_SA(1, 1), a1 + hstepA, vA0, vA1);
;             PG8_WAIT_V(8); PG8_WAIT_L(0); PG8_BAR; PG8_MMA(0, 0, At, B0); PG8_MMA(0, 1, At, B1); PG8_BAR; PG8_SCHED;
;             PG8_LDA(At, 0, 1); PG8_STAGE(PG8_SB(0, 0), b2, vB0, vB1); PG8_STAGE(PG8_SB(0, 1), b2 + hstepB, vB0, vB1); PG8_STAGE(PG8_SA(0, 0), a2, vA0, vA1);
;             PG8_WAIT_V(8); PG8_WAIT_L(0); PG8_BAR; PG8_MMA(1, 0, At, B0); PG8_MMA(1, 1, At, B1); PG8_BAR; PG8_SCHED;
;             PG8_LDB(B0, 1, 0); PG8_LDB(B1, 1, 1); PG8_SCHED; PG8_LDA(At, 1, 0); PG8_STAGE(PG8_SA(0, 1), a2 + hstepA, vA0, vA1);
;             PG8_WAIT_V(8); PG8_WAIT_L(0); PG8_BAR; PG8_MMA(0, 0, At, B0); PG8_MMA(0, 1, At, B1); PG8_BAR; PG8_SCHED;
;             PG8_LDA(At, 1, 1); PG8_STAGE(PG8_SB(1, 0), b3, vB0, vB1); PG8_STAGE(PG8_SB(1, 1), b3 + hstepB, vB0, vB1); PG8_STAGE(PG8_SA(1, 0), a3, vA0, vA1);
;             PG8_WAIT_V(8); PG8_WAIT_L(0); PG8_BAR; PG8_MMA(1, 0, At, B0); PG8_MMA(1, 1, At, B1); PG8_BAR; PG8_SCHED;
	s_setprio 0
	s_add_i32 s52, s58, s73
	v_lshl_add_u64 v[144:145], v[144:145], 0, s[86:87]
	s_mov_b32 m0, s52
	ds_read_b128 v[178:181], v149 offset:49152
	ds_read_b128 v[182:185], v149 offset:50176
	ds_read_b128 v[186:189], v149 offset:51200
	ds_read_b128 v[190:193], v149 offset:52224
	ds_read_b128 v[202:205], v149 offset:53248
	ds_read_b128 v[206:209], v149 offset:54272
	ds_read_b128 v[210:213], v149 offset:55296
	ds_read_b128 v[214:217], v149 offset:56320
	global_load_lds_dwordx4 v[144:145], off
	s_add_i32 m0, s52, 0x2000
	s_add_u32 s30, s30, 0xb0080
	v_lshl_add_u64 v[144:145], v[194:195], 0, s[86:87]
	s_addc_u32 s31, s31, 0
	s_add_i32 s52, s59, s73
	global_load_lds_dwordx4 v[144:145], off
	v_lshl_add_u64 v[144:145], s[30:31], 0, v[96:97]
	s_mov_b32 m0, s52
	s_nop 0
	global_load_lds_dwordx4 v[144:145], off
	v_lshl_add_u64 v[144:145], s[30:31], 0, v[130:131]
	s_add_i32 m0, s52, 0x2000
	s_nop 0
	global_load_lds_dwordx4 v[144:145], off
	v_lshl_add_u64 v[144:145], v[218:219], 0, s[86:87]
	s_mov_b32 m0, s81
	s_nop 0
	global_load_lds_dwordx4 v[144:145], off
	v_lshl_add_u64 v[144:145], v[220:221], 0, s[86:87]
	s_mov_b32 m0, s82
	s_nop 0
	global_load_lds_dwordx4 v[144:145], off
	s_waitcnt vmcnt(8)
	s_waitcnt lgkmcnt(0)
	s_setprio 1
	s_barrier
	s_waitcnt lgkmcnt(0)
	v_mfma_f32_16x16x32_bf16 v[60:63], v[140:143], v[178:181], v[60:63]
	v_mfma_f32_16x16x32_bf16 v[56:59], v[154:157], v[178:181], v[56:59]
	v_mfma_f32_16x16x32_bf16 v[40:43], v[154:157], v[186:189], v[40:43]
	v_mfma_f32_16x16x32_bf16 v[44:47], v[140:143], v[186:189], v[44:47]
	v_mfma_f32_16x16x32_bf16 v[28:31], v[140:143], v[202:205], v[28:31]
	v_mfma_f32_16x16x32_bf16 v[24:27], v[154:157], v[202:205], v[24:27]
	v_mfma_f32_16x16x32_bf16 v[8:11], v[154:157], v[210:213], v[8:11]
	v_mfma_f32_16x16x32_bf16 v[12:15], v[140:143], v[210:213], v[12:15]
	v_mfma_f32_16x16x32_bf16 v[60:63], v[150:153], v[182:185], v[60:63]
	v_mfma_f32_16x16x32_bf16 v[56:59], v[158:161], v[182:185], v[56:59]
	v_mfma_f32_16x16x32_bf16 v[40:43], v[158:161], v[190:193], v[40:43]
	v_mfma_f32_16x16x32_bf16 v[44:47], v[150:153], v[190:193], v[44:47]
	v_mfma_f32_16x16x32_bf16 v[28:31], v[150:153], v[206:209], v[28:31]
	v_mfma_f32_16x16x32_bf16 v[24:27], v[158:161], v[206:209], v[24:27]
	v_mfma_f32_16x16x32_bf16 v[8:11], v[158:161], v[214:217], v[8:11]
	v_mfma_f32_16x16x32_bf16 v[12:15], v[150:153], v[214:217], v[12:15]
	s_setprio 0
	s_setprio 1
	v_mfma_f32_16x16x32_bf16 v[52:55], v[162:165], v[178:181], v[52:55]
	v_mfma_f32_16x16x32_bf16 v[48:51], v[170:173], v[178:181], v[48:51]
	v_mfma_f32_16x16x32_bf16 v[32:35], v[170:173], v[186:189], v[32:35]
	v_mfma_f32_16x16x32_bf16 v[36:39], v[162:165], v[186:189], v[36:39]
	v_mfma_f32_16x16x32_bf16 v[20:23], v[162:165], v[202:205], v[20:23]
	v_mfma_f32_16x16x32_bf16 v[16:19], v[170:173], v[202:205], v[16:19]
	v_mfma_f32_16x16x32_bf16 v[0:3], v[170:173], v[210:213], v[0:3]
	v_mfma_f32_16x16x32_bf16 v[4:7], v[162:165], v[210:213], v[4:7]
	v_mfma_f32_16x16x32_bf16 v[52:55], v[166:169], v[182:185], v[52:55]
	v_mfma_f32_16x16x32_bf16 v[48:51], v[174:177], v[182:185], v[48:51]
	v_mfma_f32_16x16x32_bf16 v[32:35], v[174:177], v[190:193], v[32:35]
	v_mfma_f32_16x16x32_bf16 v[36:39], v[166:169], v[190:193], v[36:39]
	v_mfma_f32_16x16x32_bf16 v[20:23], v[166:169], v[206:209], v[20:23]
	v_mfma_f32_16x16x32_bf16 v[16:19], v[174:177], v[206:209], v[16:19]
	v_mfma_f32_16x16x32_bf16 v[0:3], v[174:177], v[214:217], v[0:3]
	v_mfma_f32_16x16x32_bf16 v[4:7], v[166:169], v[214:217], v[4:7]
	s_barrier
	s_setprio 0
	s_add_i32 s57, s57, 2
	s_add_u32 s28, s28, 0x100
	s_addc_u32 s29, s29, 0
	s_add_u32 s1, s1, 0x100
	s_addc_u32 s10, s10, 0
.LBB0_1124:
	s_add_u32 s30, s28, 0xfff50080
	s_addc_u32 s31, s29, -1
	s_add_i32 vcc_lo, 0, 0x10000
	s_cmp_eq_u32 s57, 40
	s_cselect_b32 s53, s25, s31
	s_cselect_b32 s52, s24, s30
	v_add_u32_e32 v144, vcc_lo, v148
	s_cselect_b32 s31, s27, s10
	s_cselect_b32 s30, s26, s1
	s_add_i32 s58, 0, 0x14000
	ds_read_b128 v[140:143], v144
	ds_read_b128 v[150:153], v144 offset:1024
	ds_read_b128 v[154:157], v144 offset:2048
	ds_read_b128 v[158:161], v144 offset:3072
	v_add_u32_e32 v144, s58, v148
	ds_read_b128 v[162:165], v144
	ds_read_b128 v[166:169], v144 offset:1024
	ds_read_b128 v[170:173], v144 offset:2048
	ds_read_b128 v[174:177], v144 offset:3072
	v_lshl_add_u64 v[144:145], s[28:29], 0, v[136:137]
	s_add_i32 m0, s74, 0xc000
	ds_read_b128 v[178:181], v149
	ds_read_b128 v[182:185], v149 offset:1024
	ds_read_b128 v[186:189], v149 offset:2048
	ds_read_b128 v[190:193], v149 offset:3072
	ds_read_b128 v[202:205], v149 offset:4096
	ds_read_b128 v[206:209], v149 offset:5120
	ds_read_b128 v[210:213], v149 offset:6144
	ds_read_b128 v[214:217], v149 offset:7168
	global_load_lds_dwordx4 v[144:145], off
	v_lshl_add_u64 v[144:145], s[28:29], 0, v[138:139]
	s_add_i32 m0, s74, 0xe000
	s_nop 0
	global_load_lds_dwordx4 v[144:145], off
	s_waitcnt vmcnt(8)
	s_waitcnt lgkmcnt(0)
	s_setprio 1
	s_barrier
; #define PG8_STAGE(bufoff, gbase, V0, V1) do { \
;         __builtin_amdgcn_global_load_lds((const unsigned*)((const char*)(gbase) + (V0)), (LAS unsigned*)(lds + (bufoff) + ldsw), 16, 0, 0); \
;         __builtin_amdgcn_global_load_lds((const unsigned*)((const char*)(gbase) + (V1)), (LAS unsigned*)(lds + (bufoff) + ldsw + 8192), 16, 0, 0); } while (0)
; #define PG8_LDA(dst, b, h) do { _Pragma("unroll") for (int m = 0; m < 4; ++m) _Pragma("unroll") for (int k = 0; k < 2; ++k) dst[m][k] = *(const LAS bf16x8*)(lds + PG8_SA(b, h) + aoff + m * 2048 + k * 1024); } while (0)
; #define PG8_LDB(dst, b, h) do { _Pragma("unroll") for (int n = 0; n < 2; ++n) _Pragma("unroll") for (int k = 0; k < 2; ++k) dst[n][k] = *(const LAS bf16x8*)(lds + PG8_SB(b, h) + boff + n * 2048 + k * 1024); } while (0)
; #define PG8_MMA(ai, bj, At, Bt) do { __builtin_amdgcn_s_setprio(1); _Pragma("unroll") for (int m = 0; m < 4; ++m) _Pragma("unroll") for (int n = 0; n < 2; ++n) _Pragma("unroll") for (int k = 0; k < 2; ++k) \
;         acc[ai][bj][m][n] = __builtin_amdgcn_mfma_f32_16x16x32_bf16(Bt[n][k], At[m][k], acc[ai][bj][m][n], 0, 0, 0); __builtin_amdgcn_s_setprio(0); } while (0)
; template <class Epi, class Sched>
; DI void gemm_phase(LAS unsigned char* lds, const int lda2, const int ldb2, const int nt, const Sched& S, const Epi& E) {
;     ...
;             PG8_LDB(B0, 0, 0); PG8_LDB(B1, 0, 1); PG8_SCHED; PG8_LDA(At, 0, 0); PG8_STAGE(PG8_SA(1, 1), a1 + hstepA, vA0, vA1);
;             PG8_WAIT_V(8); PG8_WAIT_L(0); PG8_BAR; PG8_MMA(0, 0, At, B0); PG8_MMA(0, 1, At, B1); PG8_BAR; PG8_SCHED;
;             PG8_LDA(At, 0, 1); PG8_STAGE(PG8_SB(0, 0), b2, vB0, vB1); PG8_STAGE(PG8_SB(0, 1), b2 + hstepB, vB0, vB1); PG8_STAGE(PG8_SA(0, 0), a2, vA0, vA1);
;             PG8_WAIT_V(8); PG8_WAIT_L(0); PG8_BAR; PG8_MMA(1, 0, At, B0); PG8_MMA(1, 1, At, B1); PG8_BAR; PG8_SCHED;
;             PG8_LDB(B0, 1, 0); PG8_LDB(B1, 1, 1); PG8_SCHED; PG8_LDA(At, 1, 0); PG8_STAGE(PG8_SA(0, 1), a2 + hstepA, vA0, vA1);
;             PG8_WAIT_V(8); PG8_WAIT_L(0); PG8_BAR; PG8_MMA(0, 0, At, B0); PG8_MMA(0, 1, At, B1); PG8_BAR; PG8_SCHED;
;             PG8_LDA(At, 1, 1); PG8_STAGE(PG8_SB(1, 0), b3, vB0, vB1); PG8_STAGE(PG8_SB(1, 1), b3 + hstepB, vB0, vB1); PG8_STAGE(PG8_SA(1, 0), a3, vA0, vA1);
;             PG8_WAIT_V(8); PG8_WAIT_L(0); PG8_BAR; PG8_MMA(1, 0, At, B0); PG8_MMA(1, 1, At, B1); PG8_BAR; PG8_SCHED;
	s_waitcnt lgkmcnt(0)
	v_mfma_f32_16x16x32_bf16 v[126:129], v[140:143], v[178:181], v[126:129]
	v_mfma_f32_16x16x32_bf16 v[122:125], v[154:157], v[178:181], v[122:125]
	v_mfma_f32_16x16x32_bf16 v[106:109], v[154:157], v[186:189], v[106:109]
	v_mfma_f32_16x16x32_bf16 v[110:113], v[140:143], v[186:189], v[110:113]
	v_mfma_f32_16x16x32_bf16 v[92:95], v[140:143], v[202:205], v[92:95]
	v_mfma_f32_16x16x32_bf16 v[88:91], v[154:157], v[202:205], v[88:91]
	v_mfma_f32_16x16x32_bf16 v[72:75], v[154:157], v[210:213], v[72:75]
	v_mfma_f32_16x16x32_bf16 v[76:79], v[140:143], v[210:213], v[76:79]
	v_mfma_f32_16x16x32_bf16 v[126:129], v[150:153], v[182:185], v[126:129]
	v_mfma_f32_16x16x32_bf16 v[122:125], v[158:161], v[182:185], v[122:125]
	v_mfma_f32_16x16x32_bf16 v[106:109], v[158:161], v[190:193], v[106:109]
	v_mfma_f32_16x16x32_bf16 v[110:113], v[150:153], v[190:193], v[110:113]
	v_mfma_f32_16x16x32_bf16 v[92:95], v[150:153], v[206:209], v[92:95]
	v_mfma_f32_16x16x32_bf16 v[88:91], v[158:161], v[206:209], v[88:91]
	v_mfma_f32_16x16x32_bf16 v[72:75], v[158:161], v[214:217], v[72:75]
	v_mfma_f32_16x16x32_bf16 v[76:79], v[150:153], v[214:217], v[76:79]
	s_setprio 0
	s_setprio 1
	v_mfma_f32_16x16x32_bf16 v[118:121], v[162:165], v[178:181], v[118:121]
	v_mfma_f32_16x16x32_bf16 v[114:117], v[170:173], v[178:181], v[114:117]
	v_mfma_f32_16x16x32_bf16 v[98:101], v[170:173], v[186:189], v[98:101]
	v_mfma_f32_16x16x32_bf16 v[102:105], v[162:165], v[186:189], v[102:105]
	v_mfma_f32_16x16x32_bf16 v[84:87], v[162:165], v[202:205], v[84:87]
	v_mfma_f32_16x16x32_bf16 v[80:83], v[170:173], v[202:205], v[80:83]
	v_mfma_f32_16x16x32_bf16 v[64:67], v[170:173], v[210:213], v[64:67]
	v_mfma_f32_16x16x32_bf16 v[68:71], v[162:165], v[210:213], v[68:71]
	v_mfma_f32_16x16x32_bf16 v[118:121], v[166:169], v[182:185], v[118:121]
	v_mfma_f32_16x16x32_bf16 v[114:117], v[174:177], v[182:185], v[114:117]
	v_mfma_f32_16x16x32_bf16 v[98:101], v[174:177], v[190:193], v[98:101]
	v_mfma_f32_16x16x32_bf16 v[102:105], v[166:169], v[190:193], v[102:105]
	v_mfma_f32_16x16x32_bf16 v[84:87], v[166:169], v[206:209], v[84:87]
	v_mfma_f32_16x16x32_bf16 v[80:83], v[174:177], v[206:209], v[80:83]
	v_mfma_f32_16x16x32_bf16 v[64:67], v[174:177], v[214:217], v[64:67]
	v_mfma_f32_16x16x32_bf16 v[68:71], v[166:169], v[214:217], v[68:71]
	s_barrier
	s_setprio 0
	s_add_i32 s59, vcc_lo, s73
	v_lshl_add_u64 v[144:145], s[30:31], 0, v[96:97]
	s_mov_b32 m0, s59
	ds_read_b128 v[178:181], v149 offset:16384
	ds_read_b128 v[182:185], v149 offset:17408
	ds_read_b128 v[186:189], v149 offset:18432
	ds_read_b128 v[190:193], v149 offset:19456
	ds_read_b128 v[202:205], v149 offset:20480
	ds_read_b128 v[206:209], v149 offset:21504
	ds_read_b128 v[210:213], v149 offset:22528
	ds_read_b128 v[214:217], v149 offset:23552
	global_load_lds_dwordx4 v[144:145], off
	s_add_i32 m0, s59, 0x2000
	s_add_u32 vcc_lo, s30, 0xb0000
	v_lshl_add_u64 v[194:195], s[30:31], 0, v[130:131]
	s_addc_u32 vcc_hi, s31, 0
	s_add_i32 s58, s58, s73
	global_load_lds_dwordx4 v[194:195], off
	v_lshl_add_u64 v[218:219], vcc, 0, v[96:97]
	s_mov_b32 m0, s58
	v_lshl_add_u64 v[220:221], s[52:53], 0, v[134:135]
	global_load_lds_dwordx4 v[218:219], off
	v_lshl_add_u64 v[218:219], vcc, 0, v[130:131]
	s_add_i32 m0, s58, 0x2000
	s_nop 0
	global_load_lds_dwordx4 v[218:219], off
	v_lshl_add_u64 v[218:219], s[52:53], 0, v[132:133]
	s_mov_b32 m0, s74
	s_nop 0
	global_load_lds_dwordx4 v[218:219], off
	s_mov_b32 m0, s75
	s_nop 0
	global_load_lds_dwordx4 v[220:221], off
	s_waitcnt vmcnt(8)
	s_waitcnt lgkmcnt(0)
	s_setprio 1
	s_barrier
	s_waitcnt lgkmcnt(0)
	v_mfma_f32_16x16x32_bf16 v[60:63], v[140:143], v[178:181], v[60:63]
	v_mfma_f32_16x16x32_bf16 v[56:59], v[154:157], v[178:181], v[56:59]
	v_mfma_f32_16x16x32_bf16 v[40:43], v[154:157], v[186:189], v[40:43]
	v_mfma_f32_16x16x32_bf16 v[44:47], v[140:143], v[186:189], v[44:47]
	v_mfma_f32_16x16x32_bf16 v[28:31], v[140:143], v[202:205], v[28:31]
	v_mfma_f32_16x16x32_bf16 v[24:27], v[154:157], v[202:205], v[24:27]
	v_mfma_f32_16x16x32_bf16 v[8:11], v[154:157], v[210:213], v[8:11]
	v_mfma_f32_16x16x32_bf16 v[12:15], v[140:143], v[210:213], v[12:15]
	v_mfma_f32_16x16x32_bf16 v[60:63], v[150:153], v[182:185], v[60:63]
	v_mfma_f32_16x16x32_bf16 v[56:59], v[158:161], v[182:185], v[56:59]
	v_mfma_f32_16x16x32_bf16 v[40:43], v[158:161], v[190:193], v[40:43]
	v_mfma_f32_16x16x32_bf16 v[44:47], v[150:153], v[190:193], v[44:47]
	v_mfma_f32_16x16x32_bf16 v[28:31], v[150:153], v[206:209], v[28:31]
	v_mfma_f32_16x16x32_bf16 v[24:27], v[158:161], v[206:209], v[24:27]
	v_mfma_f32_16x16x32_bf16 v[8:11], v[158:161], v[214:217], v[8:11]
	v_mfma_f32_16x16x32_bf16 v[12:15], v[150:153], v[214:217], v[12:15]
	s_setprio 0
	s_setprio 1
	v_mfma_f32_16x16x32_bf16 v[52:55], v[162:165], v[178:181], v[52:55]
	v_mfma_f32_16x16x32_bf16 v[48:51], v[170:173], v[178:181], v[48:51]
	v_mfma_f32_16x16x32_bf16 v[32:35], v[170:173], v[186:189], v[32:35]
	v_mfma_f32_16x16x32_bf16 v[36:39], v[162:165], v[186:189], v[36:39]
	v_mfma_f32_16x16x32_bf16 v[20:23], v[162:165], v[202:205], v[20:23]
	v_mfma_f32_16x16x32_bf16 v[16:19], v[170:173], v[202:205], v[16:19]
	v_mfma_f32_16x16x32_bf16 v[0:3], v[170:173], v[210:213], v[0:3]
	v_mfma_f32_16x16x32_bf16 v[4:7], v[162:165], v[210:213], v[4:7]
	v_mfma_f32_16x16x32_bf16 v[52:55], v[166:169], v[182:185], v[52:55]
	v_mfma_f32_16x16x32_bf16 v[48:51], v[174:177], v[182:185], v[48:51]
	v_mfma_f32_16x16x32_bf16 v[32:35], v[174:177], v[190:193], v[32:35]
	v_mfma_f32_16x16x32_bf16 v[36:39], v[166:169], v[190:193], v[36:39]
	v_mfma_f32_16x16x32_bf16 v[20:23], v[166:169], v[206:209], v[20:23]
	v_mfma_f32_16x16x32_bf16 v[16:19], v[174:177], v[206:209], v[16:19]
	v_mfma_f32_16x16x32_bf16 v[0:3], v[174:177], v[214:217], v[0:3]
	v_mfma_f32_16x16x32_bf16 v[4:7], v[166:169], v[214:217], v[4:7]
	s_barrier
; #define PG8_STAGE(bufoff, gbase, V0, V1) do { \
;         __builtin_amdgcn_global_load_lds((const unsigned*)((const char*)(gbase) + (V0)), (LAS unsigned*)(lds + (bufoff) + ldsw), 16, 0, 0); \
;         __builtin_amdgcn_global_load_lds((const unsigned*)((const char*)(gbase) + (V1)), (LAS unsigned*)(lds + (bufoff) + ldsw + 8192), 16, 0, 0); } while (0)
; #define PG8_LDA(dst, b, h) do { _Pragma("unroll") for (int m = 0; m < 4; ++m) _Pragma("unroll") for (int k = 0; k < 2; ++k) dst[m][k] = *(const LAS bf16x8*)(lds + PG8_SA(b, h) + aoff + m * 2048 + k * 1024); } while (0)
; #define PG8_MMA(ai, bj, At, Bt) do { __builtin_amdgcn_s_setprio(1); _Pragma("unroll") for (int m = 0; m < 4; ++m) _Pragma("unroll") for (int n = 0; n < 2; ++n) _Pragma("unroll") for (int k = 0; k < 2; ++k) \
;         acc[ai][bj][m][n] = __builtin_amdgcn_mfma_f32_16x16x32_bf16(Bt[n][k], At[m][k], acc[ai][bj][m][n], 0, 0, 0); __builtin_amdgcn_s_setprio(0); } while (0)
; #define PG8_WAIT_V(n) asm volatile("s_waitcnt vmcnt(" #n ")" ::: "memory")
; #define PG8_WAIT_L(n) asm volatile("s_waitcnt lgkmcnt(" #n ")" ::: "memory")
; #define PG8_BAR __builtin_amdgcn_s_barrier()
; #define PG8_SCHED __builtin_amdgcn_sched_barrier(0)
; template <class Epi, class Sched>
; DI void gemm_phase(LAS unsigned char* lds, const int lda2, const int ldb2, const int nt, const Sched& S, const Epi& E) {
;     ...
;             PG8_LDA(At, 1, 1); PG8_STAGE(PG8_SB(1, 0), b3, vB0, vB1); PG8_STAGE(PG8_SB(1, 1), b3 + hstepB, vB0, vB1); PG8_STAGE(PG8_SA(1, 0), a3, vA0, vA1);
;             PG8_WAIT_V(8); PG8_WAIT_L(0); PG8_BAR; PG8_MMA(1, 0, At, B0); PG8_MMA(1, 1, At, B1); PG8_BAR; PG8_SCHED;
	s_setprio 0
	s_add_i32 s58, 0, 0x18000
	s_add_i32 s59, 0, 0x1c000
	v_add_u32_e32 v158, s58, v148
	v_add_u32_e32 v174, s59, v148
	ds_read_b128 v[140:143], v158
	ds_read_b128 v[150:153], v158 offset:1024
	ds_read_b128 v[154:157], v158 offset:2048
	ds_read_b128 v[158:161], v158 offset:3072
	ds_read_b128 v[162:165], v174
	ds_read_b128 v[166:169], v174 offset:1024
	ds_read_b128 v[170:173], v174 offset:2048
	ds_read_b128 v[174:177], v174 offset:3072
	s_add_u32 s52, s52, 0xb0000
	s_addc_u32 s53, s53, 0
	s_mov_b32 m0, s76
	v_lshl_add_u64 v[222:223], s[52:53], 0, v[132:133]
	ds_read_b128 v[178:181], v149 offset:32768
	ds_read_b128 v[182:185], v149 offset:33792
	ds_read_b128 v[186:189], v149 offset:34816
	ds_read_b128 v[190:193], v149 offset:35840
	ds_read_b128 v[202:205], v149 offset:36864
	ds_read_b128 v[206:209], v149 offset:37888
	ds_read_b128 v[210:213], v149 offset:38912
	ds_read_b128 v[214:217], v149 offset:39936
	global_load_lds_dwordx4 v[222:223], off
	v_lshl_add_u64 v[222:223], s[52:53], 0, v[134:135]
	s_mov_b32 m0, s77
	s_nop 0
	global_load_lds_dwordx4 v[222:223], off
	s_waitcnt vmcnt(8)
	s_waitcnt lgkmcnt(0)
	s_setprio 1
	s_barrier
	s_waitcnt lgkmcnt(0)
	v_mfma_f32_16x16x32_bf16 v[126:129], v[140:143], v[178:181], v[126:129]
	v_mfma_f32_16x16x32_bf16 v[122:125], v[154:157], v[178:181], v[122:125]
	v_mfma_f32_16x16x32_bf16 v[106:109], v[154:157], v[186:189], v[106:109]
	v_mfma_f32_16x16x32_bf16 v[110:113], v[140:143], v[186:189], v[110:113]
	v_mfma_f32_16x16x32_bf16 v[92:95], v[140:143], v[202:205], v[92:95]
	v_mfma_f32_16x16x32_bf16 v[88:91], v[154:157], v[202:205], v[88:91]
	v_mfma_f32_16x16x32_bf16 v[72:75], v[154:157], v[210:213], v[72:75]
	v_mfma_f32_16x16x32_bf16 v[76:79], v[140:143], v[210:213], v[76:79]
	v_mfma_f32_16x16x32_bf16 v[126:129], v[150:153], v[182:185], v[126:129]
	v_mfma_f32_16x16x32_bf16 v[122:125], v[158:161], v[182:185], v[122:125]
	v_mfma_f32_16x16x32_bf16 v[106:109], v[158:161], v[190:193], v[106:109]
	v_mfma_f32_16x16x32_bf16 v[110:113], v[150:153], v[190:193], v[110:113]
	v_mfma_f32_16x16x32_bf16 v[92:95], v[150:153], v[206:209], v[92:95]
	v_mfma_f32_16x16x32_bf16 v[88:91], v[158:161], v[206:209], v[88:91]
	v_mfma_f32_16x16x32_bf16 v[72:75], v[158:161], v[214:217], v[72:75]
	v_mfma_f32_16x16x32_bf16 v[76:79], v[150:153], v[214:217], v[76:79]
	s_setprio 0
	s_setprio 1
	v_mfma_f32_16x16x32_bf16 v[118:121], v[162:165], v[178:181], v[118:121]
	v_mfma_f32_16x16x32_bf16 v[114:117], v[170:173], v[178:181], v[114:117]
	v_mfma_f32_16x16x32_bf16 v[98:101], v[170:173], v[186:189], v[98:101]
	v_mfma_f32_16x16x32_bf16 v[102:105], v[162:165], v[186:189], v[102:105]
	v_mfma_f32_16x16x32_bf16 v[84:87], v[162:165], v[202:205], v[84:87]
	v_mfma_f32_16x16x32_bf16 v[80:83], v[170:173], v[202:205], v[80:83]
	v_mfma_f32_16x16x32_bf16 v[64:67], v[170:173], v[210:213], v[64:67]
	v_mfma_f32_16x16x32_bf16 v[68:71], v[162:165], v[210:213], v[68:71]
	v_mfma_f32_16x16x32_bf16 v[118:121], v[166:169], v[182:185], v[118:121]
	v_mfma_f32_16x16x32_bf16 v[114:117], v[174:177], v[182:185], v[114:117]
	v_mfma_f32_16x16x32_bf16 v[98:101], v[174:177], v[190:193], v[98:101]
	v_mfma_f32_16x16x32_bf16 v[102:105], v[166:169], v[190:193], v[102:105]
	v_mfma_f32_16x16x32_bf16 v[84:87], v[166:169], v[206:209], v[84:87]
	v_mfma_f32_16x16x32_bf16 v[80:83], v[174:177], v[206:209], v[80:83]
	v_mfma_f32_16x16x32_bf16 v[64:67], v[174:177], v[214:217], v[64:67]
	v_mfma_f32_16x16x32_bf16 v[68:71], v[166:169], v[214:217], v[68:71]
	s_barrier
; #define PG8_STAGE(bufoff, gbase, V0, V1) do { \
;         __builtin_amdgcn_global_load_lds((const unsigned*)((const char*)(gbase) + (V0)), (LAS unsigned*)(lds + (bufoff) + ldsw), 16, 0, 0); \
;         __builtin_amdgcn_global_load_lds((const unsigned*)((const char*)(gbase) + (V1)), (LAS unsigned*)(lds + (bufoff) + ldsw + 8192), 16, 0, 0); } while (0)
; #define PG8_LDA(dst, b, h) do { _Pragma("unroll") for (int m = 0; m < 4; ++m) _Pragma("unroll") for (int k = 0; k < 2; ++k) dst[m][k] = *(const LAS bf16x8*)(lds + PG8_SA(b, h) + aoff + m * 2048 + k * 1024); } while (0)
; #define PG8_MMA(ai, bj, At, Bt) do { __builtin_amdgcn_s_setprio(1); _Pragma("unroll") for (int m = 0; m < 4; ++m) _Pragma("unroll") for (int n = 0; n < 2; ++n) _Pragma("unroll") for (int k = 0; k < 2; ++k) \
;         acc[ai][bj][m][n] = __builtin_amdgcn_mfma_f32_16x16x32_bf16(Bt[n][k], At[m][k], acc[ai][bj][m][n], 0, 0, 0); __builtin_amdgcn_s_setprio(0); } while (0)
; #define PG8_WAIT_V(n) asm volatile("s_waitcnt vmcnt(" #n ")" ::: "memory")
; #define PG8_WAIT_L(n) asm volatile("s_waitcnt lgkmcnt(" #n ")" ::: "memory")
; #define PG8_BAR __builtin_amdgcn_s_barrier()
; #define PG8_SCHED __builtin_amdgcn_sched_barrier(0)
; template <class Epi, class Sched>
; DI void gemm_phase(LAS unsigned char* lds, const int lda2, const int ldb2, const int nt, const Sched& S, const Epi& E) {
;     ...
;             PG8_LDA(At, 1, 1); PG8_STAGE(PG8_SB(1, 0), b3, vB0, vB1); PG8_STAGE(PG8_SB(1, 1), b3 + hstepB, vB0, vB1); PG8_STAGE(PG8_SA(1, 0), a3, vA0, vA1);
;             PG8_WAIT_V(8); PG8_WAIT_L(0); PG8_BAR; PG8_MMA(1, 0, At, B0); PG8_MMA(1, 1, At, B1); PG8_BAR; PG8_SCHED;
;         }
;         if (wr == 0) PG8_BAR;
	s_setprio 0
	s_add_i32 s52, s58, s73
	v_lshl_add_u64 v[144:145], v[144:145], 0, s[86:87]
	s_mov_b32 m0, s52
	ds_read_b128 v[178:181], v149 offset:49152
	ds_read_b128 v[182:185], v149 offset:50176
	ds_read_b128 v[186:189], v149 offset:51200
	ds_read_b128 v[190:193], v149 offset:52224
	ds_read_b128 v[202:205], v149 offset:53248
	ds_read_b128 v[206:209], v149 offset:54272
	ds_read_b128 v[210:213], v149 offset:55296
	ds_read_b128 v[214:217], v149 offset:56320
	global_load_lds_dwordx4 v[144:145], off
	s_add_i32 m0, s52, 0x2000
	s_add_u32 s30, s30, 0xb0080
	v_lshl_add_u64 v[144:145], v[194:195], 0, s[86:87]
	s_addc_u32 s31, s31, 0
	s_add_i32 s52, s59, s73
	global_load_lds_dwordx4 v[144:145], off
	v_lshl_add_u64 v[144:145], s[30:31], 0, v[96:97]
	s_mov_b32 m0, s52
	s_nop 0
	global_load_lds_dwordx4 v[144:145], off
	v_lshl_add_u64 v[144:145], s[30:31], 0, v[130:131]
	s_add_i32 m0, s52, 0x2000
	s_nop 0
	global_load_lds_dwordx4 v[144:145], off
	v_lshl_add_u64 v[144:145], v[218:219], 0, s[86:87]
	s_mov_b32 m0, s81
	s_nop 0
	global_load_lds_dwordx4 v[144:145], off
	v_lshl_add_u64 v[144:145], v[220:221], 0, s[86:87]
	s_mov_b32 m0, s82
	s_nop 0
	global_load_lds_dwordx4 v[144:145], off
	s_waitcnt vmcnt(8)
	s_waitcnt lgkmcnt(0)
	s_setprio 1
	s_barrier
	s_waitcnt lgkmcnt(0)
	v_mfma_f32_16x16x32_bf16 v[60:63], v[140:143], v[178:181], v[60:63]
	v_mfma_f32_16x16x32_bf16 v[56:59], v[154:157], v[178:181], v[56:59]
	v_mfma_f32_16x16x32_bf16 v[40:43], v[154:157], v[186:189], v[40:43]
	v_mfma_f32_16x16x32_bf16 v[44:47], v[140:143], v[186:189], v[44:47]
	v_mfma_f32_16x16x32_bf16 v[28:31], v[140:143], v[202:205], v[28:31]
	v_mfma_f32_16x16x32_bf16 v[24:27], v[154:157], v[202:205], v[24:27]
	v_mfma_f32_16x16x32_bf16 v[8:11], v[154:157], v[210:213], v[8:11]
	v_mfma_f32_16x16x32_bf16 v[12:15], v[140:143], v[210:213], v[12:15]
	v_mfma_f32_16x16x32_bf16 v[60:63], v[150:153], v[182:185], v[60:63]
	v_mfma_f32_16x16x32_bf16 v[56:59], v[158:161], v[182:185], v[56:59]
	v_mfma_f32_16x16x32_bf16 v[40:43], v[158:161], v[190:193], v[40:43]
	v_mfma_f32_16x16x32_bf16 v[44:47], v[150:153], v[190:193], v[44:47]
	v_mfma_f32_16x16x32_bf16 v[28:31], v[150:153], v[206:209], v[28:31]
	v_mfma_f32_16x16x32_bf16 v[24:27], v[158:161], v[206:209], v[24:27]
	v_mfma_f32_16x16x32_bf16 v[8:11], v[158:161], v[214:217], v[8:11]
	v_mfma_f32_16x16x32_bf16 v[12:15], v[150:153], v[214:217], v[12:15]
	s_setprio 0
	s_setprio 1
	v_mfma_f32_16x16x32_bf16 v[52:55], v[162:165], v[178:181], v[52:55]
	v_mfma_f32_16x16x32_bf16 v[48:51], v[170:173], v[178:181], v[48:51]
	v_mfma_f32_16x16x32_bf16 v[32:35], v[170:173], v[186:189], v[32:35]
	v_mfma_f32_16x16x32_bf16 v[36:39], v[162:165], v[186:189], v[36:39]
	v_mfma_f32_16x16x32_bf16 v[20:23], v[162:165], v[202:205], v[20:23]
	v_mfma_f32_16x16x32_bf16 v[16:19], v[170:173], v[202:205], v[16:19]
	v_mfma_f32_16x16x32_bf16 v[0:3], v[170:173], v[210:213], v[0:3]
	v_mfma_f32_16x16x32_bf16 v[4:7], v[162:165], v[210:213], v[4:7]
	v_mfma_f32_16x16x32_bf16 v[52:55], v[166:169], v[182:185], v[52:55]
	v_mfma_f32_16x16x32_bf16 v[48:51], v[174:177], v[182:185], v[48:51]
	v_mfma_f32_16x16x32_bf16 v[32:35], v[174:177], v[190:193], v[32:35]
	v_mfma_f32_16x16x32_bf16 v[36:39], v[166:169], v[190:193], v[36:39]
	v_mfma_f32_16x16x32_bf16 v[20:23], v[166:169], v[206:209], v[20:23]
	v_mfma_f32_16x16x32_bf16 v[16:19], v[174:177], v[206:209], v[16:19]
	v_mfma_f32_16x16x32_bf16 v[0:3], v[174:177], v[214:217], v[0:3]
	v_mfma_f32_16x16x32_bf16 v[4:7], v[166:169], v[214:217], v[4:7]
	s_barrier
	s_setprio 0
	s_add_i32 s57, s57, 2
	s_add_u32 s28, s28, 0x100
	s_addc_u32 s29, s29, 0
	s_add_u32 s1, s1, 0x100
	s_addc_u32 s10, s10, 0
	s_cmp_gt_u32 s57, 41
	s_cbranch_scc0 .LBB0_1124
	s_and_b64 vcc, exec, s[22:23]
	s_cbranch_vccz .LBB0_1127
	s_barrier
